# phase A part 1 hand-written (256x128 LDS-DMA ring core, silu/f32 epilogues, 2 tiles per block); B0 LoRA weight fragments loaded in two round trips instead of ten
# baseline (speedup 1.0000x reference)
.LBB0_149:
	s_and_b64 s[0:1], s[24:25], exec
	v_readlane_b32 s0, v253, 41
	s_mov_b32 s67, s72
	s_cselect_b32 s72, s65, s0
	s_cmp_ge_i32 s2, s72
	s_cbranch_scc1 .LBB0_420
	s_cmp_eq_u64 s[24:25], 0
	s_cbranch_scc1 .La1_mine
	s_and_b64 s[0:1], s[24:25], exec
	s_cselect_b32 s10, 8, 5
	s_lshl_b32 s96, s10, 5
	v_mov_b32_e32 v14, v0
	s_cmp_lt_i32 s2, s96
	s_cselect_b64 s[6:7], -1, 0
	s_cmp_ge_i32 s2, s96
	v_readfirstlane_b32 s73, v14
	s_cbranch_scc1 .LBB0_152
	s_lshl_b32 s0, s10, 3
	v_cvt_f32_u32_e32 v1, s0
	s_lshl_b32 s1, s10, 2
	v_readlane_b32 s4, v253, 7
	s_or_b32 s1, s1, s4
	v_rcp_iflag_f32_e32 v1, v1
	s_sub_i32 s4, 0, s0
	v_readlane_b32 s5, v254, 12
	s_mul_i32 s1, s1, s5
	v_mul_f32_e32 v1, 0x4f7ffffe, v1
	v_cvt_u32_f32_e32 v1, v1
	v_readlane_b32 s5, v254, 13
	s_add_i32 s1, s1, s5
	s_abs_i32 s8, s1
	v_readfirstlane_b32 s9, v1
	s_mul_i32 s4, s4, s9
	s_mul_hi_u32 s4, s9, s4
	s_add_i32 s9, s9, s4
	s_mul_hi_u32 s4, s8, s9
	s_mul_i32 s9, s4, s0
	s_sub_i32 s8, s8, s9
	s_ashr_i32 s5, s1, 31
	s_add_i32 s11, s4, 1
	s_sub_i32 s9, s8, s0
	s_cmp_ge_u32 s8, s0
	s_cselect_b32 s4, s11, s4
	s_cselect_b32 s8, s9, s8
	s_add_i32 s9, s4, 1
	s_cmp_ge_u32 s8, s0
	s_cselect_b32 s4, s9, s4
	s_xor_b32 s4, s4, s5
	s_sub_i32 s4, s4, s5
	s_lshl_b32 s5, s4, 3
	s_sub_i32 s8, 32, s5
	s_min_i32 s8, s8, 8
	s_mul_i32 s4, s4, s0
	s_sext_i32_i8 s0, s8
	v_cvt_f32_i32_e32 v1, s0
	s_sub_i32 s4, s1, s4
	s_sext_i32_i8 s1, s4
	s_waitcnt vmcnt(0) lgkmcnt(0)
	v_cvt_f32_i32_e32 v2, s1
	v_rcp_iflag_f32_e32 v3, v1
	s_xor_b32 s0, s1, s0
	s_ashr_i32 s0, s0, 30
	s_or_b32 s9, s0, 1
	v_mul_f32_e32 v3, v2, v3
	v_trunc_f32_e32 v3, v3
	v_fma_f32 v2, -v3, v1, v2
	v_cvt_i32_f32_e32 v3, v3
	v_cmp_ge_f32_e64 s[0:1], |v2|, |v1|
	s_and_b64 s[0:1], s[0:1], exec
	s_cselect_b32 s0, s9, 0
	v_readfirstlane_b32 s1, v3
	s_add_i32 s1, s1, s0
	s_sext_i32_i8 s0, s1
	s_mul_i32 s1, s1, s8
	s_sub_i32 s1, s4, s1
	s_sext_i32_i8 s1, s1
	s_add_i32 s4, s5, s1

.La1_mine:
	v_mov_b32_e32 v238, 0x200f0
	ds_read_b64 v[236:237], v238
	s_waitcnt lgkmcnt(0)
	v_readfirstlane_b32 s20, v236
	v_readfirstlane_b32 s21, v237
	s_barrier
	v_and_b32_e32 v236, 63, v0
	v_lshrrev_b32_e32 v237, 6, v0
	v_lshrrev_b32_e32 v238, 3, v236
	v_lshrrev_b32_e32 v239, 4, v236
	s_nop 0
	v_readfirstlane_b32 s0, v237
	v_add_u32_e32 v200, 0, v239
	v_xor_b32_e32 v200, v200, v236
	v_and_b32_e32 v200, 7, v200
	v_lshlrev_b32_e32 v200, 4, v200
	v_lshl_add_u32 v130, v237, 5, v238
	v_add_u32_e32 v130, 0, v130
	v_mul_u32_u24_e32 v130, 0x800, v130
	v_add_u32_e32 v200, v200, v130
	v_add_u32_e32 v201, 4, v239
	v_xor_b32_e32 v201, v201, v236
	v_and_b32_e32 v201, 7, v201
	v_lshlrev_b32_e32 v201, 4, v201
	v_lshl_add_u32 v130, v237, 5, v238
	v_add_u32_e32 v130, 8, v130
	v_mul_u32_u24_e32 v130, 0x800, v130
	v_add_u32_e32 v201, v201, v130
	v_add_u32_e32 v202, 8, v239
	v_xor_b32_e32 v202, v202, v236
	v_and_b32_e32 v202, 7, v202
	v_lshlrev_b32_e32 v202, 4, v202
	v_lshl_add_u32 v130, v237, 5, v238
	v_add_u32_e32 v130, 16, v130
	v_mul_u32_u24_e32 v130, 0x800, v130
	v_add_u32_e32 v202, v202, v130
	v_add_u32_e32 v203, 12, v239
	v_xor_b32_e32 v203, v203, v236
	v_and_b32_e32 v203, 7, v203
	v_lshlrev_b32_e32 v203, 4, v203
	v_lshl_add_u32 v130, v237, 5, v238
	v_add_u32_e32 v130, 24, v130
	v_mul_u32_u24_e32 v130, 0x800, v130
	v_add_u32_e32 v203, v203, v130
	v_add_u32_e32 v204, 0, v239
	v_xor_b32_e32 v204, v204, v236
	v_and_b32_e32 v204, 7, v204
	v_lshlrev_b32_e32 v204, 4, v204
	v_lshl_add_u32 v130, v237, 4, v238
	v_add_u32_e32 v130, 0, v130
	v_mul_u32_u24_e32 v130, 0x800, v130
	v_add_u32_e32 v204, v204, v130
	v_add_u32_e32 v205, 4, v239
	v_xor_b32_e32 v205, v205, v236
	v_and_b32_e32 v205, 7, v205
	v_lshlrev_b32_e32 v205, 4, v205
	v_lshl_add_u32 v130, v237, 4, v238
	v_add_u32_e32 v130, 8, v130
	v_mul_u32_u24_e32 v130, 0x800, v130
	v_add_u32_e32 v205, v205, v130
	v_and_b32_e32 v238, 15, v236
	v_lshrrev_b32_e32 v130, 1, v238
	v_xor_b32_e32 v130, v130, v239
	v_lshlrev_b32_e32 v130, 4, v130
	v_lshrrev_b32_e32 v236, 1, v237
	v_lshl_add_u32 v236, v236, 6, v238
	v_lshl_add_u32 v236, v236, 7, v130
	v_and_b32_e32 v237, 1, v237
	v_lshl_add_u32 v237, v237, 6, v238
	v_lshl_add_u32 v237, v237, 7, v130
	v_add_u32_e32 v218, 0x100, v236
	v_xor_b32_e32 v225, 64, v218
	v_add_u32_e32 v230, 0x8100, v237
	v_xor_b32_e32 v233, 64, v230
	v_add_u32_e32 v219, 0xc100, v236
	v_xor_b32_e32 v228, 64, v219
	v_add_u32_e32 v231, 0x14100, v237
	v_xor_b32_e32 v234, 64, v231
	v_add_u32_e32 v224, 0x18100, v236
	v_xor_b32_e32 v229, 64, v224
	v_add_u32_e32 v232, 0x20100, v237
	v_xor_b32_e32 v235, 64, v232
	s_lshl_b32 s1, s0, 12
	s_add_u32 s8, s1, 0x100
	s_lshl_b32 s1, s0, 11
	s_add_u32 s9, s1, 0x8100
	v_and_b32_e32 v238, 63, v0
	v_lshrrev_b32_e32 v239, 6, v0
	v_and_b32_e32 v1, 15, v238
	v_lshrrev_b32_e32 v238, 4, v238
	v_lshrrev_b32_e32 v130, 1, v239
	v_lshl_add_u32 v1, v130, 6, v1
	v_and_b32_e32 v239, 1, v239
	v_lshlrev_b32_e32 v236, 11, v1
	v_lshl_add_u32 v236, v239, 7, v236
	v_lshl_add_u32 v236, v238, 3, v236
	v_mul_u32_u24_e32 v237, 0x2200, v1
	v_lshl_add_u32 v237, v239, 8, v237
	v_lshl_add_u32 v237, v238, 4, v237
	s_and_b32 s1, s2, 31
	s_lshr_b32 s22, s2, 5
	s_lshl_b32 s23, s1, 19
	s_add_u32 s4, s26, s23
	s_addc_u32 s5, s27, 0
	v_readlane_b32 s6, v254, 57
	v_readlane_b32 s7, v254, 58
	s_lshl_b32 s50, s22, 1
	s_add_u32 s50, s50, 1
	s_cmp_eq_u32 s22, 4
	s_cselect_b32 s50, 0, s50
	s_lshl_b32 s51, s50, 18
	s_add_u32 s51, s51, 0x400000
	s_add_u32 s6, s6, s51
	s_addc_u32 s7, s7, 0
	s_mov_b32 s12, 0xbfb8aa3b
	s_add_u32 s52, s28, 0x4400000
	s_addc_u32 s53, s29, 0
	s_add_u32 s52, s52, s23
	s_addc_u32 s53, s53, 0
	s_sub_u32 s51, s50, 1
	s_lshl_b32 s51, s51, 8
	s_add_u32 s52, s52, s51
	s_addc_u32 s53, s53, 0
	s_cmp_eq_u32 s22, 4
	s_cbranch_scc1 .La1_p
	s_mov_b32 m0, s8
	s_nop 0
	global_load_lds_dwordx4 v200, s[4:5]
	s_add_u32 m0, s8, 0x400
	s_nop 0
	global_load_lds_dwordx4 v201, s[4:5]
	s_add_u32 m0, s8, 0x800
	s_nop 0
	global_load_lds_dwordx4 v202, s[4:5]
	s_add_u32 m0, s8, 0xc00
	s_nop 0
	global_load_lds_dwordx4 v203, s[4:5]
	s_mov_b32 m0, s9
	s_nop 0
	global_load_lds_dwordx4 v204, s[6:7]
	s_add_u32 m0, s9, 0x400
	s_nop 0
	global_load_lds_dwordx4 v205, s[6:7]
	s_add_u32 s4, s4, 0x80
	s_addc_u32 s5, s5, 0
	s_add_u32 s6, s6, 0x80
	s_addc_u32 s7, s7, 0
	s_add_u32 m0, s8, 0xc000
	s_nop 0
	global_load_lds_dwordx4 v200, s[4:5]
	s_add_u32 m0, s8, 0xc400
	s_nop 0
	global_load_lds_dwordx4 v201, s[4:5]
	s_add_u32 m0, s8, 0xc800
	s_nop 0
	global_load_lds_dwordx4 v202, s[4:5]
	s_add_u32 m0, s8, 0xcc00
	s_nop 0
	global_load_lds_dwordx4 v203, s[4:5]
	s_add_u32 m0, s9, 0xc000
	s_nop 0
	global_load_lds_dwordx4 v204, s[6:7]
	s_add_u32 m0, s9, 0xc400
	s_nop 0
	global_load_lds_dwordx4 v205, s[6:7]
	s_add_u32 s4, s4, 0x80
	s_addc_u32 s5, s5, 0
	s_add_u32 s6, s6, 0x80
	s_addc_u32 s7, s7, 0
	s_add_u32 m0, s8, 0x18000
	s_nop 0
	global_load_lds_dwordx4 v200, s[4:5]
	s_add_u32 m0, s8, 0x18400
	s_nop 0
	global_load_lds_dwordx4 v201, s[4:5]
	s_add_u32 m0, s8, 0x18800
	s_nop 0
	global_load_lds_dwordx4 v202, s[4:5]
	s_add_u32 m0, s8, 0x18c00
	s_nop 0
	global_load_lds_dwordx4 v203, s[4:5]
	s_add_u32 m0, s9, 0x18000
	s_nop 0
	global_load_lds_dwordx4 v204, s[6:7]
	s_add_u32 m0, s9, 0x18400
	s_nop 0
	global_load_lds_dwordx4 v205, s[6:7]
	s_add_u32 s4, s4, 0x80
	s_addc_u32 s5, s5, 0
	s_add_u32 s6, s6, 0x80
	s_addc_u32 s7, s7, 0
	s_waitcnt vmcnt(12)
	s_barrier
	ds_read_b128 v[136:139], v218 offset:0
	ds_read_b128 v[140:143], v218 offset:2048
	ds_read_b128 v[144:147], v218 offset:4096
	ds_read_b128 v[148:151], v218 offset:6144
	ds_read_b128 v[152:155], v230 offset:0
	ds_read_b128 v[156:159], v230 offset:2048
	ds_read_b128 v[160:163], v230 offset:4096
	ds_read_b128 v[164:167], v230 offset:6144
	s_waitcnt lgkmcnt(0)
	v_mfma_f32_16x16x32_bf16 v[2:5], v[152:155], v[136:139], 0
	ds_read_b128 v[168:171], v225 offset:0
	v_mfma_f32_16x16x32_bf16 v[6:9], v[156:159], v[136:139], 0
	ds_read_b128 v[172:175], v225 offset:2048
	v_mfma_f32_16x16x32_bf16 v[10:13], v[160:163], v[136:139], 0
	ds_read_b128 v[176:179], v225 offset:4096
	v_mfma_f32_16x16x32_bf16 v[14:17], v[164:167], v[136:139], 0
	ds_read_b128 v[180:183], v225 offset:6144
	v_mfma_f32_16x16x32_bf16 v[18:21], v[152:155], v[140:143], 0
	ds_read_b128 v[184:187], v233 offset:0
	v_mfma_f32_16x16x32_bf16 v[22:25], v[156:159], v[140:143], 0
	ds_read_b128 v[188:191], v233 offset:2048
	v_mfma_f32_16x16x32_bf16 v[26:29], v[160:163], v[140:143], 0
	ds_read_b128 v[192:195], v233 offset:4096
	v_mfma_f32_16x16x32_bf16 v[30:33], v[164:167], v[140:143], 0
	ds_read_b128 v[196:199], v233 offset:6144
	v_mfma_f32_16x16x32_bf16 v[34:37], v[152:155], v[144:147], 0
	v_mfma_f32_16x16x32_bf16 v[38:41], v[156:159], v[144:147], 0
	v_mfma_f32_16x16x32_bf16 v[42:45], v[160:163], v[144:147], 0
	v_mfma_f32_16x16x32_bf16 v[46:49], v[164:167], v[144:147], 0
	v_mfma_f32_16x16x32_bf16 v[50:53], v[152:155], v[148:151], 0
	v_mfma_f32_16x16x32_bf16 v[54:57], v[156:159], v[148:151], 0
	v_mfma_f32_16x16x32_bf16 v[58:61], v[160:163], v[148:151], 0
	v_mfma_f32_16x16x32_bf16 v[62:65], v[164:167], v[148:151], 0
	s_waitcnt vmcnt(6) lgkmcnt(0)
	s_barrier
	v_mfma_f32_16x16x32_bf16 v[2:5], v[184:187], v[168:171], v[2:5]
	ds_read_b128 v[136:139], v219 offset:0
	v_mfma_f32_16x16x32_bf16 v[6:9], v[188:191], v[168:171], v[6:9]
	ds_read_b128 v[140:143], v219 offset:2048
	v_mfma_f32_16x16x32_bf16 v[10:13], v[192:195], v[168:171], v[10:13]
	ds_read_b128 v[144:147], v219 offset:4096
	v_mfma_f32_16x16x32_bf16 v[14:17], v[196:199], v[168:171], v[14:17]
	ds_read_b128 v[148:151], v219 offset:6144
	v_mfma_f32_16x16x32_bf16 v[18:21], v[184:187], v[172:175], v[18:21]
	ds_read_b128 v[152:155], v231 offset:0
	v_mfma_f32_16x16x32_bf16 v[22:25], v[188:191], v[172:175], v[22:25]
	ds_read_b128 v[156:159], v231 offset:2048
	v_mfma_f32_16x16x32_bf16 v[26:29], v[192:195], v[172:175], v[26:29]
	ds_read_b128 v[160:163], v231 offset:4096
	v_mfma_f32_16x16x32_bf16 v[30:33], v[196:199], v[172:175], v[30:33]
	ds_read_b128 v[164:167], v231 offset:6144
	s_mov_b32 m0, s8
	v_mfma_f32_16x16x32_bf16 v[34:37], v[184:187], v[176:179], v[34:37]
	global_load_lds_dwordx4 v200, s[4:5]
	s_add_u32 m0, s8, 0x400
	v_mfma_f32_16x16x32_bf16 v[38:41], v[188:191], v[176:179], v[38:41]
	global_load_lds_dwordx4 v201, s[4:5]
	s_add_u32 m0, s8, 0x800
	v_mfma_f32_16x16x32_bf16 v[42:45], v[192:195], v[176:179], v[42:45]
	global_load_lds_dwordx4 v202, s[4:5]
	s_add_u32 m0, s8, 0xc00
	v_mfma_f32_16x16x32_bf16 v[46:49], v[196:199], v[176:179], v[46:49]
	global_load_lds_dwordx4 v203, s[4:5]
	s_mov_b32 m0, s9
	v_mfma_f32_16x16x32_bf16 v[50:53], v[184:187], v[180:183], v[50:53]
	global_load_lds_dwordx4 v204, s[6:7]
	s_add_u32 m0, s9, 0x400
	v_mfma_f32_16x16x32_bf16 v[54:57], v[188:191], v[180:183], v[54:57]
	global_load_lds_dwordx4 v205, s[6:7]
	v_mfma_f32_16x16x32_bf16 v[58:61], v[192:195], v[180:183], v[58:61]
	s_add_u32 s4, s4, 0x80
	s_addc_u32 s5, s5, 0
	v_mfma_f32_16x16x32_bf16 v[62:65], v[196:199], v[180:183], v[62:65]
	s_add_u32 s6, s6, 0x80
	s_addc_u32 s7, s7, 0
	s_waitcnt lgkmcnt(0)
	v_mfma_f32_16x16x32_bf16 v[2:5], v[152:155], v[136:139], v[2:5]
	ds_read_b128 v[168:171], v228 offset:0
	v_mfma_f32_16x16x32_bf16 v[6:9], v[156:159], v[136:139], v[6:9]
	ds_read_b128 v[172:175], v228 offset:2048
	v_mfma_f32_16x16x32_bf16 v[10:13], v[160:163], v[136:139], v[10:13]
	ds_read_b128 v[176:179], v228 offset:4096
	v_mfma_f32_16x16x32_bf16 v[14:17], v[164:167], v[136:139], v[14:17]
	ds_read_b128 v[180:183], v228 offset:6144
	v_mfma_f32_16x16x32_bf16 v[18:21], v[152:155], v[140:143], v[18:21]
	ds_read_b128 v[184:187], v234 offset:0
	v_mfma_f32_16x16x32_bf16 v[22:25], v[156:159], v[140:143], v[22:25]
	ds_read_b128 v[188:191], v234 offset:2048
	v_mfma_f32_16x16x32_bf16 v[26:29], v[160:163], v[140:143], v[26:29]
	ds_read_b128 v[192:195], v234 offset:4096
	v_mfma_f32_16x16x32_bf16 v[30:33], v[164:167], v[140:143], v[30:33]
	ds_read_b128 v[196:199], v234 offset:6144
	v_mfma_f32_16x16x32_bf16 v[34:37], v[152:155], v[144:147], v[34:37]
	v_mfma_f32_16x16x32_bf16 v[38:41], v[156:159], v[144:147], v[38:41]
	v_mfma_f32_16x16x32_bf16 v[42:45], v[160:163], v[144:147], v[42:45]
	v_mfma_f32_16x16x32_bf16 v[46:49], v[164:167], v[144:147], v[46:49]
	v_mfma_f32_16x16x32_bf16 v[50:53], v[152:155], v[148:151], v[50:53]
	v_mfma_f32_16x16x32_bf16 v[54:57], v[156:159], v[148:151], v[54:57]
	v_mfma_f32_16x16x32_bf16 v[58:61], v[160:163], v[148:151], v[58:61]
	v_mfma_f32_16x16x32_bf16 v[62:65], v[164:167], v[148:151], v[62:65]
	s_waitcnt vmcnt(6) lgkmcnt(0)
	s_barrier
	v_mfma_f32_16x16x32_bf16 v[2:5], v[184:187], v[168:171], v[2:5]
	ds_read_b128 v[136:139], v224 offset:0
	v_mfma_f32_16x16x32_bf16 v[6:9], v[188:191], v[168:171], v[6:9]
	ds_read_b128 v[140:143], v224 offset:2048
	v_mfma_f32_16x16x32_bf16 v[10:13], v[192:195], v[168:171], v[10:13]
	ds_read_b128 v[144:147], v224 offset:4096
	v_mfma_f32_16x16x32_bf16 v[14:17], v[196:199], v[168:171], v[14:17]
	ds_read_b128 v[148:151], v224 offset:6144
	v_mfma_f32_16x16x32_bf16 v[18:21], v[184:187], v[172:175], v[18:21]
	ds_read_b128 v[152:155], v232 offset:0
	v_mfma_f32_16x16x32_bf16 v[22:25], v[188:191], v[172:175], v[22:25]
	ds_read_b128 v[156:159], v232 offset:2048
	v_mfma_f32_16x16x32_bf16 v[26:29], v[192:195], v[172:175], v[26:29]
	ds_read_b128 v[160:163], v232 offset:4096
	v_mfma_f32_16x16x32_bf16 v[30:33], v[196:199], v[172:175], v[30:33]
	ds_read_b128 v[164:167], v232 offset:6144
	s_add_u32 m0, s8, 0xc000
	v_mfma_f32_16x16x32_bf16 v[34:37], v[184:187], v[176:179], v[34:37]
	global_load_lds_dwordx4 v200, s[4:5]
	s_add_u32 m0, s8, 0xc400
	v_mfma_f32_16x16x32_bf16 v[38:41], v[188:191], v[176:179], v[38:41]
	global_load_lds_dwordx4 v201, s[4:5]
	s_add_u32 m0, s8, 0xc800
	v_mfma_f32_16x16x32_bf16 v[42:45], v[192:195], v[176:179], v[42:45]
	global_load_lds_dwordx4 v202, s[4:5]
	s_add_u32 m0, s8, 0xcc00
	v_mfma_f32_16x16x32_bf16 v[46:49], v[196:199], v[176:179], v[46:49]
	global_load_lds_dwordx4 v203, s[4:5]
	s_add_u32 m0, s9, 0xc000
	v_mfma_f32_16x16x32_bf16 v[50:53], v[184:187], v[180:183], v[50:53]
	global_load_lds_dwordx4 v204, s[6:7]
	s_add_u32 m0, s9, 0xc400
	v_mfma_f32_16x16x32_bf16 v[54:57], v[188:191], v[180:183], v[54:57]
	global_load_lds_dwordx4 v205, s[6:7]
	v_mfma_f32_16x16x32_bf16 v[58:61], v[192:195], v[180:183], v[58:61]
	s_add_u32 s4, s4, 0x80
	s_addc_u32 s5, s5, 0
	v_mfma_f32_16x16x32_bf16 v[62:65], v[196:199], v[180:183], v[62:65]
	s_add_u32 s6, s6, 0x80
	s_addc_u32 s7, s7, 0
	s_waitcnt lgkmcnt(0)
	v_mfma_f32_16x16x32_bf16 v[2:5], v[152:155], v[136:139], v[2:5]
	ds_read_b128 v[168:171], v229 offset:0
	v_mfma_f32_16x16x32_bf16 v[6:9], v[156:159], v[136:139], v[6:9]
	ds_read_b128 v[172:175], v229 offset:2048
	v_mfma_f32_16x16x32_bf16 v[10:13], v[160:163], v[136:139], v[10:13]
	ds_read_b128 v[176:179], v229 offset:4096
	v_mfma_f32_16x16x32_bf16 v[14:17], v[164:167], v[136:139], v[14:17]
	ds_read_b128 v[180:183], v229 offset:6144
	v_mfma_f32_16x16x32_bf16 v[18:21], v[152:155], v[140:143], v[18:21]
	ds_read_b128 v[184:187], v235 offset:0
	v_mfma_f32_16x16x32_bf16 v[22:25], v[156:159], v[140:143], v[22:25]
	ds_read_b128 v[188:191], v235 offset:2048
	v_mfma_f32_16x16x32_bf16 v[26:29], v[160:163], v[140:143], v[26:29]
	ds_read_b128 v[192:195], v235 offset:4096
	v_mfma_f32_16x16x32_bf16 v[30:33], v[164:167], v[140:143], v[30:33]
	ds_read_b128 v[196:199], v235 offset:6144
	v_mfma_f32_16x16x32_bf16 v[34:37], v[152:155], v[144:147], v[34:37]
	v_mfma_f32_16x16x32_bf16 v[38:41], v[156:159], v[144:147], v[38:41]
	v_mfma_f32_16x16x32_bf16 v[42:45], v[160:163], v[144:147], v[42:45]
	v_mfma_f32_16x16x32_bf16 v[46:49], v[164:167], v[144:147], v[46:49]
	v_mfma_f32_16x16x32_bf16 v[50:53], v[152:155], v[148:151], v[50:53]
	v_mfma_f32_16x16x32_bf16 v[54:57], v[156:159], v[148:151], v[54:57]
	v_mfma_f32_16x16x32_bf16 v[58:61], v[160:163], v[148:151], v[58:61]
	v_mfma_f32_16x16x32_bf16 v[62:65], v[164:167], v[148:151], v[62:65]
	s_waitcnt vmcnt(6) lgkmcnt(0)
	s_barrier
	v_mfma_f32_16x16x32_bf16 v[2:5], v[184:187], v[168:171], v[2:5]
	ds_read_b128 v[136:139], v218 offset:0
	v_mfma_f32_16x16x32_bf16 v[6:9], v[188:191], v[168:171], v[6:9]
	ds_read_b128 v[140:143], v218 offset:2048
	v_mfma_f32_16x16x32_bf16 v[10:13], v[192:195], v[168:171], v[10:13]
	ds_read_b128 v[144:147], v218 offset:4096
	v_mfma_f32_16x16x32_bf16 v[14:17], v[196:199], v[168:171], v[14:17]
	ds_read_b128 v[148:151], v218 offset:6144
	v_mfma_f32_16x16x32_bf16 v[18:21], v[184:187], v[172:175], v[18:21]
	ds_read_b128 v[152:155], v230 offset:0
	v_mfma_f32_16x16x32_bf16 v[22:25], v[188:191], v[172:175], v[22:25]
	ds_read_b128 v[156:159], v230 offset:2048
	v_mfma_f32_16x16x32_bf16 v[26:29], v[192:195], v[172:175], v[26:29]
	ds_read_b128 v[160:163], v230 offset:4096
	v_mfma_f32_16x16x32_bf16 v[30:33], v[196:199], v[172:175], v[30:33]
	ds_read_b128 v[164:167], v230 offset:6144
	s_add_u32 m0, s8, 0x18000
	v_mfma_f32_16x16x32_bf16 v[34:37], v[184:187], v[176:179], v[34:37]
	global_load_lds_dwordx4 v200, s[4:5]
	s_add_u32 m0, s8, 0x18400
	v_mfma_f32_16x16x32_bf16 v[38:41], v[188:191], v[176:179], v[38:41]
	global_load_lds_dwordx4 v201, s[4:5]
	s_add_u32 m0, s8, 0x18800
	v_mfma_f32_16x16x32_bf16 v[42:45], v[192:195], v[176:179], v[42:45]
	global_load_lds_dwordx4 v202, s[4:5]
	s_add_u32 m0, s8, 0x18c00
	v_mfma_f32_16x16x32_bf16 v[46:49], v[196:199], v[176:179], v[46:49]
	global_load_lds_dwordx4 v203, s[4:5]
	s_add_u32 m0, s9, 0x18000
	v_mfma_f32_16x16x32_bf16 v[50:53], v[184:187], v[180:183], v[50:53]
	global_load_lds_dwordx4 v204, s[6:7]
	s_add_u32 m0, s9, 0x18400
	v_mfma_f32_16x16x32_bf16 v[54:57], v[188:191], v[180:183], v[54:57]
	global_load_lds_dwordx4 v205, s[6:7]
	v_mfma_f32_16x16x32_bf16 v[58:61], v[192:195], v[180:183], v[58:61]
	s_add_u32 s4, s4, 0x80
	s_addc_u32 s5, s5, 0
	v_mfma_f32_16x16x32_bf16 v[62:65], v[196:199], v[180:183], v[62:65]
	s_add_u32 s6, s6, 0x80
	s_addc_u32 s7, s7, 0
	s_waitcnt lgkmcnt(0)
	v_mfma_f32_16x16x32_bf16 v[2:5], v[152:155], v[136:139], v[2:5]
	ds_read_b128 v[168:171], v225 offset:0
	v_mfma_f32_16x16x32_bf16 v[6:9], v[156:159], v[136:139], v[6:9]
	ds_read_b128 v[172:175], v225 offset:2048
	v_mfma_f32_16x16x32_bf16 v[10:13], v[160:163], v[136:139], v[10:13]
	ds_read_b128 v[176:179], v225 offset:4096
	v_mfma_f32_16x16x32_bf16 v[14:17], v[164:167], v[136:139], v[14:17]
	ds_read_b128 v[180:183], v225 offset:6144
	v_mfma_f32_16x16x32_bf16 v[18:21], v[152:155], v[140:143], v[18:21]
	ds_read_b128 v[184:187], v233 offset:0
	v_mfma_f32_16x16x32_bf16 v[22:25], v[156:159], v[140:143], v[22:25]
	ds_read_b128 v[188:191], v233 offset:2048
	v_mfma_f32_16x16x32_bf16 v[26:29], v[160:163], v[140:143], v[26:29]
	ds_read_b128 v[192:195], v233 offset:4096
	v_mfma_f32_16x16x32_bf16 v[30:33], v[164:167], v[140:143], v[30:33]
	ds_read_b128 v[196:199], v233 offset:6144
	v_mfma_f32_16x16x32_bf16 v[34:37], v[152:155], v[144:147], v[34:37]
	v_mfma_f32_16x16x32_bf16 v[38:41], v[156:159], v[144:147], v[38:41]
	v_mfma_f32_16x16x32_bf16 v[42:45], v[160:163], v[144:147], v[42:45]
	v_mfma_f32_16x16x32_bf16 v[46:49], v[164:167], v[144:147], v[46:49]
	v_mfma_f32_16x16x32_bf16 v[50:53], v[152:155], v[148:151], v[50:53]
	v_mfma_f32_16x16x32_bf16 v[54:57], v[156:159], v[148:151], v[54:57]
	v_mfma_f32_16x16x32_bf16 v[58:61], v[160:163], v[148:151], v[58:61]
	v_mfma_f32_16x16x32_bf16 v[62:65], v[164:167], v[148:151], v[62:65]
	s_waitcnt vmcnt(6) lgkmcnt(0)
	s_barrier
	v_mfma_f32_16x16x32_bf16 v[2:5], v[184:187], v[168:171], v[2:5]
	ds_read_b128 v[136:139], v219 offset:0
	v_mfma_f32_16x16x32_bf16 v[6:9], v[188:191], v[168:171], v[6:9]
	ds_read_b128 v[140:143], v219 offset:2048
	v_mfma_f32_16x16x32_bf16 v[10:13], v[192:195], v[168:171], v[10:13]
	ds_read_b128 v[144:147], v219 offset:4096
	v_mfma_f32_16x16x32_bf16 v[14:17], v[196:199], v[168:171], v[14:17]
	ds_read_b128 v[148:151], v219 offset:6144
	v_mfma_f32_16x16x32_bf16 v[18:21], v[184:187], v[172:175], v[18:21]
	ds_read_b128 v[152:155], v231 offset:0
	v_mfma_f32_16x16x32_bf16 v[22:25], v[188:191], v[172:175], v[22:25]
	ds_read_b128 v[156:159], v231 offset:2048
	v_mfma_f32_16x16x32_bf16 v[26:29], v[192:195], v[172:175], v[26:29]
	ds_read_b128 v[160:163], v231 offset:4096
	v_mfma_f32_16x16x32_bf16 v[30:33], v[196:199], v[172:175], v[30:33]
	ds_read_b128 v[164:167], v231 offset:6144
	s_mov_b32 m0, s8
	v_mfma_f32_16x16x32_bf16 v[34:37], v[184:187], v[176:179], v[34:37]
	global_load_lds_dwordx4 v200, s[4:5]
	s_add_u32 m0, s8, 0x400
	v_mfma_f32_16x16x32_bf16 v[38:41], v[188:191], v[176:179], v[38:41]
	global_load_lds_dwordx4 v201, s[4:5]
	s_add_u32 m0, s8, 0x800
	v_mfma_f32_16x16x32_bf16 v[42:45], v[192:195], v[176:179], v[42:45]
	global_load_lds_dwordx4 v202, s[4:5]
	s_add_u32 m0, s8, 0xc00
	v_mfma_f32_16x16x32_bf16 v[46:49], v[196:199], v[176:179], v[46:49]
	global_load_lds_dwordx4 v203, s[4:5]
	s_mov_b32 m0, s9
	v_mfma_f32_16x16x32_bf16 v[50:53], v[184:187], v[180:183], v[50:53]
	global_load_lds_dwordx4 v204, s[6:7]
	s_add_u32 m0, s9, 0x400
	v_mfma_f32_16x16x32_bf16 v[54:57], v[188:191], v[180:183], v[54:57]
	global_load_lds_dwordx4 v205, s[6:7]
	v_mfma_f32_16x16x32_bf16 v[58:61], v[192:195], v[180:183], v[58:61]
	s_add_u32 s4, s4, 0x80
	s_addc_u32 s5, s5, 0
	v_mfma_f32_16x16x32_bf16 v[62:65], v[196:199], v[180:183], v[62:65]
	s_add_u32 s6, s6, 0x80
	s_addc_u32 s7, s7, 0
	s_waitcnt lgkmcnt(0)
	v_mfma_f32_16x16x32_bf16 v[2:5], v[152:155], v[136:139], v[2:5]
	ds_read_b128 v[168:171], v228 offset:0
	v_mfma_f32_16x16x32_bf16 v[6:9], v[156:159], v[136:139], v[6:9]
	ds_read_b128 v[172:175], v228 offset:2048
	v_mfma_f32_16x16x32_bf16 v[10:13], v[160:163], v[136:139], v[10:13]
	ds_read_b128 v[176:179], v228 offset:4096
	v_mfma_f32_16x16x32_bf16 v[14:17], v[164:167], v[136:139], v[14:17]
	ds_read_b128 v[180:183], v228 offset:6144
	v_mfma_f32_16x16x32_bf16 v[18:21], v[152:155], v[140:143], v[18:21]
	ds_read_b128 v[184:187], v234 offset:0
	v_mfma_f32_16x16x32_bf16 v[22:25], v[156:159], v[140:143], v[22:25]
	ds_read_b128 v[188:191], v234 offset:2048
	v_mfma_f32_16x16x32_bf16 v[26:29], v[160:163], v[140:143], v[26:29]
	ds_read_b128 v[192:195], v234 offset:4096
	v_mfma_f32_16x16x32_bf16 v[30:33], v[164:167], v[140:143], v[30:33]
	ds_read_b128 v[196:199], v234 offset:6144
	v_mfma_f32_16x16x32_bf16 v[34:37], v[152:155], v[144:147], v[34:37]
	v_mfma_f32_16x16x32_bf16 v[38:41], v[156:159], v[144:147], v[38:41]
	v_mfma_f32_16x16x32_bf16 v[42:45], v[160:163], v[144:147], v[42:45]
	v_mfma_f32_16x16x32_bf16 v[46:49], v[164:167], v[144:147], v[46:49]
	v_mfma_f32_16x16x32_bf16 v[50:53], v[152:155], v[148:151], v[50:53]
	v_mfma_f32_16x16x32_bf16 v[54:57], v[156:159], v[148:151], v[54:57]
	v_mfma_f32_16x16x32_bf16 v[58:61], v[160:163], v[148:151], v[58:61]
	v_mfma_f32_16x16x32_bf16 v[62:65], v[164:167], v[148:151], v[62:65]
	s_waitcnt vmcnt(6) lgkmcnt(0)
	s_barrier
	v_mfma_f32_16x16x32_bf16 v[2:5], v[184:187], v[168:171], v[2:5]
	ds_read_b128 v[136:139], v224 offset:0
	v_mfma_f32_16x16x32_bf16 v[6:9], v[188:191], v[168:171], v[6:9]
	ds_read_b128 v[140:143], v224 offset:2048
	v_mfma_f32_16x16x32_bf16 v[10:13], v[192:195], v[168:171], v[10:13]
	ds_read_b128 v[144:147], v224 offset:4096
	v_mfma_f32_16x16x32_bf16 v[14:17], v[196:199], v[168:171], v[14:17]
	ds_read_b128 v[148:151], v224 offset:6144
	v_mfma_f32_16x16x32_bf16 v[18:21], v[184:187], v[172:175], v[18:21]
	ds_read_b128 v[152:155], v232 offset:0
	v_mfma_f32_16x16x32_bf16 v[22:25], v[188:191], v[172:175], v[22:25]
	ds_read_b128 v[156:159], v232 offset:2048
	v_mfma_f32_16x16x32_bf16 v[26:29], v[192:195], v[172:175], v[26:29]
	ds_read_b128 v[160:163], v232 offset:4096
	v_mfma_f32_16x16x32_bf16 v[30:33], v[196:199], v[172:175], v[30:33]
	ds_read_b128 v[164:167], v232 offset:6144
	s_add_u32 m0, s8, 0xc000
	v_mfma_f32_16x16x32_bf16 v[34:37], v[184:187], v[176:179], v[34:37]
	global_load_lds_dwordx4 v200, s[4:5]
	s_add_u32 m0, s8, 0xc400
	v_mfma_f32_16x16x32_bf16 v[38:41], v[188:191], v[176:179], v[38:41]
	global_load_lds_dwordx4 v201, s[4:5]
	s_add_u32 m0, s8, 0xc800
	v_mfma_f32_16x16x32_bf16 v[42:45], v[192:195], v[176:179], v[42:45]
	global_load_lds_dwordx4 v202, s[4:5]
	s_add_u32 m0, s8, 0xcc00
	v_mfma_f32_16x16x32_bf16 v[46:49], v[196:199], v[176:179], v[46:49]
	global_load_lds_dwordx4 v203, s[4:5]
	s_add_u32 m0, s9, 0xc000
	v_mfma_f32_16x16x32_bf16 v[50:53], v[184:187], v[180:183], v[50:53]
	global_load_lds_dwordx4 v204, s[6:7]
	s_add_u32 m0, s9, 0xc400
	v_mfma_f32_16x16x32_bf16 v[54:57], v[188:191], v[180:183], v[54:57]
	global_load_lds_dwordx4 v205, s[6:7]
	v_mfma_f32_16x16x32_bf16 v[58:61], v[192:195], v[180:183], v[58:61]
	s_add_u32 s4, s4, 0x80
	s_addc_u32 s5, s5, 0
	v_mfma_f32_16x16x32_bf16 v[62:65], v[196:199], v[180:183], v[62:65]
	s_add_u32 s6, s6, 0x80
	s_addc_u32 s7, s7, 0
	s_waitcnt lgkmcnt(0)
	v_mfma_f32_16x16x32_bf16 v[2:5], v[152:155], v[136:139], v[2:5]
	ds_read_b128 v[168:171], v229 offset:0
	v_mfma_f32_16x16x32_bf16 v[6:9], v[156:159], v[136:139], v[6:9]
	ds_read_b128 v[172:175], v229 offset:2048
	v_mfma_f32_16x16x32_bf16 v[10:13], v[160:163], v[136:139], v[10:13]
	ds_read_b128 v[176:179], v229 offset:4096
	v_mfma_f32_16x16x32_bf16 v[14:17], v[164:167], v[136:139], v[14:17]
	ds_read_b128 v[180:183], v229 offset:6144
	v_mfma_f32_16x16x32_bf16 v[18:21], v[152:155], v[140:143], v[18:21]
	ds_read_b128 v[184:187], v235 offset:0
	v_mfma_f32_16x16x32_bf16 v[22:25], v[156:159], v[140:143], v[22:25]
	ds_read_b128 v[188:191], v235 offset:2048
	v_mfma_f32_16x16x32_bf16 v[26:29], v[160:163], v[140:143], v[26:29]
	ds_read_b128 v[192:195], v235 offset:4096
	v_mfma_f32_16x16x32_bf16 v[30:33], v[164:167], v[140:143], v[30:33]
	ds_read_b128 v[196:199], v235 offset:6144
	v_mfma_f32_16x16x32_bf16 v[34:37], v[152:155], v[144:147], v[34:37]
	v_mfma_f32_16x16x32_bf16 v[38:41], v[156:159], v[144:147], v[38:41]
	v_mfma_f32_16x16x32_bf16 v[42:45], v[160:163], v[144:147], v[42:45]
	v_mfma_f32_16x16x32_bf16 v[46:49], v[164:167], v[144:147], v[46:49]
	v_mfma_f32_16x16x32_bf16 v[50:53], v[152:155], v[148:151], v[50:53]
	v_mfma_f32_16x16x32_bf16 v[54:57], v[156:159], v[148:151], v[54:57]
	v_mfma_f32_16x16x32_bf16 v[58:61], v[160:163], v[148:151], v[58:61]
	v_mfma_f32_16x16x32_bf16 v[62:65], v[164:167], v[148:151], v[62:65]
	s_waitcnt vmcnt(6) lgkmcnt(0)
	s_barrier
	v_mfma_f32_16x16x32_bf16 v[2:5], v[184:187], v[168:171], v[2:5]
	ds_read_b128 v[136:139], v218 offset:0
	v_mfma_f32_16x16x32_bf16 v[6:9], v[188:191], v[168:171], v[6:9]
	ds_read_b128 v[140:143], v218 offset:2048
	v_mfma_f32_16x16x32_bf16 v[10:13], v[192:195], v[168:171], v[10:13]
	ds_read_b128 v[144:147], v218 offset:4096
	v_mfma_f32_16x16x32_bf16 v[14:17], v[196:199], v[168:171], v[14:17]
	ds_read_b128 v[148:151], v218 offset:6144
	v_mfma_f32_16x16x32_bf16 v[18:21], v[184:187], v[172:175], v[18:21]
	ds_read_b128 v[152:155], v230 offset:0
	v_mfma_f32_16x16x32_bf16 v[22:25], v[188:191], v[172:175], v[22:25]
	ds_read_b128 v[156:159], v230 offset:2048
	v_mfma_f32_16x16x32_bf16 v[26:29], v[192:195], v[172:175], v[26:29]
	ds_read_b128 v[160:163], v230 offset:4096
	v_mfma_f32_16x16x32_bf16 v[30:33], v[196:199], v[172:175], v[30:33]
	ds_read_b128 v[164:167], v230 offset:6144
	s_add_u32 m0, s8, 0x18000
	v_mfma_f32_16x16x32_bf16 v[34:37], v[184:187], v[176:179], v[34:37]
	global_load_lds_dwordx4 v200, s[4:5]
	s_add_u32 m0, s8, 0x18400
	v_mfma_f32_16x16x32_bf16 v[38:41], v[188:191], v[176:179], v[38:41]
	global_load_lds_dwordx4 v201, s[4:5]
	s_add_u32 m0, s8, 0x18800
	v_mfma_f32_16x16x32_bf16 v[42:45], v[192:195], v[176:179], v[42:45]
	global_load_lds_dwordx4 v202, s[4:5]
	s_add_u32 m0, s8, 0x18c00
	v_mfma_f32_16x16x32_bf16 v[46:49], v[196:199], v[176:179], v[46:49]
	global_load_lds_dwordx4 v203, s[4:5]
	s_add_u32 m0, s9, 0x18000
	v_mfma_f32_16x16x32_bf16 v[50:53], v[184:187], v[180:183], v[50:53]
	global_load_lds_dwordx4 v204, s[6:7]
	s_add_u32 m0, s9, 0x18400
	v_mfma_f32_16x16x32_bf16 v[54:57], v[188:191], v[180:183], v[54:57]
	global_load_lds_dwordx4 v205, s[6:7]
	v_mfma_f32_16x16x32_bf16 v[58:61], v[192:195], v[180:183], v[58:61]
	s_add_u32 s4, s4, 0x80
	s_addc_u32 s5, s5, 0
	v_mfma_f32_16x16x32_bf16 v[62:65], v[196:199], v[180:183], v[62:65]
	s_add_u32 s6, s6, 0x80
	s_addc_u32 s7, s7, 0
	s_waitcnt lgkmcnt(0)
	v_mfma_f32_16x16x32_bf16 v[2:5], v[152:155], v[136:139], v[2:5]
	ds_read_b128 v[168:171], v225 offset:0
	v_mfma_f32_16x16x32_bf16 v[6:9], v[156:159], v[136:139], v[6:9]
	ds_read_b128 v[172:175], v225 offset:2048
	v_mfma_f32_16x16x32_bf16 v[10:13], v[160:163], v[136:139], v[10:13]
	ds_read_b128 v[176:179], v225 offset:4096
	v_mfma_f32_16x16x32_bf16 v[14:17], v[164:167], v[136:139], v[14:17]
	ds_read_b128 v[180:183], v225 offset:6144
	v_mfma_f32_16x16x32_bf16 v[18:21], v[152:155], v[140:143], v[18:21]
	ds_read_b128 v[184:187], v233 offset:0
	v_mfma_f32_16x16x32_bf16 v[22:25], v[156:159], v[140:143], v[22:25]
	ds_read_b128 v[188:191], v233 offset:2048
	v_mfma_f32_16x16x32_bf16 v[26:29], v[160:163], v[140:143], v[26:29]
	ds_read_b128 v[192:195], v233 offset:4096
	v_mfma_f32_16x16x32_bf16 v[30:33], v[164:167], v[140:143], v[30:33]
	ds_read_b128 v[196:199], v233 offset:6144
	v_mfma_f32_16x16x32_bf16 v[34:37], v[152:155], v[144:147], v[34:37]
	v_mfma_f32_16x16x32_bf16 v[38:41], v[156:159], v[144:147], v[38:41]
	v_mfma_f32_16x16x32_bf16 v[42:45], v[160:163], v[144:147], v[42:45]
	v_mfma_f32_16x16x32_bf16 v[46:49], v[164:167], v[144:147], v[46:49]
	v_mfma_f32_16x16x32_bf16 v[50:53], v[152:155], v[148:151], v[50:53]
	v_mfma_f32_16x16x32_bf16 v[54:57], v[156:159], v[148:151], v[54:57]
	v_mfma_f32_16x16x32_bf16 v[58:61], v[160:163], v[148:151], v[58:61]
	v_mfma_f32_16x16x32_bf16 v[62:65], v[164:167], v[148:151], v[62:65]
	s_waitcnt vmcnt(6) lgkmcnt(0)
	s_barrier
	v_mfma_f32_16x16x32_bf16 v[2:5], v[184:187], v[168:171], v[2:5]
	ds_read_b128 v[136:139], v219 offset:0
	v_mfma_f32_16x16x32_bf16 v[6:9], v[188:191], v[168:171], v[6:9]
	ds_read_b128 v[140:143], v219 offset:2048
	v_mfma_f32_16x16x32_bf16 v[10:13], v[192:195], v[168:171], v[10:13]
	ds_read_b128 v[144:147], v219 offset:4096
	v_mfma_f32_16x16x32_bf16 v[14:17], v[196:199], v[168:171], v[14:17]
	ds_read_b128 v[148:151], v219 offset:6144
	v_mfma_f32_16x16x32_bf16 v[18:21], v[184:187], v[172:175], v[18:21]
	ds_read_b128 v[152:155], v231 offset:0
	v_mfma_f32_16x16x32_bf16 v[22:25], v[188:191], v[172:175], v[22:25]
	ds_read_b128 v[156:159], v231 offset:2048
	v_mfma_f32_16x16x32_bf16 v[26:29], v[192:195], v[172:175], v[26:29]
	ds_read_b128 v[160:163], v231 offset:4096
	v_mfma_f32_16x16x32_bf16 v[30:33], v[196:199], v[172:175], v[30:33]
	ds_read_b128 v[164:167], v231 offset:6144
	s_mov_b32 m0, s8
	v_mfma_f32_16x16x32_bf16 v[34:37], v[184:187], v[176:179], v[34:37]
	global_load_lds_dwordx4 v200, s[4:5]
	s_add_u32 m0, s8, 0x400
	v_mfma_f32_16x16x32_bf16 v[38:41], v[188:191], v[176:179], v[38:41]
	global_load_lds_dwordx4 v201, s[4:5]
	s_add_u32 m0, s8, 0x800
	v_mfma_f32_16x16x32_bf16 v[42:45], v[192:195], v[176:179], v[42:45]
	global_load_lds_dwordx4 v202, s[4:5]
	s_add_u32 m0, s8, 0xc00
	v_mfma_f32_16x16x32_bf16 v[46:49], v[196:199], v[176:179], v[46:49]
	global_load_lds_dwordx4 v203, s[4:5]
	s_mov_b32 m0, s9
	v_mfma_f32_16x16x32_bf16 v[50:53], v[184:187], v[180:183], v[50:53]
	global_load_lds_dwordx4 v204, s[6:7]
	s_add_u32 m0, s9, 0x400
	v_mfma_f32_16x16x32_bf16 v[54:57], v[188:191], v[180:183], v[54:57]
	global_load_lds_dwordx4 v205, s[6:7]
	v_mfma_f32_16x16x32_bf16 v[58:61], v[192:195], v[180:183], v[58:61]
	s_add_u32 s4, s4, 0x80
	s_addc_u32 s5, s5, 0
	v_mfma_f32_16x16x32_bf16 v[62:65], v[196:199], v[180:183], v[62:65]
	s_add_u32 s6, s6, 0x80
	s_addc_u32 s7, s7, 0
	s_waitcnt lgkmcnt(0)
	v_mfma_f32_16x16x32_bf16 v[2:5], v[152:155], v[136:139], v[2:5]
	ds_read_b128 v[168:171], v228 offset:0
	v_mfma_f32_16x16x32_bf16 v[6:9], v[156:159], v[136:139], v[6:9]
	ds_read_b128 v[172:175], v228 offset:2048
	v_mfma_f32_16x16x32_bf16 v[10:13], v[160:163], v[136:139], v[10:13]
	ds_read_b128 v[176:179], v228 offset:4096
	v_mfma_f32_16x16x32_bf16 v[14:17], v[164:167], v[136:139], v[14:17]
	ds_read_b128 v[180:183], v228 offset:6144
	v_mfma_f32_16x16x32_bf16 v[18:21], v[152:155], v[140:143], v[18:21]
	ds_read_b128 v[184:187], v234 offset:0
	v_mfma_f32_16x16x32_bf16 v[22:25], v[156:159], v[140:143], v[22:25]
	ds_read_b128 v[188:191], v234 offset:2048
	v_mfma_f32_16x16x32_bf16 v[26:29], v[160:163], v[140:143], v[26:29]
	ds_read_b128 v[192:195], v234 offset:4096
	v_mfma_f32_16x16x32_bf16 v[30:33], v[164:167], v[140:143], v[30:33]
	ds_read_b128 v[196:199], v234 offset:6144
	v_mfma_f32_16x16x32_bf16 v[34:37], v[152:155], v[144:147], v[34:37]
	v_mfma_f32_16x16x32_bf16 v[38:41], v[156:159], v[144:147], v[38:41]
	v_mfma_f32_16x16x32_bf16 v[42:45], v[160:163], v[144:147], v[42:45]
	v_mfma_f32_16x16x32_bf16 v[46:49], v[164:167], v[144:147], v[46:49]
	v_mfma_f32_16x16x32_bf16 v[50:53], v[152:155], v[148:151], v[50:53]
	v_mfma_f32_16x16x32_bf16 v[54:57], v[156:159], v[148:151], v[54:57]
	v_mfma_f32_16x16x32_bf16 v[58:61], v[160:163], v[148:151], v[58:61]
	v_mfma_f32_16x16x32_bf16 v[62:65], v[164:167], v[148:151], v[62:65]
	s_waitcnt vmcnt(6) lgkmcnt(0)
	s_barrier
	v_mfma_f32_16x16x32_bf16 v[2:5], v[184:187], v[168:171], v[2:5]
	ds_read_b128 v[136:139], v224 offset:0
	v_mfma_f32_16x16x32_bf16 v[6:9], v[188:191], v[168:171], v[6:9]
	ds_read_b128 v[140:143], v224 offset:2048
	v_mfma_f32_16x16x32_bf16 v[10:13], v[192:195], v[168:171], v[10:13]
	ds_read_b128 v[144:147], v224 offset:4096
	v_mfma_f32_16x16x32_bf16 v[14:17], v[196:199], v[168:171], v[14:17]
	ds_read_b128 v[148:151], v224 offset:6144
	v_mfma_f32_16x16x32_bf16 v[18:21], v[184:187], v[172:175], v[18:21]
	ds_read_b128 v[152:155], v232 offset:0
	v_mfma_f32_16x16x32_bf16 v[22:25], v[188:191], v[172:175], v[22:25]
	ds_read_b128 v[156:159], v232 offset:2048
	v_mfma_f32_16x16x32_bf16 v[26:29], v[192:195], v[172:175], v[26:29]
	ds_read_b128 v[160:163], v232 offset:4096
	v_mfma_f32_16x16x32_bf16 v[30:33], v[196:199], v[172:175], v[30:33]
	ds_read_b128 v[164:167], v232 offset:6144
	s_add_u32 m0, s8, 0xc000
	v_mfma_f32_16x16x32_bf16 v[34:37], v[184:187], v[176:179], v[34:37]
	global_load_lds_dwordx4 v200, s[4:5]
	s_add_u32 m0, s8, 0xc400
	v_mfma_f32_16x16x32_bf16 v[38:41], v[188:191], v[176:179], v[38:41]
	global_load_lds_dwordx4 v201, s[4:5]
	s_add_u32 m0, s8, 0xc800
	v_mfma_f32_16x16x32_bf16 v[42:45], v[192:195], v[176:179], v[42:45]
	global_load_lds_dwordx4 v202, s[4:5]
	s_add_u32 m0, s8, 0xcc00
	v_mfma_f32_16x16x32_bf16 v[46:49], v[196:199], v[176:179], v[46:49]
	global_load_lds_dwordx4 v203, s[4:5]
	s_add_u32 m0, s9, 0xc000
	v_mfma_f32_16x16x32_bf16 v[50:53], v[184:187], v[180:183], v[50:53]
	global_load_lds_dwordx4 v204, s[6:7]
	s_add_u32 m0, s9, 0xc400
	v_mfma_f32_16x16x32_bf16 v[54:57], v[188:191], v[180:183], v[54:57]
	global_load_lds_dwordx4 v205, s[6:7]
	v_mfma_f32_16x16x32_bf16 v[58:61], v[192:195], v[180:183], v[58:61]
	s_add_u32 s4, s4, 0x80
	s_addc_u32 s5, s5, 0
	v_mfma_f32_16x16x32_bf16 v[62:65], v[196:199], v[180:183], v[62:65]
	s_add_u32 s6, s6, 0x80
	s_addc_u32 s7, s7, 0
	s_waitcnt lgkmcnt(0)
	v_mfma_f32_16x16x32_bf16 v[2:5], v[152:155], v[136:139], v[2:5]
	ds_read_b128 v[168:171], v229 offset:0
	v_mfma_f32_16x16x32_bf16 v[6:9], v[156:159], v[136:139], v[6:9]
	ds_read_b128 v[172:175], v229 offset:2048
	v_mfma_f32_16x16x32_bf16 v[10:13], v[160:163], v[136:139], v[10:13]
	ds_read_b128 v[176:179], v229 offset:4096
	v_mfma_f32_16x16x32_bf16 v[14:17], v[164:167], v[136:139], v[14:17]
	ds_read_b128 v[180:183], v229 offset:6144
	v_mfma_f32_16x16x32_bf16 v[18:21], v[152:155], v[140:143], v[18:21]
	ds_read_b128 v[184:187], v235 offset:0
	v_mfma_f32_16x16x32_bf16 v[22:25], v[156:159], v[140:143], v[22:25]
	ds_read_b128 v[188:191], v235 offset:2048
	v_mfma_f32_16x16x32_bf16 v[26:29], v[160:163], v[140:143], v[26:29]
	ds_read_b128 v[192:195], v235 offset:4096
	v_mfma_f32_16x16x32_bf16 v[30:33], v[164:167], v[140:143], v[30:33]
	ds_read_b128 v[196:199], v235 offset:6144
	v_mfma_f32_16x16x32_bf16 v[34:37], v[152:155], v[144:147], v[34:37]
	v_mfma_f32_16x16x32_bf16 v[38:41], v[156:159], v[144:147], v[38:41]
	v_mfma_f32_16x16x32_bf16 v[42:45], v[160:163], v[144:147], v[42:45]
	v_mfma_f32_16x16x32_bf16 v[46:49], v[164:167], v[144:147], v[46:49]
	v_mfma_f32_16x16x32_bf16 v[50:53], v[152:155], v[148:151], v[50:53]
	v_mfma_f32_16x16x32_bf16 v[54:57], v[156:159], v[148:151], v[54:57]
	v_mfma_f32_16x16x32_bf16 v[58:61], v[160:163], v[148:151], v[58:61]
	v_mfma_f32_16x16x32_bf16 v[62:65], v[164:167], v[148:151], v[62:65]
	s_waitcnt vmcnt(6) lgkmcnt(0)
	s_barrier
	v_mfma_f32_16x16x32_bf16 v[2:5], v[184:187], v[168:171], v[2:5]
	ds_read_b128 v[136:139], v218 offset:0
	v_mfma_f32_16x16x32_bf16 v[6:9], v[188:191], v[168:171], v[6:9]
	ds_read_b128 v[140:143], v218 offset:2048
	v_mfma_f32_16x16x32_bf16 v[10:13], v[192:195], v[168:171], v[10:13]
	ds_read_b128 v[144:147], v218 offset:4096
	v_mfma_f32_16x16x32_bf16 v[14:17], v[196:199], v[168:171], v[14:17]
	ds_read_b128 v[148:151], v218 offset:6144
	v_mfma_f32_16x16x32_bf16 v[18:21], v[184:187], v[172:175], v[18:21]
	ds_read_b128 v[152:155], v230 offset:0
	v_mfma_f32_16x16x32_bf16 v[22:25], v[188:191], v[172:175], v[22:25]
	ds_read_b128 v[156:159], v230 offset:2048
	v_mfma_f32_16x16x32_bf16 v[26:29], v[192:195], v[172:175], v[26:29]
	ds_read_b128 v[160:163], v230 offset:4096
	v_mfma_f32_16x16x32_bf16 v[30:33], v[196:199], v[172:175], v[30:33]
	ds_read_b128 v[164:167], v230 offset:6144
	s_add_u32 m0, s8, 0x18000
	v_mfma_f32_16x16x32_bf16 v[34:37], v[184:187], v[176:179], v[34:37]
	global_load_lds_dwordx4 v200, s[4:5]
	s_add_u32 m0, s8, 0x18400
	v_mfma_f32_16x16x32_bf16 v[38:41], v[188:191], v[176:179], v[38:41]
	global_load_lds_dwordx4 v201, s[4:5]
	s_add_u32 m0, s8, 0x18800
	v_mfma_f32_16x16x32_bf16 v[42:45], v[192:195], v[176:179], v[42:45]
	global_load_lds_dwordx4 v202, s[4:5]
	s_add_u32 m0, s8, 0x18c00
	v_mfma_f32_16x16x32_bf16 v[46:49], v[196:199], v[176:179], v[46:49]
	global_load_lds_dwordx4 v203, s[4:5]
	s_add_u32 m0, s9, 0x18000
	v_mfma_f32_16x16x32_bf16 v[50:53], v[184:187], v[180:183], v[50:53]
	global_load_lds_dwordx4 v204, s[6:7]
	s_add_u32 m0, s9, 0x18400
	v_mfma_f32_16x16x32_bf16 v[54:57], v[188:191], v[180:183], v[54:57]
	global_load_lds_dwordx4 v205, s[6:7]
	v_mfma_f32_16x16x32_bf16 v[58:61], v[192:195], v[180:183], v[58:61]
	s_add_u32 s4, s4, 0x80
	s_addc_u32 s5, s5, 0
	v_mfma_f32_16x16x32_bf16 v[62:65], v[196:199], v[180:183], v[62:65]
	s_add_u32 s6, s6, 0x80
	s_addc_u32 s7, s7, 0
	s_waitcnt lgkmcnt(0)
	v_mfma_f32_16x16x32_bf16 v[2:5], v[152:155], v[136:139], v[2:5]
	ds_read_b128 v[168:171], v225 offset:0
	v_mfma_f32_16x16x32_bf16 v[6:9], v[156:159], v[136:139], v[6:9]
	ds_read_b128 v[172:175], v225 offset:2048
	v_mfma_f32_16x16x32_bf16 v[10:13], v[160:163], v[136:139], v[10:13]
	ds_read_b128 v[176:179], v225 offset:4096
	v_mfma_f32_16x16x32_bf16 v[14:17], v[164:167], v[136:139], v[14:17]
	ds_read_b128 v[180:183], v225 offset:6144
	v_mfma_f32_16x16x32_bf16 v[18:21], v[152:155], v[140:143], v[18:21]
	ds_read_b128 v[184:187], v233 offset:0
	v_mfma_f32_16x16x32_bf16 v[22:25], v[156:159], v[140:143], v[22:25]
	ds_read_b128 v[188:191], v233 offset:2048
	v_mfma_f32_16x16x32_bf16 v[26:29], v[160:163], v[140:143], v[26:29]
	ds_read_b128 v[192:195], v233 offset:4096
	v_mfma_f32_16x16x32_bf16 v[30:33], v[164:167], v[140:143], v[30:33]
	ds_read_b128 v[196:199], v233 offset:6144
	v_mfma_f32_16x16x32_bf16 v[34:37], v[152:155], v[144:147], v[34:37]
	v_mfma_f32_16x16x32_bf16 v[38:41], v[156:159], v[144:147], v[38:41]
	v_mfma_f32_16x16x32_bf16 v[42:45], v[160:163], v[144:147], v[42:45]
	v_mfma_f32_16x16x32_bf16 v[46:49], v[164:167], v[144:147], v[46:49]
	v_mfma_f32_16x16x32_bf16 v[50:53], v[152:155], v[148:151], v[50:53]
	v_mfma_f32_16x16x32_bf16 v[54:57], v[156:159], v[148:151], v[54:57]
	v_mfma_f32_16x16x32_bf16 v[58:61], v[160:163], v[148:151], v[58:61]
	v_mfma_f32_16x16x32_bf16 v[62:65], v[164:167], v[148:151], v[62:65]
	s_waitcnt vmcnt(6) lgkmcnt(0)
	s_barrier
	v_mfma_f32_16x16x32_bf16 v[2:5], v[184:187], v[168:171], v[2:5]
	ds_read_b128 v[136:139], v219 offset:0
	v_mfma_f32_16x16x32_bf16 v[6:9], v[188:191], v[168:171], v[6:9]
	ds_read_b128 v[140:143], v219 offset:2048
	v_mfma_f32_16x16x32_bf16 v[10:13], v[192:195], v[168:171], v[10:13]
	ds_read_b128 v[144:147], v219 offset:4096
	v_mfma_f32_16x16x32_bf16 v[14:17], v[196:199], v[168:171], v[14:17]
	ds_read_b128 v[148:151], v219 offset:6144
	v_mfma_f32_16x16x32_bf16 v[18:21], v[184:187], v[172:175], v[18:21]
	ds_read_b128 v[152:155], v231 offset:0
	v_mfma_f32_16x16x32_bf16 v[22:25], v[188:191], v[172:175], v[22:25]
	ds_read_b128 v[156:159], v231 offset:2048
	v_mfma_f32_16x16x32_bf16 v[26:29], v[192:195], v[172:175], v[26:29]
	ds_read_b128 v[160:163], v231 offset:4096
	v_mfma_f32_16x16x32_bf16 v[30:33], v[196:199], v[172:175], v[30:33]
	ds_read_b128 v[164:167], v231 offset:6144
	s_mov_b32 m0, s8
	v_mfma_f32_16x16x32_bf16 v[34:37], v[184:187], v[176:179], v[34:37]
	global_load_lds_dwordx4 v200, s[4:5]
	s_add_u32 m0, s8, 0x400
	v_mfma_f32_16x16x32_bf16 v[38:41], v[188:191], v[176:179], v[38:41]
	global_load_lds_dwordx4 v201, s[4:5]
	s_add_u32 m0, s8, 0x800
	v_mfma_f32_16x16x32_bf16 v[42:45], v[192:195], v[176:179], v[42:45]
	global_load_lds_dwordx4 v202, s[4:5]
	s_add_u32 m0, s8, 0xc00
	v_mfma_f32_16x16x32_bf16 v[46:49], v[196:199], v[176:179], v[46:49]
	global_load_lds_dwordx4 v203, s[4:5]
	s_mov_b32 m0, s9
	v_mfma_f32_16x16x32_bf16 v[50:53], v[184:187], v[180:183], v[50:53]
	global_load_lds_dwordx4 v204, s[6:7]
	s_add_u32 m0, s9, 0x400
	v_mfma_f32_16x16x32_bf16 v[54:57], v[188:191], v[180:183], v[54:57]
	global_load_lds_dwordx4 v205, s[6:7]
	v_mfma_f32_16x16x32_bf16 v[58:61], v[192:195], v[180:183], v[58:61]
	s_add_u32 s4, s4, 0x80
	s_addc_u32 s5, s5, 0
	v_mfma_f32_16x16x32_bf16 v[62:65], v[196:199], v[180:183], v[62:65]
	s_add_u32 s6, s6, 0x80
	s_addc_u32 s7, s7, 0
	s_waitcnt lgkmcnt(0)
	v_mfma_f32_16x16x32_bf16 v[2:5], v[152:155], v[136:139], v[2:5]
	ds_read_b128 v[168:171], v228 offset:0
	v_mfma_f32_16x16x32_bf16 v[6:9], v[156:159], v[136:139], v[6:9]
	ds_read_b128 v[172:175], v228 offset:2048
	v_mfma_f32_16x16x32_bf16 v[10:13], v[160:163], v[136:139], v[10:13]
	ds_read_b128 v[176:179], v228 offset:4096
	v_mfma_f32_16x16x32_bf16 v[14:17], v[164:167], v[136:139], v[14:17]
	ds_read_b128 v[180:183], v228 offset:6144
	v_mfma_f32_16x16x32_bf16 v[18:21], v[152:155], v[140:143], v[18:21]
	ds_read_b128 v[184:187], v234 offset:0
	v_mfma_f32_16x16x32_bf16 v[22:25], v[156:159], v[140:143], v[22:25]
	ds_read_b128 v[188:191], v234 offset:2048
	v_mfma_f32_16x16x32_bf16 v[26:29], v[160:163], v[140:143], v[26:29]
	ds_read_b128 v[192:195], v234 offset:4096
	v_mfma_f32_16x16x32_bf16 v[30:33], v[164:167], v[140:143], v[30:33]
	ds_read_b128 v[196:199], v234 offset:6144
	v_mfma_f32_16x16x32_bf16 v[34:37], v[152:155], v[144:147], v[34:37]
	v_mfma_f32_16x16x32_bf16 v[38:41], v[156:159], v[144:147], v[38:41]
	v_mfma_f32_16x16x32_bf16 v[42:45], v[160:163], v[144:147], v[42:45]
	v_mfma_f32_16x16x32_bf16 v[46:49], v[164:167], v[144:147], v[46:49]
	v_mfma_f32_16x16x32_bf16 v[50:53], v[152:155], v[148:151], v[50:53]
	v_mfma_f32_16x16x32_bf16 v[54:57], v[156:159], v[148:151], v[54:57]
	v_mfma_f32_16x16x32_bf16 v[58:61], v[160:163], v[148:151], v[58:61]
	v_mfma_f32_16x16x32_bf16 v[62:65], v[164:167], v[148:151], v[62:65]
	s_waitcnt vmcnt(6) lgkmcnt(0)
	s_barrier
	v_mfma_f32_16x16x32_bf16 v[2:5], v[184:187], v[168:171], v[2:5]
	ds_read_b128 v[136:139], v224 offset:0
	v_mfma_f32_16x16x32_bf16 v[6:9], v[188:191], v[168:171], v[6:9]
	ds_read_b128 v[140:143], v224 offset:2048
	v_mfma_f32_16x16x32_bf16 v[10:13], v[192:195], v[168:171], v[10:13]
	ds_read_b128 v[144:147], v224 offset:4096
	v_mfma_f32_16x16x32_bf16 v[14:17], v[196:199], v[168:171], v[14:17]
	ds_read_b128 v[148:151], v224 offset:6144
	v_mfma_f32_16x16x32_bf16 v[18:21], v[184:187], v[172:175], v[18:21]
	ds_read_b128 v[152:155], v232 offset:0
	v_mfma_f32_16x16x32_bf16 v[22:25], v[188:191], v[172:175], v[22:25]
	ds_read_b128 v[156:159], v232 offset:2048
	v_mfma_f32_16x16x32_bf16 v[26:29], v[192:195], v[172:175], v[26:29]
	ds_read_b128 v[160:163], v232 offset:4096
	v_mfma_f32_16x16x32_bf16 v[30:33], v[196:199], v[172:175], v[30:33]
	ds_read_b128 v[164:167], v232 offset:6144
	s_add_u32 m0, s8, 0xc000
	v_mfma_f32_16x16x32_bf16 v[34:37], v[184:187], v[176:179], v[34:37]
	global_load_lds_dwordx4 v200, s[4:5]
	s_add_u32 m0, s8, 0xc400
	v_mfma_f32_16x16x32_bf16 v[38:41], v[188:191], v[176:179], v[38:41]
	global_load_lds_dwordx4 v201, s[4:5]
	s_add_u32 m0, s8, 0xc800
	v_mfma_f32_16x16x32_bf16 v[42:45], v[192:195], v[176:179], v[42:45]
	global_load_lds_dwordx4 v202, s[4:5]
	s_add_u32 m0, s8, 0xcc00
	v_mfma_f32_16x16x32_bf16 v[46:49], v[196:199], v[176:179], v[46:49]
	global_load_lds_dwordx4 v203, s[4:5]
	s_add_u32 m0, s9, 0xc000
	v_mfma_f32_16x16x32_bf16 v[50:53], v[184:187], v[180:183], v[50:53]
	global_load_lds_dwordx4 v204, s[6:7]
	s_add_u32 m0, s9, 0xc400
	v_mfma_f32_16x16x32_bf16 v[54:57], v[188:191], v[180:183], v[54:57]
	global_load_lds_dwordx4 v205, s[6:7]
	v_mfma_f32_16x16x32_bf16 v[58:61], v[192:195], v[180:183], v[58:61]
	s_add_u32 s4, s4, 0x80
	s_addc_u32 s5, s5, 0
	v_mfma_f32_16x16x32_bf16 v[62:65], v[196:199], v[180:183], v[62:65]
	s_add_u32 s6, s6, 0x80
	s_addc_u32 s7, s7, 0
	s_waitcnt lgkmcnt(0)
	v_mfma_f32_16x16x32_bf16 v[2:5], v[152:155], v[136:139], v[2:5]
	ds_read_b128 v[168:171], v229 offset:0
	v_mfma_f32_16x16x32_bf16 v[6:9], v[156:159], v[136:139], v[6:9]
	ds_read_b128 v[172:175], v229 offset:2048
	v_mfma_f32_16x16x32_bf16 v[10:13], v[160:163], v[136:139], v[10:13]
	ds_read_b128 v[176:179], v229 offset:4096
	v_mfma_f32_16x16x32_bf16 v[14:17], v[164:167], v[136:139], v[14:17]
	ds_read_b128 v[180:183], v229 offset:6144
	v_mfma_f32_16x16x32_bf16 v[18:21], v[152:155], v[140:143], v[18:21]
	ds_read_b128 v[184:187], v235 offset:0
	v_mfma_f32_16x16x32_bf16 v[22:25], v[156:159], v[140:143], v[22:25]
	ds_read_b128 v[188:191], v235 offset:2048
	v_mfma_f32_16x16x32_bf16 v[26:29], v[160:163], v[140:143], v[26:29]
	ds_read_b128 v[192:195], v235 offset:4096
	v_mfma_f32_16x16x32_bf16 v[30:33], v[164:167], v[140:143], v[30:33]
	ds_read_b128 v[196:199], v235 offset:6144
	v_mfma_f32_16x16x32_bf16 v[34:37], v[152:155], v[144:147], v[34:37]
	v_mfma_f32_16x16x32_bf16 v[38:41], v[156:159], v[144:147], v[38:41]
	v_mfma_f32_16x16x32_bf16 v[42:45], v[160:163], v[144:147], v[42:45]
	v_mfma_f32_16x16x32_bf16 v[46:49], v[164:167], v[144:147], v[46:49]
	v_mfma_f32_16x16x32_bf16 v[50:53], v[152:155], v[148:151], v[50:53]
	v_mfma_f32_16x16x32_bf16 v[54:57], v[156:159], v[148:151], v[54:57]
	v_mfma_f32_16x16x32_bf16 v[58:61], v[160:163], v[148:151], v[58:61]
	v_mfma_f32_16x16x32_bf16 v[62:65], v[164:167], v[148:151], v[62:65]
	s_waitcnt vmcnt(6) lgkmcnt(0)
	s_barrier
	v_mfma_f32_16x16x32_bf16 v[2:5], v[184:187], v[168:171], v[2:5]
	ds_read_b128 v[136:139], v218 offset:0
	v_mfma_f32_16x16x32_bf16 v[6:9], v[188:191], v[168:171], v[6:9]
	ds_read_b128 v[140:143], v218 offset:2048
	v_mfma_f32_16x16x32_bf16 v[10:13], v[192:195], v[168:171], v[10:13]
	ds_read_b128 v[144:147], v218 offset:4096
	v_mfma_f32_16x16x32_bf16 v[14:17], v[196:199], v[168:171], v[14:17]
	ds_read_b128 v[148:151], v218 offset:6144
	v_mfma_f32_16x16x32_bf16 v[18:21], v[184:187], v[172:175], v[18:21]
	ds_read_b128 v[152:155], v230 offset:0
	v_mfma_f32_16x16x32_bf16 v[22:25], v[188:191], v[172:175], v[22:25]
	ds_read_b128 v[156:159], v230 offset:2048
	v_mfma_f32_16x16x32_bf16 v[26:29], v[192:195], v[172:175], v[26:29]
	ds_read_b128 v[160:163], v230 offset:4096
	v_mfma_f32_16x16x32_bf16 v[30:33], v[196:199], v[172:175], v[30:33]
	ds_read_b128 v[164:167], v230 offset:6144
	s_add_u32 m0, s8, 0x18000
	v_mfma_f32_16x16x32_bf16 v[34:37], v[184:187], v[176:179], v[34:37]
	global_load_lds_dwordx4 v200, s[4:5]
	s_add_u32 m0, s8, 0x18400
	v_mfma_f32_16x16x32_bf16 v[38:41], v[188:191], v[176:179], v[38:41]
	global_load_lds_dwordx4 v201, s[4:5]
	s_add_u32 m0, s8, 0x18800
	v_mfma_f32_16x16x32_bf16 v[42:45], v[192:195], v[176:179], v[42:45]
	global_load_lds_dwordx4 v202, s[4:5]
	s_add_u32 m0, s8, 0x18c00
	v_mfma_f32_16x16x32_bf16 v[46:49], v[196:199], v[176:179], v[46:49]
	global_load_lds_dwordx4 v203, s[4:5]
	s_add_u32 m0, s9, 0x18000
	v_mfma_f32_16x16x32_bf16 v[50:53], v[184:187], v[180:183], v[50:53]
	global_load_lds_dwordx4 v204, s[6:7]
	s_add_u32 m0, s9, 0x18400
	v_mfma_f32_16x16x32_bf16 v[54:57], v[188:191], v[180:183], v[54:57]
	global_load_lds_dwordx4 v205, s[6:7]
	v_mfma_f32_16x16x32_bf16 v[58:61], v[192:195], v[180:183], v[58:61]
	s_add_u32 s4, s4, 0x80
	s_addc_u32 s5, s5, 0
	v_mfma_f32_16x16x32_bf16 v[62:65], v[196:199], v[180:183], v[62:65]
	s_add_u32 s6, s6, 0x80
	s_addc_u32 s7, s7, 0
	s_waitcnt lgkmcnt(0)
	v_mfma_f32_16x16x32_bf16 v[2:5], v[152:155], v[136:139], v[2:5]
	ds_read_b128 v[168:171], v225 offset:0
	v_mfma_f32_16x16x32_bf16 v[6:9], v[156:159], v[136:139], v[6:9]
	ds_read_b128 v[172:175], v225 offset:2048
	v_mfma_f32_16x16x32_bf16 v[10:13], v[160:163], v[136:139], v[10:13]
	ds_read_b128 v[176:179], v225 offset:4096
	v_mfma_f32_16x16x32_bf16 v[14:17], v[164:167], v[136:139], v[14:17]
	ds_read_b128 v[180:183], v225 offset:6144
	v_mfma_f32_16x16x32_bf16 v[18:21], v[152:155], v[140:143], v[18:21]
	ds_read_b128 v[184:187], v233 offset:0
	v_mfma_f32_16x16x32_bf16 v[22:25], v[156:159], v[140:143], v[22:25]
	ds_read_b128 v[188:191], v233 offset:2048
	v_mfma_f32_16x16x32_bf16 v[26:29], v[160:163], v[140:143], v[26:29]
	ds_read_b128 v[192:195], v233 offset:4096
	v_mfma_f32_16x16x32_bf16 v[30:33], v[164:167], v[140:143], v[30:33]
	ds_read_b128 v[196:199], v233 offset:6144
	v_mfma_f32_16x16x32_bf16 v[34:37], v[152:155], v[144:147], v[34:37]
	v_mfma_f32_16x16x32_bf16 v[38:41], v[156:159], v[144:147], v[38:41]
	v_mfma_f32_16x16x32_bf16 v[42:45], v[160:163], v[144:147], v[42:45]
	v_mfma_f32_16x16x32_bf16 v[46:49], v[164:167], v[144:147], v[46:49]
	v_mfma_f32_16x16x32_bf16 v[50:53], v[152:155], v[148:151], v[50:53]
	v_mfma_f32_16x16x32_bf16 v[54:57], v[156:159], v[148:151], v[54:57]
	v_mfma_f32_16x16x32_bf16 v[58:61], v[160:163], v[148:151], v[58:61]
	v_mfma_f32_16x16x32_bf16 v[62:65], v[164:167], v[148:151], v[62:65]
	s_waitcnt vmcnt(6) lgkmcnt(0)
	s_barrier
	v_mfma_f32_16x16x32_bf16 v[2:5], v[184:187], v[168:171], v[2:5]
	ds_read_b128 v[136:139], v219 offset:0
	v_mfma_f32_16x16x32_bf16 v[6:9], v[188:191], v[168:171], v[6:9]
	ds_read_b128 v[140:143], v219 offset:2048
	v_mfma_f32_16x16x32_bf16 v[10:13], v[192:195], v[168:171], v[10:13]
	ds_read_b128 v[144:147], v219 offset:4096
	v_mfma_f32_16x16x32_bf16 v[14:17], v[196:199], v[168:171], v[14:17]
	ds_read_b128 v[148:151], v219 offset:6144
	v_mfma_f32_16x16x32_bf16 v[18:21], v[184:187], v[172:175], v[18:21]
	ds_read_b128 v[152:155], v231 offset:0
	v_mfma_f32_16x16x32_bf16 v[22:25], v[188:191], v[172:175], v[22:25]
	ds_read_b128 v[156:159], v231 offset:2048
	v_mfma_f32_16x16x32_bf16 v[26:29], v[192:195], v[172:175], v[26:29]
	ds_read_b128 v[160:163], v231 offset:4096
	v_mfma_f32_16x16x32_bf16 v[30:33], v[196:199], v[172:175], v[30:33]
	ds_read_b128 v[164:167], v231 offset:6144
	s_mov_b32 m0, s8
	v_mfma_f32_16x16x32_bf16 v[34:37], v[184:187], v[176:179], v[34:37]
	global_load_lds_dwordx4 v200, s[4:5]
	s_add_u32 m0, s8, 0x400
	v_mfma_f32_16x16x32_bf16 v[38:41], v[188:191], v[176:179], v[38:41]
	global_load_lds_dwordx4 v201, s[4:5]
	s_add_u32 m0, s8, 0x800
	v_mfma_f32_16x16x32_bf16 v[42:45], v[192:195], v[176:179], v[42:45]
	global_load_lds_dwordx4 v202, s[4:5]
	s_add_u32 m0, s8, 0xc00
	v_mfma_f32_16x16x32_bf16 v[46:49], v[196:199], v[176:179], v[46:49]
	global_load_lds_dwordx4 v203, s[4:5]
	s_mov_b32 m0, s9
	v_mfma_f32_16x16x32_bf16 v[50:53], v[184:187], v[180:183], v[50:53]
	global_load_lds_dwordx4 v204, s[6:7]
	s_add_u32 m0, s9, 0x400
	v_mfma_f32_16x16x32_bf16 v[54:57], v[188:191], v[180:183], v[54:57]
	global_load_lds_dwordx4 v205, s[6:7]
	v_mfma_f32_16x16x32_bf16 v[58:61], v[192:195], v[180:183], v[58:61]
	s_sub_u32 s4, s4, 0x780
	s_subb_u32 s5, s5, 0
	v_mfma_f32_16x16x32_bf16 v[62:65], v[196:199], v[180:183], v[62:65]
	s_add_u32 s6, s6, 0x3f880
	s_addc_u32 s7, s7, 0
	s_waitcnt lgkmcnt(0)
	v_mfma_f32_16x16x32_bf16 v[2:5], v[152:155], v[136:139], v[2:5]
	ds_read_b128 v[168:171], v228 offset:0
	v_mfma_f32_16x16x32_bf16 v[6:9], v[156:159], v[136:139], v[6:9]
	ds_read_b128 v[172:175], v228 offset:2048
	v_mfma_f32_16x16x32_bf16 v[10:13], v[160:163], v[136:139], v[10:13]
	ds_read_b128 v[176:179], v228 offset:4096
	v_mfma_f32_16x16x32_bf16 v[14:17], v[164:167], v[136:139], v[14:17]
	ds_read_b128 v[180:183], v228 offset:6144
	v_mfma_f32_16x16x32_bf16 v[18:21], v[152:155], v[140:143], v[18:21]
	ds_read_b128 v[184:187], v234 offset:0
	v_mfma_f32_16x16x32_bf16 v[22:25], v[156:159], v[140:143], v[22:25]
	ds_read_b128 v[188:191], v234 offset:2048
	v_mfma_f32_16x16x32_bf16 v[26:29], v[160:163], v[140:143], v[26:29]
	ds_read_b128 v[192:195], v234 offset:4096
	v_mfma_f32_16x16x32_bf16 v[30:33], v[164:167], v[140:143], v[30:33]
	ds_read_b128 v[196:199], v234 offset:6144
	v_mfma_f32_16x16x32_bf16 v[34:37], v[152:155], v[144:147], v[34:37]
	v_mfma_f32_16x16x32_bf16 v[38:41], v[156:159], v[144:147], v[38:41]
	v_mfma_f32_16x16x32_bf16 v[42:45], v[160:163], v[144:147], v[42:45]
	v_mfma_f32_16x16x32_bf16 v[46:49], v[164:167], v[144:147], v[46:49]
	v_mfma_f32_16x16x32_bf16 v[50:53], v[152:155], v[148:151], v[50:53]
	v_mfma_f32_16x16x32_bf16 v[54:57], v[156:159], v[148:151], v[54:57]
	v_mfma_f32_16x16x32_bf16 v[58:61], v[160:163], v[148:151], v[58:61]
	v_mfma_f32_16x16x32_bf16 v[62:65], v[164:167], v[148:151], v[62:65]
	s_waitcnt vmcnt(6) lgkmcnt(0)
	s_barrier
	v_mfma_f32_16x16x32_bf16 v[2:5], v[184:187], v[168:171], v[2:5]
	ds_read_b128 v[136:139], v224 offset:0
	v_mfma_f32_16x16x32_bf16 v[6:9], v[188:191], v[168:171], v[6:9]
	ds_read_b128 v[140:143], v224 offset:2048
	v_mfma_f32_16x16x32_bf16 v[10:13], v[192:195], v[168:171], v[10:13]
	ds_read_b128 v[144:147], v224 offset:4096
	v_mfma_f32_16x16x32_bf16 v[14:17], v[196:199], v[168:171], v[14:17]
	ds_read_b128 v[148:151], v224 offset:6144
	v_mfma_f32_16x16x32_bf16 v[18:21], v[184:187], v[172:175], v[18:21]
	ds_read_b128 v[152:155], v232 offset:0
	v_mfma_f32_16x16x32_bf16 v[22:25], v[188:191], v[172:175], v[22:25]
	ds_read_b128 v[156:159], v232 offset:2048
	v_mfma_f32_16x16x32_bf16 v[26:29], v[192:195], v[172:175], v[26:29]
	ds_read_b128 v[160:163], v232 offset:4096
	v_mfma_f32_16x16x32_bf16 v[30:33], v[196:199], v[172:175], v[30:33]
	ds_read_b128 v[164:167], v232 offset:6144
	s_add_u32 m0, s8, 0xc000
	v_mfma_f32_16x16x32_bf16 v[34:37], v[184:187], v[176:179], v[34:37]
	global_load_lds_dwordx4 v200, s[4:5]
	s_add_u32 m0, s8, 0xc400
	v_mfma_f32_16x16x32_bf16 v[38:41], v[188:191], v[176:179], v[38:41]
	global_load_lds_dwordx4 v201, s[4:5]
	s_add_u32 m0, s8, 0xc800
	v_mfma_f32_16x16x32_bf16 v[42:45], v[192:195], v[176:179], v[42:45]
	global_load_lds_dwordx4 v202, s[4:5]
	s_add_u32 m0, s8, 0xcc00
	v_mfma_f32_16x16x32_bf16 v[46:49], v[196:199], v[176:179], v[46:49]
	global_load_lds_dwordx4 v203, s[4:5]
	s_add_u32 m0, s9, 0xc000
	v_mfma_f32_16x16x32_bf16 v[50:53], v[184:187], v[180:183], v[50:53]
	global_load_lds_dwordx4 v204, s[6:7]
	s_add_u32 m0, s9, 0xc400
	v_mfma_f32_16x16x32_bf16 v[54:57], v[188:191], v[180:183], v[54:57]
	global_load_lds_dwordx4 v205, s[6:7]
	v_mfma_f32_16x16x32_bf16 v[58:61], v[192:195], v[180:183], v[58:61]
	s_add_u32 s4, s4, 0x80
	s_addc_u32 s5, s5, 0
	v_mfma_f32_16x16x32_bf16 v[62:65], v[196:199], v[180:183], v[62:65]
	s_add_u32 s6, s6, 0x80
	s_addc_u32 s7, s7, 0
	s_waitcnt lgkmcnt(0)
	v_mfma_f32_16x16x32_bf16 v[2:5], v[152:155], v[136:139], v[2:5]
	ds_read_b128 v[168:171], v229 offset:0
	v_mfma_f32_16x16x32_bf16 v[6:9], v[156:159], v[136:139], v[6:9]
	ds_read_b128 v[172:175], v229 offset:2048
	v_mfma_f32_16x16x32_bf16 v[10:13], v[160:163], v[136:139], v[10:13]
	ds_read_b128 v[176:179], v229 offset:4096
	v_mfma_f32_16x16x32_bf16 v[14:17], v[164:167], v[136:139], v[14:17]
	ds_read_b128 v[180:183], v229 offset:6144
	v_mfma_f32_16x16x32_bf16 v[18:21], v[152:155], v[140:143], v[18:21]
	ds_read_b128 v[184:187], v235 offset:0
	v_mfma_f32_16x16x32_bf16 v[22:25], v[156:159], v[140:143], v[22:25]
	ds_read_b128 v[188:191], v235 offset:2048
	v_mfma_f32_16x16x32_bf16 v[26:29], v[160:163], v[140:143], v[26:29]
	ds_read_b128 v[192:195], v235 offset:4096
	v_mfma_f32_16x16x32_bf16 v[30:33], v[164:167], v[140:143], v[30:33]
	ds_read_b128 v[196:199], v235 offset:6144
	v_mfma_f32_16x16x32_bf16 v[34:37], v[152:155], v[144:147], v[34:37]
	v_mfma_f32_16x16x32_bf16 v[38:41], v[156:159], v[144:147], v[38:41]
	v_mfma_f32_16x16x32_bf16 v[42:45], v[160:163], v[144:147], v[42:45]
	v_mfma_f32_16x16x32_bf16 v[46:49], v[164:167], v[144:147], v[46:49]
	v_mfma_f32_16x16x32_bf16 v[50:53], v[152:155], v[148:151], v[50:53]
	v_mfma_f32_16x16x32_bf16 v[54:57], v[156:159], v[148:151], v[54:57]
	v_mfma_f32_16x16x32_bf16 v[58:61], v[160:163], v[148:151], v[58:61]
	v_mfma_f32_16x16x32_bf16 v[62:65], v[164:167], v[148:151], v[62:65]
	s_waitcnt vmcnt(6) lgkmcnt(0)
	s_barrier
	v_mfma_f32_16x16x32_bf16 v[2:5], v[184:187], v[168:171], v[2:5]
	ds_read_b128 v[136:139], v218 offset:0
	v_mfma_f32_16x16x32_bf16 v[6:9], v[188:191], v[168:171], v[6:9]
	ds_read_b128 v[140:143], v218 offset:2048
	v_mfma_f32_16x16x32_bf16 v[10:13], v[192:195], v[168:171], v[10:13]
	ds_read_b128 v[144:147], v218 offset:4096
	v_mfma_f32_16x16x32_bf16 v[14:17], v[196:199], v[168:171], v[14:17]
	ds_read_b128 v[148:151], v218 offset:6144
	v_mfma_f32_16x16x32_bf16 v[18:21], v[184:187], v[172:175], v[18:21]
	ds_read_b128 v[152:155], v230 offset:0
	v_mfma_f32_16x16x32_bf16 v[22:25], v[188:191], v[172:175], v[22:25]
	ds_read_b128 v[156:159], v230 offset:2048
	v_mfma_f32_16x16x32_bf16 v[26:29], v[192:195], v[172:175], v[26:29]
	ds_read_b128 v[160:163], v230 offset:4096
	v_mfma_f32_16x16x32_bf16 v[30:33], v[196:199], v[172:175], v[30:33]
	ds_read_b128 v[164:167], v230 offset:6144
	s_add_u32 m0, s8, 0x18000
	v_mfma_f32_16x16x32_bf16 v[34:37], v[184:187], v[176:179], v[34:37]
	global_load_lds_dwordx4 v200, s[4:5]
	s_add_u32 m0, s8, 0x18400
	v_mfma_f32_16x16x32_bf16 v[38:41], v[188:191], v[176:179], v[38:41]
	global_load_lds_dwordx4 v201, s[4:5]
	s_add_u32 m0, s8, 0x18800
	v_mfma_f32_16x16x32_bf16 v[42:45], v[192:195], v[176:179], v[42:45]
	global_load_lds_dwordx4 v202, s[4:5]
	s_add_u32 m0, s8, 0x18c00
	v_mfma_f32_16x16x32_bf16 v[46:49], v[196:199], v[176:179], v[46:49]
	global_load_lds_dwordx4 v203, s[4:5]
	s_add_u32 m0, s9, 0x18000
	v_mfma_f32_16x16x32_bf16 v[50:53], v[184:187], v[180:183], v[50:53]
	global_load_lds_dwordx4 v204, s[6:7]
	s_add_u32 m0, s9, 0x18400
	v_mfma_f32_16x16x32_bf16 v[54:57], v[188:191], v[180:183], v[54:57]
	global_load_lds_dwordx4 v205, s[6:7]
	v_mfma_f32_16x16x32_bf16 v[58:61], v[192:195], v[180:183], v[58:61]
	s_add_u32 s4, s4, 0x80
	s_addc_u32 s5, s5, 0
	v_mfma_f32_16x16x32_bf16 v[62:65], v[196:199], v[180:183], v[62:65]
	s_add_u32 s6, s6, 0x80
	s_addc_u32 s7, s7, 0
	s_waitcnt lgkmcnt(0)
	v_mfma_f32_16x16x32_bf16 v[2:5], v[152:155], v[136:139], v[2:5]
	ds_read_b128 v[168:171], v225 offset:0
	v_mfma_f32_16x16x32_bf16 v[6:9], v[156:159], v[136:139], v[6:9]
	ds_read_b128 v[172:175], v225 offset:2048
	v_mfma_f32_16x16x32_bf16 v[10:13], v[160:163], v[136:139], v[10:13]
	ds_read_b128 v[176:179], v225 offset:4096
	v_mfma_f32_16x16x32_bf16 v[14:17], v[164:167], v[136:139], v[14:17]
	ds_read_b128 v[180:183], v225 offset:6144
	v_mfma_f32_16x16x32_bf16 v[18:21], v[152:155], v[140:143], v[18:21]
	ds_read_b128 v[184:187], v233 offset:0
	v_mfma_f32_16x16x32_bf16 v[22:25], v[156:159], v[140:143], v[22:25]
	ds_read_b128 v[188:191], v233 offset:2048
	v_mfma_f32_16x16x32_bf16 v[26:29], v[160:163], v[140:143], v[26:29]
	ds_read_b128 v[192:195], v233 offset:4096
	v_mfma_f32_16x16x32_bf16 v[30:33], v[164:167], v[140:143], v[30:33]
	ds_read_b128 v[196:199], v233 offset:6144
	v_mfma_f32_16x16x32_bf16 v[34:37], v[152:155], v[144:147], v[34:37]
	v_mfma_f32_16x16x32_bf16 v[38:41], v[156:159], v[144:147], v[38:41]
	v_mfma_f32_16x16x32_bf16 v[42:45], v[160:163], v[144:147], v[42:45]
	v_mfma_f32_16x16x32_bf16 v[46:49], v[164:167], v[144:147], v[46:49]
	v_mfma_f32_16x16x32_bf16 v[50:53], v[152:155], v[148:151], v[50:53]
	v_mfma_f32_16x16x32_bf16 v[54:57], v[156:159], v[148:151], v[54:57]
	v_mfma_f32_16x16x32_bf16 v[58:61], v[160:163], v[148:151], v[58:61]
	v_mfma_f32_16x16x32_bf16 v[62:65], v[164:167], v[148:151], v[62:65]
	s_waitcnt vmcnt(6) lgkmcnt(0)
	s_barrier
	v_mfma_f32_16x16x32_bf16 v[2:5], v[184:187], v[168:171], v[2:5]
	ds_read_b128 v[136:139], v219 offset:0
	v_mfma_f32_16x16x32_bf16 v[6:9], v[188:191], v[168:171], v[6:9]
	ds_read_b128 v[140:143], v219 offset:2048
	v_mfma_f32_16x16x32_bf16 v[10:13], v[192:195], v[168:171], v[10:13]
	ds_read_b128 v[144:147], v219 offset:4096
	v_mfma_f32_16x16x32_bf16 v[14:17], v[196:199], v[168:171], v[14:17]
	ds_read_b128 v[148:151], v219 offset:6144
	v_mfma_f32_16x16x32_bf16 v[18:21], v[184:187], v[172:175], v[18:21]
	ds_read_b128 v[152:155], v231 offset:0
	v_mfma_f32_16x16x32_bf16 v[22:25], v[188:191], v[172:175], v[22:25]
	ds_read_b128 v[156:159], v231 offset:2048
	v_mfma_f32_16x16x32_bf16 v[26:29], v[192:195], v[172:175], v[26:29]
	ds_read_b128 v[160:163], v231 offset:4096
	v_mfma_f32_16x16x32_bf16 v[30:33], v[196:199], v[172:175], v[30:33]
	ds_read_b128 v[164:167], v231 offset:6144
	s_mov_b32 m0, s8
	v_mfma_f32_16x16x32_bf16 v[34:37], v[184:187], v[176:179], v[34:37]
	global_load_lds_dwordx4 v200, s[4:5]
	s_add_u32 m0, s8, 0x400
	v_mfma_f32_16x16x32_bf16 v[38:41], v[188:191], v[176:179], v[38:41]
	global_load_lds_dwordx4 v201, s[4:5]
	s_add_u32 m0, s8, 0x800
	v_mfma_f32_16x16x32_bf16 v[42:45], v[192:195], v[176:179], v[42:45]
	global_load_lds_dwordx4 v202, s[4:5]
	s_add_u32 m0, s8, 0xc00
	v_mfma_f32_16x16x32_bf16 v[46:49], v[196:199], v[176:179], v[46:49]
	global_load_lds_dwordx4 v203, s[4:5]
	s_mov_b32 m0, s9
	v_mfma_f32_16x16x32_bf16 v[50:53], v[184:187], v[180:183], v[50:53]
	global_load_lds_dwordx4 v204, s[6:7]
	s_add_u32 m0, s9, 0x400
	v_mfma_f32_16x16x32_bf16 v[54:57], v[188:191], v[180:183], v[54:57]
	global_load_lds_dwordx4 v205, s[6:7]
	v_mfma_f32_16x16x32_bf16 v[58:61], v[192:195], v[180:183], v[58:61]
	s_add_u32 s4, s4, 0x80
	s_addc_u32 s5, s5, 0
	v_mfma_f32_16x16x32_bf16 v[62:65], v[196:199], v[180:183], v[62:65]
	s_add_u32 s6, s6, 0x80
	s_addc_u32 s7, s7, 0
	s_waitcnt lgkmcnt(0)
	v_mfma_f32_16x16x32_bf16 v[66:69], v[152:155], v[136:139], 0
	ds_read_b128 v[168:171], v228 offset:0
	v_mfma_f32_16x16x32_bf16 v[70:73], v[156:159], v[136:139], 0
	ds_read_b128 v[172:175], v228 offset:2048
	s_add_u32 s10, s52, 0x0
	s_addc_u32 s11, s53, 0
	v_mfma_f32_16x16x32_bf16 v[74:77], v[160:163], v[136:139], 0
	ds_read_b128 v[176:179], v228 offset:4096
	v_mul_f32_e32 v1, s12, v2
	v_mfma_f32_16x16x32_bf16 v[78:81], v[164:167], v[136:139], 0
	ds_read_b128 v[180:183], v228 offset:6144
	v_mul_f32_e32 v130, s12, v3
	v_mfma_f32_16x16x32_bf16 v[82:85], v[152:155], v[140:143], 0
	ds_read_b128 v[184:187], v234 offset:0
	v_mul_f32_e32 v238, s12, v4
	v_mfma_f32_16x16x32_bf16 v[86:89], v[156:159], v[140:143], 0
	ds_read_b128 v[188:191], v234 offset:2048
	v_mul_f32_e32 v239, s12, v5
	v_mfma_f32_16x16x32_bf16 v[90:93], v[160:163], v[140:143], 0
	ds_read_b128 v[192:195], v234 offset:4096
	v_exp_f32_e32 v1, v1
	v_mfma_f32_16x16x32_bf16 v[94:97], v[164:167], v[140:143], 0
	ds_read_b128 v[196:199], v234 offset:6144
	v_exp_f32_e32 v130, v130
	v_mfma_f32_16x16x32_bf16 v[98:101], v[152:155], v[144:147], 0
	v_mfma_f32_16x16x32_bf16 v[102:105], v[156:159], v[144:147], 0
	v_exp_f32_e32 v238, v238
	v_mfma_f32_16x16x32_bf16 v[106:109], v[160:163], v[144:147], 0
	v_exp_f32_e32 v239, v239
	v_mfma_f32_16x16x32_bf16 v[110:113], v[164:167], v[144:147], 0
	v_add_f32_e32 v1, 1.0, v1
	v_mfma_f32_16x16x32_bf16 v[114:117], v[152:155], v[148:151], 0
	v_add_f32_e32 v130, 1.0, v130
	v_mfma_f32_16x16x32_bf16 v[118:121], v[156:159], v[148:151], 0
	v_add_f32_e32 v238, 1.0, v238
	v_mfma_f32_16x16x32_bf16 v[122:125], v[160:163], v[148:151], 0
	v_add_f32_e32 v239, 1.0, v239
	v_mfma_f32_16x16x32_bf16 v[126:129], v[164:167], v[148:151], 0
	v_rcp_f32_e32 v1, v1
	s_waitcnt vmcnt(6) lgkmcnt(0)
	s_barrier
	v_mfma_f32_16x16x32_bf16 v[66:69], v[184:187], v[168:171], v[66:69]
	ds_read_b128 v[136:139], v224 offset:0
	v_mfma_f32_16x16x32_bf16 v[70:73], v[188:191], v[168:171], v[70:73]
	ds_read_b128 v[140:143], v224 offset:2048
	v_rcp_f32_e32 v130, v130
	v_mfma_f32_16x16x32_bf16 v[74:77], v[192:195], v[168:171], v[74:77]
	ds_read_b128 v[144:147], v224 offset:4096
	v_mfma_f32_16x16x32_bf16 v[78:81], v[196:199], v[168:171], v[78:81]
	ds_read_b128 v[148:151], v224 offset:6144
	v_rcp_f32_e32 v238, v238
	v_mfma_f32_16x16x32_bf16 v[82:85], v[184:187], v[172:175], v[82:85]
	ds_read_b128 v[152:155], v232 offset:0
	v_rcp_f32_e32 v239, v239
	v_mfma_f32_16x16x32_bf16 v[86:89], v[188:191], v[172:175], v[86:89]
	ds_read_b128 v[156:159], v232 offset:2048
	v_mfma_f32_16x16x32_bf16 v[90:93], v[192:195], v[172:175], v[90:93]
	ds_read_b128 v[160:163], v232 offset:4096
	v_mul_f32_e32 v2, v2, v1
	v_mfma_f32_16x16x32_bf16 v[94:97], v[196:199], v[172:175], v[94:97]
	ds_read_b128 v[164:167], v232 offset:6144
	v_mul_f32_e32 v3, v3, v130
	s_add_u32 m0, s8, 0xc000
	v_mfma_f32_16x16x32_bf16 v[98:101], v[184:187], v[176:179], v[98:101]
	global_load_lds_dwordx4 v200, s[4:5]
	s_add_u32 m0, s8, 0xc400
	v_mfma_f32_16x16x32_bf16 v[102:105], v[188:191], v[176:179], v[102:105]
	global_load_lds_dwordx4 v201, s[4:5]
	v_mul_f32_e32 v4, v4, v238
	s_add_u32 m0, s8, 0xc800
	v_mfma_f32_16x16x32_bf16 v[106:109], v[192:195], v[176:179], v[106:109]
	global_load_lds_dwordx4 v202, s[4:5]
	s_add_u32 m0, s8, 0xcc00
	v_mfma_f32_16x16x32_bf16 v[110:113], v[196:199], v[176:179], v[110:113]
	global_load_lds_dwordx4 v203, s[4:5]
	v_mul_f32_e32 v5, v5, v239
	s_add_u32 m0, s9, 0xc000
	v_mfma_f32_16x16x32_bf16 v[114:117], v[184:187], v[180:183], v[114:117]
	global_load_lds_dwordx4 v204, s[6:7]
	v_cvt_pk_bf16_f32 v2, v2, v3
	s_add_u32 m0, s9, 0xc400
	v_mfma_f32_16x16x32_bf16 v[118:121], v[188:191], v[180:183], v[118:121]
	global_load_lds_dwordx4 v205, s[6:7]
	v_mfma_f32_16x16x32_bf16 v[122:125], v[192:195], v[180:183], v[122:125]
	s_add_u32 s4, s4, 0x80
	s_addc_u32 s5, s5, 0
	v_cvt_pk_bf16_f32 v3, v4, v5
	v_mfma_f32_16x16x32_bf16 v[126:129], v[196:199], v[180:183], v[126:129]
	s_add_u32 s6, s6, 0x80
	s_addc_u32 s7, s7, 0
	global_store_dwordx2 v236, v[2:3], s[10:11] offset:0
	s_waitcnt lgkmcnt(0)
	v_mfma_f32_16x16x32_bf16 v[66:69], v[152:155], v[136:139], v[66:69]
	ds_read_b128 v[168:171], v229 offset:0
	v_mfma_f32_16x16x32_bf16 v[70:73], v[156:159], v[136:139], v[70:73]
	ds_read_b128 v[172:175], v229 offset:2048
	v_mul_f32_e32 v1, s12, v6
	v_mfma_f32_16x16x32_bf16 v[74:77], v[160:163], v[136:139], v[74:77]
	ds_read_b128 v[176:179], v229 offset:4096
	v_mul_f32_e32 v130, s12, v7
	v_mfma_f32_16x16x32_bf16 v[78:81], v[164:167], v[136:139], v[78:81]
	ds_read_b128 v[180:183], v229 offset:6144
	v_mul_f32_e32 v238, s12, v8
	v_mfma_f32_16x16x32_bf16 v[82:85], v[152:155], v[140:143], v[82:85]
	ds_read_b128 v[184:187], v235 offset:0
	v_mul_f32_e32 v239, s12, v9
	v_mfma_f32_16x16x32_bf16 v[86:89], v[156:159], v[140:143], v[86:89]
	ds_read_b128 v[188:191], v235 offset:2048
	v_exp_f32_e32 v1, v1
	v_mfma_f32_16x16x32_bf16 v[90:93], v[160:163], v[140:143], v[90:93]
	ds_read_b128 v[192:195], v235 offset:4096
	v_exp_f32_e32 v130, v130
	v_mfma_f32_16x16x32_bf16 v[94:97], v[164:167], v[140:143], v[94:97]
	ds_read_b128 v[196:199], v235 offset:6144
	v_exp_f32_e32 v238, v238
	v_mfma_f32_16x16x32_bf16 v[98:101], v[152:155], v[144:147], v[98:101]
	v_mfma_f32_16x16x32_bf16 v[102:105], v[156:159], v[144:147], v[102:105]
	v_exp_f32_e32 v239, v239
	v_mfma_f32_16x16x32_bf16 v[106:109], v[160:163], v[144:147], v[106:109]
	v_add_f32_e32 v1, 1.0, v1
	v_mfma_f32_16x16x32_bf16 v[110:113], v[164:167], v[144:147], v[110:113]
	v_add_f32_e32 v130, 1.0, v130
	v_mfma_f32_16x16x32_bf16 v[114:117], v[152:155], v[148:151], v[114:117]
	v_add_f32_e32 v238, 1.0, v238
	v_mfma_f32_16x16x32_bf16 v[118:121], v[156:159], v[148:151], v[118:121]
	v_add_f32_e32 v239, 1.0, v239
	v_mfma_f32_16x16x32_bf16 v[122:125], v[160:163], v[148:151], v[122:125]
	v_rcp_f32_e32 v1, v1
	v_mfma_f32_16x16x32_bf16 v[126:129], v[164:167], v[148:151], v[126:129]
	v_rcp_f32_e32 v130, v130
	s_waitcnt vmcnt(7) lgkmcnt(0)
	s_barrier
	v_mfma_f32_16x16x32_bf16 v[66:69], v[184:187], v[168:171], v[66:69]
	ds_read_b128 v[136:139], v218 offset:0
	v_mfma_f32_16x16x32_bf16 v[70:73], v[188:191], v[168:171], v[70:73]
	ds_read_b128 v[140:143], v218 offset:2048
	v_rcp_f32_e32 v238, v238
	v_mfma_f32_16x16x32_bf16 v[74:77], v[192:195], v[168:171], v[74:77]
	ds_read_b128 v[144:147], v218 offset:4096
	v_mfma_f32_16x16x32_bf16 v[78:81], v[196:199], v[168:171], v[78:81]
	ds_read_b128 v[148:151], v218 offset:6144
	v_rcp_f32_e32 v239, v239
	v_mfma_f32_16x16x32_bf16 v[82:85], v[184:187], v[172:175], v[82:85]
	ds_read_b128 v[152:155], v230 offset:0
	v_mul_f32_e32 v6, v6, v1
	v_mfma_f32_16x16x32_bf16 v[86:89], v[188:191], v[172:175], v[86:89]
	ds_read_b128 v[156:159], v230 offset:2048
	v_mfma_f32_16x16x32_bf16 v[90:93], v[192:195], v[172:175], v[90:93]
	ds_read_b128 v[160:163], v230 offset:4096
	v_mul_f32_e32 v7, v7, v130
	v_mfma_f32_16x16x32_bf16 v[94:97], v[196:199], v[172:175], v[94:97]
	ds_read_b128 v[164:167], v230 offset:6144
	v_mul_f32_e32 v8, v8, v238
	s_add_u32 m0, s8, 0x18000
	v_mfma_f32_16x16x32_bf16 v[98:101], v[184:187], v[176:179], v[98:101]
	global_load_lds_dwordx4 v200, s[4:5]
	s_add_u32 m0, s8, 0x18400
	v_mfma_f32_16x16x32_bf16 v[102:105], v[188:191], v[176:179], v[102:105]
	global_load_lds_dwordx4 v201, s[4:5]
	v_mul_f32_e32 v9, v9, v239
	s_add_u32 m0, s8, 0x18800
	v_mfma_f32_16x16x32_bf16 v[106:109], v[192:195], v[176:179], v[106:109]
	global_load_lds_dwordx4 v202, s[4:5]
	s_add_u32 m0, s8, 0x18c00
	v_mfma_f32_16x16x32_bf16 v[110:113], v[196:199], v[176:179], v[110:113]
	global_load_lds_dwordx4 v203, s[4:5]
	v_cvt_pk_bf16_f32 v6, v6, v7
	s_add_u32 m0, s9, 0x18000
	v_mfma_f32_16x16x32_bf16 v[114:117], v[184:187], v[180:183], v[114:117]
	global_load_lds_dwordx4 v204, s[6:7]
	v_cvt_pk_bf16_f32 v7, v8, v9
	s_add_u32 m0, s9, 0x18400
	v_mfma_f32_16x16x32_bf16 v[118:121], v[188:191], v[180:183], v[118:121]
	global_load_lds_dwordx4 v205, s[6:7]
	v_mfma_f32_16x16x32_bf16 v[122:125], v[192:195], v[180:183], v[122:125]
	s_add_u32 s4, s4, 0x80
	s_addc_u32 s5, s5, 0
	global_store_dwordx2 v236, v[6:7], s[10:11] offset:32
	v_mfma_f32_16x16x32_bf16 v[126:129], v[196:199], v[180:183], v[126:129]
	s_add_u32 s6, s6, 0x80
	s_addc_u32 s7, s7, 0
	v_mul_f32_e32 v1, s12, v10
	s_waitcnt lgkmcnt(0)
	v_mfma_f32_16x16x32_bf16 v[66:69], v[152:155], v[136:139], v[66:69]
	ds_read_b128 v[168:171], v225 offset:0
	v_mfma_f32_16x16x32_bf16 v[70:73], v[156:159], v[136:139], v[70:73]
	ds_read_b128 v[172:175], v225 offset:2048
	v_mul_f32_e32 v130, s12, v11
	v_mfma_f32_16x16x32_bf16 v[74:77], v[160:163], v[136:139], v[74:77]
	ds_read_b128 v[176:179], v225 offset:4096
	v_mul_f32_e32 v238, s12, v12
	v_mfma_f32_16x16x32_bf16 v[78:81], v[164:167], v[136:139], v[78:81]
	ds_read_b128 v[180:183], v225 offset:6144
	v_mul_f32_e32 v239, s12, v13
	v_mfma_f32_16x16x32_bf16 v[82:85], v[152:155], v[140:143], v[82:85]
	ds_read_b128 v[184:187], v233 offset:0
	v_exp_f32_e32 v1, v1
	v_mfma_f32_16x16x32_bf16 v[86:89], v[156:159], v[140:143], v[86:89]
	ds_read_b128 v[188:191], v233 offset:2048
	v_exp_f32_e32 v130, v130
	v_mfma_f32_16x16x32_bf16 v[90:93], v[160:163], v[140:143], v[90:93]
	ds_read_b128 v[192:195], v233 offset:4096
	v_exp_f32_e32 v238, v238
	v_mfma_f32_16x16x32_bf16 v[94:97], v[164:167], v[140:143], v[94:97]
	ds_read_b128 v[196:199], v233 offset:6144
	v_exp_f32_e32 v239, v239
	v_mfma_f32_16x16x32_bf16 v[98:101], v[152:155], v[144:147], v[98:101]
	v_mfma_f32_16x16x32_bf16 v[102:105], v[156:159], v[144:147], v[102:105]
	v_add_f32_e32 v1, 1.0, v1
	v_mfma_f32_16x16x32_bf16 v[106:109], v[160:163], v[144:147], v[106:109]
	v_add_f32_e32 v130, 1.0, v130
	v_mfma_f32_16x16x32_bf16 v[110:113], v[164:167], v[144:147], v[110:113]
	v_add_f32_e32 v238, 1.0, v238
	v_mfma_f32_16x16x32_bf16 v[114:117], v[152:155], v[148:151], v[114:117]
	v_add_f32_e32 v239, 1.0, v239
	v_mfma_f32_16x16x32_bf16 v[118:121], v[156:159], v[148:151], v[118:121]
	v_rcp_f32_e32 v1, v1
	v_mfma_f32_16x16x32_bf16 v[122:125], v[160:163], v[148:151], v[122:125]
	v_rcp_f32_e32 v130, v130
	v_mfma_f32_16x16x32_bf16 v[126:129], v[164:167], v[148:151], v[126:129]
	v_rcp_f32_e32 v238, v238
	s_waitcnt vmcnt(8) lgkmcnt(0)
	s_barrier
	v_mfma_f32_16x16x32_bf16 v[66:69], v[184:187], v[168:171], v[66:69]
	ds_read_b128 v[136:139], v219 offset:0
	v_mfma_f32_16x16x32_bf16 v[70:73], v[188:191], v[168:171], v[70:73]
	ds_read_b128 v[140:143], v219 offset:2048
	v_rcp_f32_e32 v239, v239
	v_mfma_f32_16x16x32_bf16 v[74:77], v[192:195], v[168:171], v[74:77]
	ds_read_b128 v[144:147], v219 offset:4096
	v_mfma_f32_16x16x32_bf16 v[78:81], v[196:199], v[168:171], v[78:81]
	ds_read_b128 v[148:151], v219 offset:6144
	v_mul_f32_e32 v10, v10, v1
	v_mfma_f32_16x16x32_bf16 v[82:85], v[184:187], v[172:175], v[82:85]
	ds_read_b128 v[152:155], v231 offset:0
	v_mul_f32_e32 v11, v11, v130
	v_mfma_f32_16x16x32_bf16 v[86:89], v[188:191], v[172:175], v[86:89]
	ds_read_b128 v[156:159], v231 offset:2048
	v_mfma_f32_16x16x32_bf16 v[90:93], v[192:195], v[172:175], v[90:93]
	ds_read_b128 v[160:163], v231 offset:4096
	v_mul_f32_e32 v12, v12, v238
	v_mfma_f32_16x16x32_bf16 v[94:97], v[196:199], v[172:175], v[94:97]
	ds_read_b128 v[164:167], v231 offset:6144
	v_mul_f32_e32 v13, v13, v239
	s_mov_b32 m0, s8
	v_mfma_f32_16x16x32_bf16 v[98:101], v[184:187], v[176:179], v[98:101]
	global_load_lds_dwordx4 v200, s[4:5]
	s_add_u32 m0, s8, 0x400
	v_mfma_f32_16x16x32_bf16 v[102:105], v[188:191], v[176:179], v[102:105]
	global_load_lds_dwordx4 v201, s[4:5]
	v_cvt_pk_bf16_f32 v10, v10, v11
	s_add_u32 m0, s8, 0x800
	v_mfma_f32_16x16x32_bf16 v[106:109], v[192:195], v[176:179], v[106:109]
	global_load_lds_dwordx4 v202, s[4:5]
	s_add_u32 m0, s8, 0xc00
	v_mfma_f32_16x16x32_bf16 v[110:113], v[196:199], v[176:179], v[110:113]
	global_load_lds_dwordx4 v203, s[4:5]
	v_cvt_pk_bf16_f32 v11, v12, v13
	s_mov_b32 m0, s9
	v_mfma_f32_16x16x32_bf16 v[114:117], v[184:187], v[180:183], v[114:117]
	global_load_lds_dwordx4 v204, s[6:7]
	global_store_dwordx2 v236, v[10:11], s[10:11] offset:64
	s_add_u32 m0, s9, 0x400
	v_mfma_f32_16x16x32_bf16 v[118:121], v[188:191], v[180:183], v[118:121]
	global_load_lds_dwordx4 v205, s[6:7]
	v_mfma_f32_16x16x32_bf16 v[122:125], v[192:195], v[180:183], v[122:125]
	s_add_u32 s4, s4, 0x80
	s_addc_u32 s5, s5, 0
	v_mul_f32_e32 v1, s12, v14
	v_mfma_f32_16x16x32_bf16 v[126:129], v[196:199], v[180:183], v[126:129]
	s_add_u32 s6, s6, 0x80
	s_addc_u32 s7, s7, 0
	v_mul_f32_e32 v130, s12, v15
	s_waitcnt lgkmcnt(0)
	v_mfma_f32_16x16x32_bf16 v[66:69], v[152:155], v[136:139], v[66:69]
	ds_read_b128 v[168:171], v228 offset:0
	v_mfma_f32_16x16x32_bf16 v[70:73], v[156:159], v[136:139], v[70:73]
	ds_read_b128 v[172:175], v228 offset:2048
	v_mul_f32_e32 v238, s12, v16
	v_mfma_f32_16x16x32_bf16 v[74:77], v[160:163], v[136:139], v[74:77]
	ds_read_b128 v[176:179], v228 offset:4096
	v_mul_f32_e32 v239, s12, v17
	v_mfma_f32_16x16x32_bf16 v[78:81], v[164:167], v[136:139], v[78:81]
	ds_read_b128 v[180:183], v228 offset:6144
	v_exp_f32_e32 v1, v1
	v_mfma_f32_16x16x32_bf16 v[82:85], v[152:155], v[140:143], v[82:85]
	ds_read_b128 v[184:187], v234 offset:0
	v_exp_f32_e32 v130, v130
	v_mfma_f32_16x16x32_bf16 v[86:89], v[156:159], v[140:143], v[86:89]
	ds_read_b128 v[188:191], v234 offset:2048
	v_exp_f32_e32 v238, v238
	v_mfma_f32_16x16x32_bf16 v[90:93], v[160:163], v[140:143], v[90:93]
	ds_read_b128 v[192:195], v234 offset:4096
	v_exp_f32_e32 v239, v239
	v_mfma_f32_16x16x32_bf16 v[94:97], v[164:167], v[140:143], v[94:97]
	ds_read_b128 v[196:199], v234 offset:6144
	v_add_f32_e32 v1, 1.0, v1
	v_mfma_f32_16x16x32_bf16 v[98:101], v[152:155], v[144:147], v[98:101]
	v_mfma_f32_16x16x32_bf16 v[102:105], v[156:159], v[144:147], v[102:105]
	v_add_f32_e32 v130, 1.0, v130
	v_mfma_f32_16x16x32_bf16 v[106:109], v[160:163], v[144:147], v[106:109]
	v_add_f32_e32 v238, 1.0, v238
	v_mfma_f32_16x16x32_bf16 v[110:113], v[164:167], v[144:147], v[110:113]
	v_add_f32_e32 v239, 1.0, v239
	v_mfma_f32_16x16x32_bf16 v[114:117], v[152:155], v[148:151], v[114:117]
	v_rcp_f32_e32 v1, v1
	v_mfma_f32_16x16x32_bf16 v[118:121], v[156:159], v[148:151], v[118:121]
	v_rcp_f32_e32 v130, v130
	v_mfma_f32_16x16x32_bf16 v[122:125], v[160:163], v[148:151], v[122:125]
	v_rcp_f32_e32 v238, v238
	v_mfma_f32_16x16x32_bf16 v[126:129], v[164:167], v[148:151], v[126:129]
	v_rcp_f32_e32 v239, v239
	s_waitcnt vmcnt(8) lgkmcnt(0)
	s_barrier
	v_mfma_f32_16x16x32_bf16 v[66:69], v[184:187], v[168:171], v[66:69]
	ds_read_b128 v[136:139], v224 offset:0
	v_mfma_f32_16x16x32_bf16 v[70:73], v[188:191], v[168:171], v[70:73]
	ds_read_b128 v[140:143], v224 offset:2048
	v_mul_f32_e32 v14, v14, v1
	v_mfma_f32_16x16x32_bf16 v[74:77], v[192:195], v[168:171], v[74:77]
	ds_read_b128 v[144:147], v224 offset:4096
	v_mfma_f32_16x16x32_bf16 v[78:81], v[196:199], v[168:171], v[78:81]
	ds_read_b128 v[148:151], v224 offset:6144
	v_mul_f32_e32 v15, v15, v130
	v_mfma_f32_16x16x32_bf16 v[82:85], v[184:187], v[172:175], v[82:85]
	ds_read_b128 v[152:155], v232 offset:0
	v_mul_f32_e32 v16, v16, v238
	v_mfma_f32_16x16x32_bf16 v[86:89], v[188:191], v[172:175], v[86:89]
	ds_read_b128 v[156:159], v232 offset:2048
	v_mfma_f32_16x16x32_bf16 v[90:93], v[192:195], v[172:175], v[90:93]
	ds_read_b128 v[160:163], v232 offset:4096
	v_mul_f32_e32 v17, v17, v239
	v_mfma_f32_16x16x32_bf16 v[94:97], v[196:199], v[172:175], v[94:97]
	ds_read_b128 v[164:167], v232 offset:6144
	v_cvt_pk_bf16_f32 v14, v14, v15
	s_add_u32 m0, s8, 0xc000
	v_mfma_f32_16x16x32_bf16 v[98:101], v[184:187], v[176:179], v[98:101]
	global_load_lds_dwordx4 v200, s[4:5]
	s_add_u32 m0, s8, 0xc400
	v_mfma_f32_16x16x32_bf16 v[102:105], v[188:191], v[176:179], v[102:105]
	global_load_lds_dwordx4 v201, s[4:5]
	v_cvt_pk_bf16_f32 v15, v16, v17
	s_add_u32 m0, s8, 0xc800
	v_mfma_f32_16x16x32_bf16 v[106:109], v[192:195], v[176:179], v[106:109]
	global_load_lds_dwordx4 v202, s[4:5]
	s_add_u32 m0, s8, 0xcc00
	v_mfma_f32_16x16x32_bf16 v[110:113], v[196:199], v[176:179], v[110:113]
	global_load_lds_dwordx4 v203, s[4:5]
	global_store_dwordx2 v236, v[14:15], s[10:11] offset:96
	s_add_u32 m0, s9, 0xc000
	v_mfma_f32_16x16x32_bf16 v[114:117], v[184:187], v[180:183], v[114:117]
	global_load_lds_dwordx4 v204, s[6:7]
	s_add_u32 s10, s10, 0x8000
	s_addc_u32 s11, s11, 0
	s_add_u32 m0, s9, 0xc400
	v_mfma_f32_16x16x32_bf16 v[118:121], v[188:191], v[180:183], v[118:121]
	global_load_lds_dwordx4 v205, s[6:7]
	v_mfma_f32_16x16x32_bf16 v[122:125], v[192:195], v[180:183], v[122:125]
	s_add_u32 s4, s4, 0x80
	s_addc_u32 s5, s5, 0
	v_mul_f32_e32 v1, s12, v18
	v_mfma_f32_16x16x32_bf16 v[126:129], v[196:199], v[180:183], v[126:129]
	s_add_u32 s6, s6, 0x80
	s_addc_u32 s7, s7, 0
	v_mul_f32_e32 v130, s12, v19
	s_waitcnt lgkmcnt(0)
	v_mfma_f32_16x16x32_bf16 v[66:69], v[152:155], v[136:139], v[66:69]
	ds_read_b128 v[168:171], v229 offset:0
	v_mfma_f32_16x16x32_bf16 v[70:73], v[156:159], v[136:139], v[70:73]
	ds_read_b128 v[172:175], v229 offset:2048
	v_mul_f32_e32 v238, s12, v20
	v_mfma_f32_16x16x32_bf16 v[74:77], v[160:163], v[136:139], v[74:77]
	ds_read_b128 v[176:179], v229 offset:4096
	v_mul_f32_e32 v239, s12, v21
	v_mfma_f32_16x16x32_bf16 v[78:81], v[164:167], v[136:139], v[78:81]
	ds_read_b128 v[180:183], v229 offset:6144
	v_exp_f32_e32 v1, v1
	v_mfma_f32_16x16x32_bf16 v[82:85], v[152:155], v[140:143], v[82:85]
	ds_read_b128 v[184:187], v235 offset:0
	v_exp_f32_e32 v130, v130
	v_mfma_f32_16x16x32_bf16 v[86:89], v[156:159], v[140:143], v[86:89]
	ds_read_b128 v[188:191], v235 offset:2048
	v_exp_f32_e32 v238, v238
	v_mfma_f32_16x16x32_bf16 v[90:93], v[160:163], v[140:143], v[90:93]
	ds_read_b128 v[192:195], v235 offset:4096
	v_exp_f32_e32 v239, v239
	v_mfma_f32_16x16x32_bf16 v[94:97], v[164:167], v[140:143], v[94:97]
	ds_read_b128 v[196:199], v235 offset:6144
	v_add_f32_e32 v1, 1.0, v1
	v_mfma_f32_16x16x32_bf16 v[98:101], v[152:155], v[144:147], v[98:101]
	v_mfma_f32_16x16x32_bf16 v[102:105], v[156:159], v[144:147], v[102:105]
	v_add_f32_e32 v130, 1.0, v130
	v_mfma_f32_16x16x32_bf16 v[106:109], v[160:163], v[144:147], v[106:109]
	v_add_f32_e32 v238, 1.0, v238
	v_mfma_f32_16x16x32_bf16 v[110:113], v[164:167], v[144:147], v[110:113]
	v_add_f32_e32 v239, 1.0, v239
	v_mfma_f32_16x16x32_bf16 v[114:117], v[152:155], v[148:151], v[114:117]
	v_rcp_f32_e32 v1, v1
	v_mfma_f32_16x16x32_bf16 v[118:121], v[156:159], v[148:151], v[118:121]
	v_rcp_f32_e32 v130, v130
	v_mfma_f32_16x16x32_bf16 v[122:125], v[160:163], v[148:151], v[122:125]
	v_rcp_f32_e32 v238, v238
	v_mfma_f32_16x16x32_bf16 v[126:129], v[164:167], v[148:151], v[126:129]
	v_rcp_f32_e32 v239, v239
	s_waitcnt vmcnt(7) lgkmcnt(0)
	s_barrier
	v_mfma_f32_16x16x32_bf16 v[66:69], v[184:187], v[168:171], v[66:69]
	ds_read_b128 v[136:139], v218 offset:0
	v_mfma_f32_16x16x32_bf16 v[70:73], v[188:191], v[168:171], v[70:73]
	ds_read_b128 v[140:143], v218 offset:2048
	v_mul_f32_e32 v18, v18, v1
	v_mfma_f32_16x16x32_bf16 v[74:77], v[192:195], v[168:171], v[74:77]
	ds_read_b128 v[144:147], v218 offset:4096
	v_mfma_f32_16x16x32_bf16 v[78:81], v[196:199], v[168:171], v[78:81]
	ds_read_b128 v[148:151], v218 offset:6144
	v_mul_f32_e32 v19, v19, v130
	v_mfma_f32_16x16x32_bf16 v[82:85], v[184:187], v[172:175], v[82:85]
	ds_read_b128 v[152:155], v230 offset:0
	v_mul_f32_e32 v20, v20, v238
	v_mfma_f32_16x16x32_bf16 v[86:89], v[188:191], v[172:175], v[86:89]
	ds_read_b128 v[156:159], v230 offset:2048
	v_mfma_f32_16x16x32_bf16 v[90:93], v[192:195], v[172:175], v[90:93]
	ds_read_b128 v[160:163], v230 offset:4096
	v_mul_f32_e32 v21, v21, v239
	v_mfma_f32_16x16x32_bf16 v[94:97], v[196:199], v[172:175], v[94:97]
	ds_read_b128 v[164:167], v230 offset:6144
	v_cvt_pk_bf16_f32 v18, v18, v19
	s_add_u32 m0, s8, 0x18000
	v_mfma_f32_16x16x32_bf16 v[98:101], v[184:187], v[176:179], v[98:101]
	global_load_lds_dwordx4 v200, s[4:5]
	s_add_u32 m0, s8, 0x18400
	v_mfma_f32_16x16x32_bf16 v[102:105], v[188:191], v[176:179], v[102:105]
	global_load_lds_dwordx4 v201, s[4:5]
	v_cvt_pk_bf16_f32 v19, v20, v21
	s_add_u32 m0, s8, 0x18800
	v_mfma_f32_16x16x32_bf16 v[106:109], v[192:195], v[176:179], v[106:109]
	global_load_lds_dwordx4 v202, s[4:5]
	s_add_u32 m0, s8, 0x18c00
	v_mfma_f32_16x16x32_bf16 v[110:113], v[196:199], v[176:179], v[110:113]
	global_load_lds_dwordx4 v203, s[4:5]
	global_store_dwordx2 v236, v[18:19], s[10:11] offset:0
	s_add_u32 m0, s9, 0x18000
	v_mfma_f32_16x16x32_bf16 v[114:117], v[184:187], v[180:183], v[114:117]
	global_load_lds_dwordx4 v204, s[6:7]
	v_mul_f32_e32 v1, s12, v22
	s_add_u32 m0, s9, 0x18400
	v_mfma_f32_16x16x32_bf16 v[118:121], v[188:191], v[180:183], v[118:121]
	global_load_lds_dwordx4 v205, s[6:7]
	v_mfma_f32_16x16x32_bf16 v[122:125], v[192:195], v[180:183], v[122:125]
	s_add_u32 s4, s4, 0x80
	s_addc_u32 s5, s5, 0
	v_mul_f32_e32 v130, s12, v23
	v_mfma_f32_16x16x32_bf16 v[126:129], v[196:199], v[180:183], v[126:129]
	s_add_u32 s6, s6, 0x80
	s_addc_u32 s7, s7, 0
	v_mul_f32_e32 v238, s12, v24
	s_waitcnt lgkmcnt(0)
	v_mfma_f32_16x16x32_bf16 v[66:69], v[152:155], v[136:139], v[66:69]
	ds_read_b128 v[168:171], v225 offset:0
	v_mfma_f32_16x16x32_bf16 v[70:73], v[156:159], v[136:139], v[70:73]
	ds_read_b128 v[172:175], v225 offset:2048
	v_mul_f32_e32 v239, s12, v25
	v_mfma_f32_16x16x32_bf16 v[74:77], v[160:163], v[136:139], v[74:77]
	ds_read_b128 v[176:179], v225 offset:4096
	v_exp_f32_e32 v1, v1
	v_mfma_f32_16x16x32_bf16 v[78:81], v[164:167], v[136:139], v[78:81]
	ds_read_b128 v[180:183], v225 offset:6144
	v_exp_f32_e32 v130, v130
	v_mfma_f32_16x16x32_bf16 v[82:85], v[152:155], v[140:143], v[82:85]
	ds_read_b128 v[184:187], v233 offset:0
	v_exp_f32_e32 v238, v238
	v_mfma_f32_16x16x32_bf16 v[86:89], v[156:159], v[140:143], v[86:89]
	ds_read_b128 v[188:191], v233 offset:2048
	v_exp_f32_e32 v239, v239
	v_mfma_f32_16x16x32_bf16 v[90:93], v[160:163], v[140:143], v[90:93]
	ds_read_b128 v[192:195], v233 offset:4096
	v_add_f32_e32 v1, 1.0, v1
	v_mfma_f32_16x16x32_bf16 v[94:97], v[164:167], v[140:143], v[94:97]
	ds_read_b128 v[196:199], v233 offset:6144
	v_add_f32_e32 v130, 1.0, v130
	v_mfma_f32_16x16x32_bf16 v[98:101], v[152:155], v[144:147], v[98:101]
	v_mfma_f32_16x16x32_bf16 v[102:105], v[156:159], v[144:147], v[102:105]
	v_add_f32_e32 v238, 1.0, v238
	v_mfma_f32_16x16x32_bf16 v[106:109], v[160:163], v[144:147], v[106:109]
	v_add_f32_e32 v239, 1.0, v239
	v_mfma_f32_16x16x32_bf16 v[110:113], v[164:167], v[144:147], v[110:113]
	v_rcp_f32_e32 v1, v1
	v_mfma_f32_16x16x32_bf16 v[114:117], v[152:155], v[148:151], v[114:117]
	v_rcp_f32_e32 v130, v130
	v_mfma_f32_16x16x32_bf16 v[118:121], v[156:159], v[148:151], v[118:121]
	v_rcp_f32_e32 v238, v238
	v_mfma_f32_16x16x32_bf16 v[122:125], v[160:163], v[148:151], v[122:125]
	v_rcp_f32_e32 v239, v239
	v_mfma_f32_16x16x32_bf16 v[126:129], v[164:167], v[148:151], v[126:129]
	v_mul_f32_e32 v22, v22, v1
	s_waitcnt vmcnt(7) lgkmcnt(0)
	s_barrier
	v_mfma_f32_16x16x32_bf16 v[66:69], v[184:187], v[168:171], v[66:69]
	ds_read_b128 v[136:139], v219 offset:0
	v_mfma_f32_16x16x32_bf16 v[70:73], v[188:191], v[168:171], v[70:73]
	ds_read_b128 v[140:143], v219 offset:2048
	v_mul_f32_e32 v23, v23, v130
	v_mfma_f32_16x16x32_bf16 v[74:77], v[192:195], v[168:171], v[74:77]
	ds_read_b128 v[144:147], v219 offset:4096
	v_mfma_f32_16x16x32_bf16 v[78:81], v[196:199], v[168:171], v[78:81]
	ds_read_b128 v[148:151], v219 offset:6144
	v_mul_f32_e32 v24, v24, v238
	v_mfma_f32_16x16x32_bf16 v[82:85], v[184:187], v[172:175], v[82:85]
	ds_read_b128 v[152:155], v231 offset:0
	v_mul_f32_e32 v25, v25, v239
	v_mfma_f32_16x16x32_bf16 v[86:89], v[188:191], v[172:175], v[86:89]
	ds_read_b128 v[156:159], v231 offset:2048
	v_mfma_f32_16x16x32_bf16 v[90:93], v[192:195], v[172:175], v[90:93]
	ds_read_b128 v[160:163], v231 offset:4096
	v_cvt_pk_bf16_f32 v22, v22, v23
	v_mfma_f32_16x16x32_bf16 v[94:97], v[196:199], v[172:175], v[94:97]
	ds_read_b128 v[164:167], v231 offset:6144
	v_cvt_pk_bf16_f32 v23, v24, v25
	s_mov_b32 m0, s8
	v_mfma_f32_16x16x32_bf16 v[98:101], v[184:187], v[176:179], v[98:101]
	global_load_lds_dwordx4 v200, s[4:5]
	s_add_u32 m0, s8, 0x400
	v_mfma_f32_16x16x32_bf16 v[102:105], v[188:191], v[176:179], v[102:105]
	global_load_lds_dwordx4 v201, s[4:5]
	global_store_dwordx2 v236, v[22:23], s[10:11] offset:32
	s_add_u32 m0, s8, 0x800
	v_mfma_f32_16x16x32_bf16 v[106:109], v[192:195], v[176:179], v[106:109]
	global_load_lds_dwordx4 v202, s[4:5]
	s_add_u32 m0, s8, 0xc00
	v_mfma_f32_16x16x32_bf16 v[110:113], v[196:199], v[176:179], v[110:113]
	global_load_lds_dwordx4 v203, s[4:5]
	v_mul_f32_e32 v1, s12, v26
	s_mov_b32 m0, s9
	v_mfma_f32_16x16x32_bf16 v[114:117], v[184:187], v[180:183], v[114:117]
	global_load_lds_dwordx4 v204, s[6:7]
	v_mul_f32_e32 v130, s12, v27
	s_add_u32 m0, s9, 0x400
	v_mfma_f32_16x16x32_bf16 v[118:121], v[188:191], v[180:183], v[118:121]
	global_load_lds_dwordx4 v205, s[6:7]
	v_mfma_f32_16x16x32_bf16 v[122:125], v[192:195], v[180:183], v[122:125]
	s_add_u32 s4, s4, 0x80
	s_addc_u32 s5, s5, 0
	v_mul_f32_e32 v238, s12, v28
	v_mfma_f32_16x16x32_bf16 v[126:129], v[196:199], v[180:183], v[126:129]
	s_add_u32 s6, s6, 0x80
	s_addc_u32 s7, s7, 0
	v_mul_f32_e32 v239, s12, v29
	s_waitcnt lgkmcnt(0)
	v_mfma_f32_16x16x32_bf16 v[66:69], v[152:155], v[136:139], v[66:69]
	ds_read_b128 v[168:171], v228 offset:0
	v_mfma_f32_16x16x32_bf16 v[70:73], v[156:159], v[136:139], v[70:73]
	ds_read_b128 v[172:175], v228 offset:2048
	v_exp_f32_e32 v1, v1
	v_mfma_f32_16x16x32_bf16 v[74:77], v[160:163], v[136:139], v[74:77]
	ds_read_b128 v[176:179], v228 offset:4096
	v_exp_f32_e32 v130, v130
	v_mfma_f32_16x16x32_bf16 v[78:81], v[164:167], v[136:139], v[78:81]
	ds_read_b128 v[180:183], v228 offset:6144
	v_exp_f32_e32 v238, v238
	v_mfma_f32_16x16x32_bf16 v[82:85], v[152:155], v[140:143], v[82:85]
	ds_read_b128 v[184:187], v234 offset:0
	v_exp_f32_e32 v239, v239
	v_mfma_f32_16x16x32_bf16 v[86:89], v[156:159], v[140:143], v[86:89]
	ds_read_b128 v[188:191], v234 offset:2048
	v_add_f32_e32 v1, 1.0, v1
	v_mfma_f32_16x16x32_bf16 v[90:93], v[160:163], v[140:143], v[90:93]
	ds_read_b128 v[192:195], v234 offset:4096
	v_add_f32_e32 v130, 1.0, v130
	v_mfma_f32_16x16x32_bf16 v[94:97], v[164:167], v[140:143], v[94:97]
	ds_read_b128 v[196:199], v234 offset:6144
	v_add_f32_e32 v238, 1.0, v238
	v_mfma_f32_16x16x32_bf16 v[98:101], v[152:155], v[144:147], v[98:101]
	v_mfma_f32_16x16x32_bf16 v[102:105], v[156:159], v[144:147], v[102:105]
	v_add_f32_e32 v239, 1.0, v239
	v_mfma_f32_16x16x32_bf16 v[106:109], v[160:163], v[144:147], v[106:109]
	v_rcp_f32_e32 v1, v1
	v_mfma_f32_16x16x32_bf16 v[110:113], v[164:167], v[144:147], v[110:113]
	v_rcp_f32_e32 v130, v130
	v_mfma_f32_16x16x32_bf16 v[114:117], v[152:155], v[148:151], v[114:117]
	v_rcp_f32_e32 v238, v238
	v_mfma_f32_16x16x32_bf16 v[118:121], v[156:159], v[148:151], v[118:121]
	v_rcp_f32_e32 v239, v239
	v_mfma_f32_16x16x32_bf16 v[122:125], v[160:163], v[148:151], v[122:125]
	v_mul_f32_e32 v26, v26, v1
	v_mfma_f32_16x16x32_bf16 v[126:129], v[164:167], v[148:151], v[126:129]
	v_mul_f32_e32 v27, v27, v130
	s_waitcnt vmcnt(7) lgkmcnt(0)
	s_barrier
	v_mfma_f32_16x16x32_bf16 v[66:69], v[184:187], v[168:171], v[66:69]
	ds_read_b128 v[136:139], v224 offset:0
	v_mfma_f32_16x16x32_bf16 v[70:73], v[188:191], v[168:171], v[70:73]
	ds_read_b128 v[140:143], v224 offset:2048
	v_mul_f32_e32 v28, v28, v238
	v_mfma_f32_16x16x32_bf16 v[74:77], v[192:195], v[168:171], v[74:77]
	ds_read_b128 v[144:147], v224 offset:4096
	v_mfma_f32_16x16x32_bf16 v[78:81], v[196:199], v[168:171], v[78:81]
	ds_read_b128 v[148:151], v224 offset:6144
	v_mul_f32_e32 v29, v29, v239
	v_mfma_f32_16x16x32_bf16 v[82:85], v[184:187], v[172:175], v[82:85]
	ds_read_b128 v[152:155], v232 offset:0
	v_cvt_pk_bf16_f32 v26, v26, v27
	v_mfma_f32_16x16x32_bf16 v[86:89], v[188:191], v[172:175], v[86:89]
	ds_read_b128 v[156:159], v232 offset:2048
	v_mfma_f32_16x16x32_bf16 v[90:93], v[192:195], v[172:175], v[90:93]
	ds_read_b128 v[160:163], v232 offset:4096
	v_cvt_pk_bf16_f32 v27, v28, v29
	v_mfma_f32_16x16x32_bf16 v[94:97], v[196:199], v[172:175], v[94:97]
	ds_read_b128 v[164:167], v232 offset:6144
	global_store_dwordx2 v236, v[26:27], s[10:11] offset:64
	s_add_u32 m0, s8, 0xc000
	v_mfma_f32_16x16x32_bf16 v[98:101], v[184:187], v[176:179], v[98:101]
	global_load_lds_dwordx4 v200, s[4:5]
	s_add_u32 m0, s8, 0xc400
	v_mfma_f32_16x16x32_bf16 v[102:105], v[188:191], v[176:179], v[102:105]
	global_load_lds_dwordx4 v201, s[4:5]
	v_mul_f32_e32 v1, s12, v30
	s_add_u32 m0, s8, 0xc800
	v_mfma_f32_16x16x32_bf16 v[106:109], v[192:195], v[176:179], v[106:109]
	global_load_lds_dwordx4 v202, s[4:5]
	s_add_u32 m0, s8, 0xcc00
	v_mfma_f32_16x16x32_bf16 v[110:113], v[196:199], v[176:179], v[110:113]
	global_load_lds_dwordx4 v203, s[4:5]
	v_mul_f32_e32 v130, s12, v31
	s_add_u32 m0, s9, 0xc000
	v_mfma_f32_16x16x32_bf16 v[114:117], v[184:187], v[180:183], v[114:117]
	global_load_lds_dwordx4 v204, s[6:7]
	v_mul_f32_e32 v238, s12, v32
	s_add_u32 m0, s9, 0xc400
	v_mfma_f32_16x16x32_bf16 v[118:121], v[188:191], v[180:183], v[118:121]
	global_load_lds_dwordx4 v205, s[6:7]
	v_mfma_f32_16x16x32_bf16 v[122:125], v[192:195], v[180:183], v[122:125]
	s_add_u32 s4, s4, 0x80
	s_addc_u32 s5, s5, 0
	v_mul_f32_e32 v239, s12, v33
	v_mfma_f32_16x16x32_bf16 v[126:129], v[196:199], v[180:183], v[126:129]
	s_add_u32 s6, s6, 0x80
	s_addc_u32 s7, s7, 0
	v_exp_f32_e32 v1, v1
	s_waitcnt lgkmcnt(0)
	v_mfma_f32_16x16x32_bf16 v[66:69], v[152:155], v[136:139], v[66:69]
	ds_read_b128 v[168:171], v229 offset:0
	v_mfma_f32_16x16x32_bf16 v[70:73], v[156:159], v[136:139], v[70:73]
	ds_read_b128 v[172:175], v229 offset:2048
	v_exp_f32_e32 v130, v130
	v_mfma_f32_16x16x32_bf16 v[74:77], v[160:163], v[136:139], v[74:77]
	ds_read_b128 v[176:179], v229 offset:4096
	v_exp_f32_e32 v238, v238
	v_mfma_f32_16x16x32_bf16 v[78:81], v[164:167], v[136:139], v[78:81]
	ds_read_b128 v[180:183], v229 offset:6144
	v_exp_f32_e32 v239, v239
	v_mfma_f32_16x16x32_bf16 v[82:85], v[152:155], v[140:143], v[82:85]
	ds_read_b128 v[184:187], v235 offset:0
	v_add_f32_e32 v1, 1.0, v1
	v_mfma_f32_16x16x32_bf16 v[86:89], v[156:159], v[140:143], v[86:89]
	ds_read_b128 v[188:191], v235 offset:2048
	v_add_f32_e32 v130, 1.0, v130
	v_mfma_f32_16x16x32_bf16 v[90:93], v[160:163], v[140:143], v[90:93]
	ds_read_b128 v[192:195], v235 offset:4096
	v_add_f32_e32 v238, 1.0, v238
	v_mfma_f32_16x16x32_bf16 v[94:97], v[164:167], v[140:143], v[94:97]
	ds_read_b128 v[196:199], v235 offset:6144
	v_add_f32_e32 v239, 1.0, v239
	v_mfma_f32_16x16x32_bf16 v[98:101], v[152:155], v[144:147], v[98:101]
	v_mfma_f32_16x16x32_bf16 v[102:105], v[156:159], v[144:147], v[102:105]
	v_rcp_f32_e32 v1, v1
	v_mfma_f32_16x16x32_bf16 v[106:109], v[160:163], v[144:147], v[106:109]
	v_rcp_f32_e32 v130, v130
	v_mfma_f32_16x16x32_bf16 v[110:113], v[164:167], v[144:147], v[110:113]
	v_rcp_f32_e32 v238, v238
	v_mfma_f32_16x16x32_bf16 v[114:117], v[152:155], v[148:151], v[114:117]
	v_rcp_f32_e32 v239, v239
	v_mfma_f32_16x16x32_bf16 v[118:121], v[156:159], v[148:151], v[118:121]
	v_mul_f32_e32 v30, v30, v1
	v_mfma_f32_16x16x32_bf16 v[122:125], v[160:163], v[148:151], v[122:125]
	v_mul_f32_e32 v31, v31, v130
	v_mfma_f32_16x16x32_bf16 v[126:129], v[164:167], v[148:151], v[126:129]
	v_mul_f32_e32 v32, v32, v238
	s_waitcnt vmcnt(7) lgkmcnt(0)
	s_barrier
	v_mfma_f32_16x16x32_bf16 v[66:69], v[184:187], v[168:171], v[66:69]
	ds_read_b128 v[136:139], v218 offset:0
	v_mfma_f32_16x16x32_bf16 v[70:73], v[188:191], v[168:171], v[70:73]
	ds_read_b128 v[140:143], v218 offset:2048
	v_mul_f32_e32 v33, v33, v239
	v_mfma_f32_16x16x32_bf16 v[74:77], v[192:195], v[168:171], v[74:77]
	ds_read_b128 v[144:147], v218 offset:4096
	v_mfma_f32_16x16x32_bf16 v[78:81], v[196:199], v[168:171], v[78:81]
	ds_read_b128 v[148:151], v218 offset:6144
	v_cvt_pk_bf16_f32 v30, v30, v31
	v_mfma_f32_16x16x32_bf16 v[82:85], v[184:187], v[172:175], v[82:85]
	ds_read_b128 v[152:155], v230 offset:0
	v_cvt_pk_bf16_f32 v31, v32, v33
	v_mfma_f32_16x16x32_bf16 v[86:89], v[188:191], v[172:175], v[86:89]
	ds_read_b128 v[156:159], v230 offset:2048
	v_mfma_f32_16x16x32_bf16 v[90:93], v[192:195], v[172:175], v[90:93]
	ds_read_b128 v[160:163], v230 offset:4096
	global_store_dwordx2 v236, v[30:31], s[10:11] offset:96
	v_mfma_f32_16x16x32_bf16 v[94:97], v[196:199], v[172:175], v[94:97]
	ds_read_b128 v[164:167], v230 offset:6144
	s_add_u32 s10, s10, 0x8000
	s_addc_u32 s11, s11, 0
	s_add_u32 m0, s8, 0x18000
	v_mfma_f32_16x16x32_bf16 v[98:101], v[184:187], v[176:179], v[98:101]
	global_load_lds_dwordx4 v200, s[4:5]
	s_add_u32 m0, s8, 0x18400
	v_mfma_f32_16x16x32_bf16 v[102:105], v[188:191], v[176:179], v[102:105]
	global_load_lds_dwordx4 v201, s[4:5]
	v_mul_f32_e32 v1, s12, v34
	s_add_u32 m0, s8, 0x18800
	v_mfma_f32_16x16x32_bf16 v[106:109], v[192:195], v[176:179], v[106:109]
	global_load_lds_dwordx4 v202, s[4:5]
	s_add_u32 m0, s8, 0x18c00
	v_mfma_f32_16x16x32_bf16 v[110:113], v[196:199], v[176:179], v[110:113]
	global_load_lds_dwordx4 v203, s[4:5]
	v_mul_f32_e32 v130, s12, v35
	s_add_u32 m0, s9, 0x18000
	v_mfma_f32_16x16x32_bf16 v[114:117], v[184:187], v[180:183], v[114:117]
	global_load_lds_dwordx4 v204, s[6:7]
	v_mul_f32_e32 v238, s12, v36
	s_add_u32 m0, s9, 0x18400
	v_mfma_f32_16x16x32_bf16 v[118:121], v[188:191], v[180:183], v[118:121]
	global_load_lds_dwordx4 v205, s[6:7]
	v_mfma_f32_16x16x32_bf16 v[122:125], v[192:195], v[180:183], v[122:125]
	s_add_u32 s4, s4, 0x80
	s_addc_u32 s5, s5, 0
	v_mul_f32_e32 v239, s12, v37
	v_mfma_f32_16x16x32_bf16 v[126:129], v[196:199], v[180:183], v[126:129]
	s_add_u32 s6, s6, 0x80
	s_addc_u32 s7, s7, 0
	v_exp_f32_e32 v1, v1
	s_waitcnt lgkmcnt(0)
	v_mfma_f32_16x16x32_bf16 v[66:69], v[152:155], v[136:139], v[66:69]
	ds_read_b128 v[168:171], v225 offset:0
	v_mfma_f32_16x16x32_bf16 v[70:73], v[156:159], v[136:139], v[70:73]
	ds_read_b128 v[172:175], v225 offset:2048
	v_exp_f32_e32 v130, v130
	v_mfma_f32_16x16x32_bf16 v[74:77], v[160:163], v[136:139], v[74:77]
	ds_read_b128 v[176:179], v225 offset:4096
	v_exp_f32_e32 v238, v238
	v_mfma_f32_16x16x32_bf16 v[78:81], v[164:167], v[136:139], v[78:81]
	ds_read_b128 v[180:183], v225 offset:6144
	v_exp_f32_e32 v239, v239
	v_mfma_f32_16x16x32_bf16 v[82:85], v[152:155], v[140:143], v[82:85]
	ds_read_b128 v[184:187], v233 offset:0
	v_add_f32_e32 v1, 1.0, v1
	v_mfma_f32_16x16x32_bf16 v[86:89], v[156:159], v[140:143], v[86:89]
	ds_read_b128 v[188:191], v233 offset:2048
	v_add_f32_e32 v130, 1.0, v130
	v_mfma_f32_16x16x32_bf16 v[90:93], v[160:163], v[140:143], v[90:93]
	ds_read_b128 v[192:195], v233 offset:4096
	v_add_f32_e32 v238, 1.0, v238
	v_mfma_f32_16x16x32_bf16 v[94:97], v[164:167], v[140:143], v[94:97]
	ds_read_b128 v[196:199], v233 offset:6144
	v_add_f32_e32 v239, 1.0, v239
	v_mfma_f32_16x16x32_bf16 v[98:101], v[152:155], v[144:147], v[98:101]
	v_mfma_f32_16x16x32_bf16 v[102:105], v[156:159], v[144:147], v[102:105]
	v_rcp_f32_e32 v1, v1
	v_mfma_f32_16x16x32_bf16 v[106:109], v[160:163], v[144:147], v[106:109]
	v_rcp_f32_e32 v130, v130
	v_mfma_f32_16x16x32_bf16 v[110:113], v[164:167], v[144:147], v[110:113]
	v_rcp_f32_e32 v238, v238
	v_mfma_f32_16x16x32_bf16 v[114:117], v[152:155], v[148:151], v[114:117]
	v_rcp_f32_e32 v239, v239
	v_mfma_f32_16x16x32_bf16 v[118:121], v[156:159], v[148:151], v[118:121]
	v_mul_f32_e32 v34, v34, v1
	v_mfma_f32_16x16x32_bf16 v[122:125], v[160:163], v[148:151], v[122:125]
	v_mul_f32_e32 v35, v35, v130
	v_mfma_f32_16x16x32_bf16 v[126:129], v[164:167], v[148:151], v[126:129]
	v_mul_f32_e32 v36, v36, v238
	s_waitcnt vmcnt(7) lgkmcnt(0)
	s_barrier
	v_mfma_f32_16x16x32_bf16 v[66:69], v[184:187], v[168:171], v[66:69]
	ds_read_b128 v[136:139], v219 offset:0
	v_mfma_f32_16x16x32_bf16 v[70:73], v[188:191], v[168:171], v[70:73]
	ds_read_b128 v[140:143], v219 offset:2048
	v_mul_f32_e32 v37, v37, v239
	v_mfma_f32_16x16x32_bf16 v[74:77], v[192:195], v[168:171], v[74:77]
	ds_read_b128 v[144:147], v219 offset:4096
	v_mfma_f32_16x16x32_bf16 v[78:81], v[196:199], v[168:171], v[78:81]
	ds_read_b128 v[148:151], v219 offset:6144
	v_cvt_pk_bf16_f32 v34, v34, v35
	v_mfma_f32_16x16x32_bf16 v[82:85], v[184:187], v[172:175], v[82:85]
	ds_read_b128 v[152:155], v231 offset:0
	v_cvt_pk_bf16_f32 v35, v36, v37
	v_mfma_f32_16x16x32_bf16 v[86:89], v[188:191], v[172:175], v[86:89]
	ds_read_b128 v[156:159], v231 offset:2048
	v_mfma_f32_16x16x32_bf16 v[90:93], v[192:195], v[172:175], v[90:93]
	ds_read_b128 v[160:163], v231 offset:4096
	global_store_dwordx2 v236, v[34:35], s[10:11] offset:0
	v_mfma_f32_16x16x32_bf16 v[94:97], v[196:199], v[172:175], v[94:97]
	ds_read_b128 v[164:167], v231 offset:6144
	v_mul_f32_e32 v1, s12, v38
	s_mov_b32 m0, s8
	v_mfma_f32_16x16x32_bf16 v[98:101], v[184:187], v[176:179], v[98:101]
	global_load_lds_dwordx4 v200, s[4:5]
	s_add_u32 m0, s8, 0x400
	v_mfma_f32_16x16x32_bf16 v[102:105], v[188:191], v[176:179], v[102:105]
	global_load_lds_dwordx4 v201, s[4:5]
	v_mul_f32_e32 v130, s12, v39
	s_add_u32 m0, s8, 0x800
	v_mfma_f32_16x16x32_bf16 v[106:109], v[192:195], v[176:179], v[106:109]
	global_load_lds_dwordx4 v202, s[4:5]
	s_add_u32 m0, s8, 0xc00
	v_mfma_f32_16x16x32_bf16 v[110:113], v[196:199], v[176:179], v[110:113]
	global_load_lds_dwordx4 v203, s[4:5]
	v_mul_f32_e32 v238, s12, v40
	s_mov_b32 m0, s9
	v_mfma_f32_16x16x32_bf16 v[114:117], v[184:187], v[180:183], v[114:117]
	global_load_lds_dwordx4 v204, s[6:7]
	v_mul_f32_e32 v239, s12, v41
	s_add_u32 m0, s9, 0x400
	v_mfma_f32_16x16x32_bf16 v[118:121], v[188:191], v[180:183], v[118:121]
	global_load_lds_dwordx4 v205, s[6:7]
	v_mfma_f32_16x16x32_bf16 v[122:125], v[192:195], v[180:183], v[122:125]
	s_add_u32 s4, s4, 0x80
	s_addc_u32 s5, s5, 0
	v_exp_f32_e32 v1, v1
	v_mfma_f32_16x16x32_bf16 v[126:129], v[196:199], v[180:183], v[126:129]
	s_add_u32 s6, s6, 0x80
	s_addc_u32 s7, s7, 0
	v_exp_f32_e32 v130, v130
	s_waitcnt lgkmcnt(0)
	v_mfma_f32_16x16x32_bf16 v[66:69], v[152:155], v[136:139], v[66:69]
	ds_read_b128 v[168:171], v228 offset:0
	v_mfma_f32_16x16x32_bf16 v[70:73], v[156:159], v[136:139], v[70:73]
	ds_read_b128 v[172:175], v228 offset:2048
	v_exp_f32_e32 v238, v238
	v_mfma_f32_16x16x32_bf16 v[74:77], v[160:163], v[136:139], v[74:77]
	ds_read_b128 v[176:179], v228 offset:4096
	v_exp_f32_e32 v239, v239
	v_mfma_f32_16x16x32_bf16 v[78:81], v[164:167], v[136:139], v[78:81]
	ds_read_b128 v[180:183], v228 offset:6144
	v_add_f32_e32 v1, 1.0, v1
	v_mfma_f32_16x16x32_bf16 v[82:85], v[152:155], v[140:143], v[82:85]
	ds_read_b128 v[184:187], v234 offset:0
	v_add_f32_e32 v130, 1.0, v130
	v_mfma_f32_16x16x32_bf16 v[86:89], v[156:159], v[140:143], v[86:89]
	ds_read_b128 v[188:191], v234 offset:2048
	v_add_f32_e32 v238, 1.0, v238
	v_mfma_f32_16x16x32_bf16 v[90:93], v[160:163], v[140:143], v[90:93]
	ds_read_b128 v[192:195], v234 offset:4096
	v_add_f32_e32 v239, 1.0, v239
	v_mfma_f32_16x16x32_bf16 v[94:97], v[164:167], v[140:143], v[94:97]
	ds_read_b128 v[196:199], v234 offset:6144
	v_rcp_f32_e32 v1, v1
	v_mfma_f32_16x16x32_bf16 v[98:101], v[152:155], v[144:147], v[98:101]
	v_mfma_f32_16x16x32_bf16 v[102:105], v[156:159], v[144:147], v[102:105]
	v_rcp_f32_e32 v130, v130
	v_mfma_f32_16x16x32_bf16 v[106:109], v[160:163], v[144:147], v[106:109]
	v_rcp_f32_e32 v238, v238
	v_mfma_f32_16x16x32_bf16 v[110:113], v[164:167], v[144:147], v[110:113]
	v_rcp_f32_e32 v239, v239
	v_mfma_f32_16x16x32_bf16 v[114:117], v[152:155], v[148:151], v[114:117]
	v_mul_f32_e32 v38, v38, v1
	v_mfma_f32_16x16x32_bf16 v[118:121], v[156:159], v[148:151], v[118:121]
	v_mul_f32_e32 v39, v39, v130
	v_mfma_f32_16x16x32_bf16 v[122:125], v[160:163], v[148:151], v[122:125]
	v_mul_f32_e32 v40, v40, v238
	v_mfma_f32_16x16x32_bf16 v[126:129], v[164:167], v[148:151], v[126:129]
	v_mul_f32_e32 v41, v41, v239
	s_waitcnt vmcnt(7) lgkmcnt(0)
	s_barrier
	v_mfma_f32_16x16x32_bf16 v[66:69], v[184:187], v[168:171], v[66:69]
	ds_read_b128 v[136:139], v224 offset:0
	v_mfma_f32_16x16x32_bf16 v[70:73], v[188:191], v[168:171], v[70:73]
	ds_read_b128 v[140:143], v224 offset:2048
	v_cvt_pk_bf16_f32 v38, v38, v39
	v_mfma_f32_16x16x32_bf16 v[74:77], v[192:195], v[168:171], v[74:77]
	ds_read_b128 v[144:147], v224 offset:4096
	v_mfma_f32_16x16x32_bf16 v[78:81], v[196:199], v[168:171], v[78:81]
	ds_read_b128 v[148:151], v224 offset:6144
	v_cvt_pk_bf16_f32 v39, v40, v41
	v_mfma_f32_16x16x32_bf16 v[82:85], v[184:187], v[172:175], v[82:85]
	ds_read_b128 v[152:155], v232 offset:0
	global_store_dwordx2 v236, v[38:39], s[10:11] offset:32
	v_mfma_f32_16x16x32_bf16 v[86:89], v[188:191], v[172:175], v[86:89]
	ds_read_b128 v[156:159], v232 offset:2048
	v_mfma_f32_16x16x32_bf16 v[90:93], v[192:195], v[172:175], v[90:93]
	ds_read_b128 v[160:163], v232 offset:4096
	v_mul_f32_e32 v1, s12, v42
	v_mfma_f32_16x16x32_bf16 v[94:97], v[196:199], v[172:175], v[94:97]
	ds_read_b128 v[164:167], v232 offset:6144
	v_mul_f32_e32 v130, s12, v43
	s_add_u32 m0, s8, 0xc000
	v_mfma_f32_16x16x32_bf16 v[98:101], v[184:187], v[176:179], v[98:101]
	global_load_lds_dwordx4 v200, s[4:5]
	s_add_u32 m0, s8, 0xc400
	v_mfma_f32_16x16x32_bf16 v[102:105], v[188:191], v[176:179], v[102:105]
	global_load_lds_dwordx4 v201, s[4:5]
	v_mul_f32_e32 v238, s12, v44
	s_add_u32 m0, s8, 0xc800
	v_mfma_f32_16x16x32_bf16 v[106:109], v[192:195], v[176:179], v[106:109]
	global_load_lds_dwordx4 v202, s[4:5]
	s_add_u32 m0, s8, 0xcc00
	v_mfma_f32_16x16x32_bf16 v[110:113], v[196:199], v[176:179], v[110:113]
	global_load_lds_dwordx4 v203, s[4:5]
	v_mul_f32_e32 v239, s12, v45
	s_add_u32 m0, s9, 0xc000
	v_mfma_f32_16x16x32_bf16 v[114:117], v[184:187], v[180:183], v[114:117]
	global_load_lds_dwordx4 v204, s[6:7]
	v_exp_f32_e32 v1, v1
	s_add_u32 m0, s9, 0xc400
	v_mfma_f32_16x16x32_bf16 v[118:121], v[188:191], v[180:183], v[118:121]
	global_load_lds_dwordx4 v205, s[6:7]
	v_mfma_f32_16x16x32_bf16 v[122:125], v[192:195], v[180:183], v[122:125]
	s_add_u32 s4, s4, 0x80
	s_addc_u32 s5, s5, 0
	v_exp_f32_e32 v130, v130
	v_mfma_f32_16x16x32_bf16 v[126:129], v[196:199], v[180:183], v[126:129]
	s_add_u32 s6, s6, 0x80
	s_addc_u32 s7, s7, 0
	v_exp_f32_e32 v238, v238
	s_waitcnt lgkmcnt(0)
	v_mfma_f32_16x16x32_bf16 v[66:69], v[152:155], v[136:139], v[66:69]
	ds_read_b128 v[168:171], v229 offset:0
	v_mfma_f32_16x16x32_bf16 v[70:73], v[156:159], v[136:139], v[70:73]
	ds_read_b128 v[172:175], v229 offset:2048
	v_exp_f32_e32 v239, v239
	v_mfma_f32_16x16x32_bf16 v[74:77], v[160:163], v[136:139], v[74:77]
	ds_read_b128 v[176:179], v229 offset:4096
	v_add_f32_e32 v1, 1.0, v1
	v_mfma_f32_16x16x32_bf16 v[78:81], v[164:167], v[136:139], v[78:81]
	ds_read_b128 v[180:183], v229 offset:6144
	v_add_f32_e32 v130, 1.0, v130
	v_mfma_f32_16x16x32_bf16 v[82:85], v[152:155], v[140:143], v[82:85]
	ds_read_b128 v[184:187], v235 offset:0
	v_add_f32_e32 v238, 1.0, v238
	v_mfma_f32_16x16x32_bf16 v[86:89], v[156:159], v[140:143], v[86:89]
	ds_read_b128 v[188:191], v235 offset:2048
	v_add_f32_e32 v239, 1.0, v239
	v_mfma_f32_16x16x32_bf16 v[90:93], v[160:163], v[140:143], v[90:93]
	ds_read_b128 v[192:195], v235 offset:4096
	v_rcp_f32_e32 v1, v1
	v_mfma_f32_16x16x32_bf16 v[94:97], v[164:167], v[140:143], v[94:97]
	ds_read_b128 v[196:199], v235 offset:6144
	v_rcp_f32_e32 v130, v130
	v_mfma_f32_16x16x32_bf16 v[98:101], v[152:155], v[144:147], v[98:101]
	v_mfma_f32_16x16x32_bf16 v[102:105], v[156:159], v[144:147], v[102:105]
	v_rcp_f32_e32 v238, v238
	v_mfma_f32_16x16x32_bf16 v[106:109], v[160:163], v[144:147], v[106:109]
	v_rcp_f32_e32 v239, v239
	v_mfma_f32_16x16x32_bf16 v[110:113], v[164:167], v[144:147], v[110:113]
	v_mul_f32_e32 v42, v42, v1
	v_mfma_f32_16x16x32_bf16 v[114:117], v[152:155], v[148:151], v[114:117]
	v_mul_f32_e32 v43, v43, v130
	v_mfma_f32_16x16x32_bf16 v[118:121], v[156:159], v[148:151], v[118:121]
	v_mul_f32_e32 v44, v44, v238
	v_mfma_f32_16x16x32_bf16 v[122:125], v[160:163], v[148:151], v[122:125]
	v_mul_f32_e32 v45, v45, v239
	v_mfma_f32_16x16x32_bf16 v[126:129], v[164:167], v[148:151], v[126:129]
	v_cvt_pk_bf16_f32 v42, v42, v43
	s_waitcnt vmcnt(7) lgkmcnt(0)
	s_barrier
	v_mfma_f32_16x16x32_bf16 v[66:69], v[184:187], v[168:171], v[66:69]
	ds_read_b128 v[136:139], v218 offset:0
	v_mfma_f32_16x16x32_bf16 v[70:73], v[188:191], v[168:171], v[70:73]
	ds_read_b128 v[140:143], v218 offset:2048
	v_cvt_pk_bf16_f32 v43, v44, v45
	v_mfma_f32_16x16x32_bf16 v[74:77], v[192:195], v[168:171], v[74:77]
	ds_read_b128 v[144:147], v218 offset:4096
	v_mfma_f32_16x16x32_bf16 v[78:81], v[196:199], v[168:171], v[78:81]
	ds_read_b128 v[148:151], v218 offset:6144
	global_store_dwordx2 v236, v[42:43], s[10:11] offset:64
	v_mfma_f32_16x16x32_bf16 v[82:85], v[184:187], v[172:175], v[82:85]
	ds_read_b128 v[152:155], v230 offset:0
	v_mul_f32_e32 v1, s12, v46
	v_mfma_f32_16x16x32_bf16 v[86:89], v[188:191], v[172:175], v[86:89]
	ds_read_b128 v[156:159], v230 offset:2048
	v_mfma_f32_16x16x32_bf16 v[90:93], v[192:195], v[172:175], v[90:93]
	ds_read_b128 v[160:163], v230 offset:4096
	v_mul_f32_e32 v130, s12, v47
	v_mfma_f32_16x16x32_bf16 v[94:97], v[196:199], v[172:175], v[94:97]
	ds_read_b128 v[164:167], v230 offset:6144
	v_mul_f32_e32 v238, s12, v48
	s_add_u32 m0, s8, 0x18000
	v_mfma_f32_16x16x32_bf16 v[98:101], v[184:187], v[176:179], v[98:101]
	global_load_lds_dwordx4 v200, s[4:5]
	s_add_u32 m0, s8, 0x18400
	v_mfma_f32_16x16x32_bf16 v[102:105], v[188:191], v[176:179], v[102:105]
	global_load_lds_dwordx4 v201, s[4:5]
	v_mul_f32_e32 v239, s12, v49
	s_add_u32 m0, s8, 0x18800
	v_mfma_f32_16x16x32_bf16 v[106:109], v[192:195], v[176:179], v[106:109]
	global_load_lds_dwordx4 v202, s[4:5]
	s_add_u32 m0, s8, 0x18c00
	v_mfma_f32_16x16x32_bf16 v[110:113], v[196:199], v[176:179], v[110:113]
	global_load_lds_dwordx4 v203, s[4:5]
	v_exp_f32_e32 v1, v1
	s_add_u32 m0, s9, 0x18000
	v_mfma_f32_16x16x32_bf16 v[114:117], v[184:187], v[180:183], v[114:117]
	global_load_lds_dwordx4 v204, s[6:7]
	v_exp_f32_e32 v130, v130
	s_add_u32 m0, s9, 0x18400
	v_mfma_f32_16x16x32_bf16 v[118:121], v[188:191], v[180:183], v[118:121]
	global_load_lds_dwordx4 v205, s[6:7]
	v_mfma_f32_16x16x32_bf16 v[122:125], v[192:195], v[180:183], v[122:125]
	s_add_u32 s4, s4, 0x80
	s_addc_u32 s5, s5, 0
	v_exp_f32_e32 v238, v238
	v_mfma_f32_16x16x32_bf16 v[126:129], v[196:199], v[180:183], v[126:129]
	s_add_u32 s6, s6, 0x80
	s_addc_u32 s7, s7, 0
	v_exp_f32_e32 v239, v239
	s_waitcnt lgkmcnt(0)
	v_mfma_f32_16x16x32_bf16 v[66:69], v[152:155], v[136:139], v[66:69]
	ds_read_b128 v[168:171], v225 offset:0
	v_mfma_f32_16x16x32_bf16 v[70:73], v[156:159], v[136:139], v[70:73]
	ds_read_b128 v[172:175], v225 offset:2048
	v_add_f32_e32 v1, 1.0, v1
	v_mfma_f32_16x16x32_bf16 v[74:77], v[160:163], v[136:139], v[74:77]
	ds_read_b128 v[176:179], v225 offset:4096
	v_add_f32_e32 v130, 1.0, v130
	v_mfma_f32_16x16x32_bf16 v[78:81], v[164:167], v[136:139], v[78:81]
	ds_read_b128 v[180:183], v225 offset:6144
	v_add_f32_e32 v238, 1.0, v238
	v_mfma_f32_16x16x32_bf16 v[82:85], v[152:155], v[140:143], v[82:85]
	ds_read_b128 v[184:187], v233 offset:0
	v_add_f32_e32 v239, 1.0, v239
	v_mfma_f32_16x16x32_bf16 v[86:89], v[156:159], v[140:143], v[86:89]
	ds_read_b128 v[188:191], v233 offset:2048
	v_rcp_f32_e32 v1, v1
	v_mfma_f32_16x16x32_bf16 v[90:93], v[160:163], v[140:143], v[90:93]
	ds_read_b128 v[192:195], v233 offset:4096
	v_rcp_f32_e32 v130, v130
	v_mfma_f32_16x16x32_bf16 v[94:97], v[164:167], v[140:143], v[94:97]
	ds_read_b128 v[196:199], v233 offset:6144
	v_rcp_f32_e32 v238, v238
	v_mfma_f32_16x16x32_bf16 v[98:101], v[152:155], v[144:147], v[98:101]
	v_mfma_f32_16x16x32_bf16 v[102:105], v[156:159], v[144:147], v[102:105]
	v_rcp_f32_e32 v239, v239
	v_mfma_f32_16x16x32_bf16 v[106:109], v[160:163], v[144:147], v[106:109]
	v_mul_f32_e32 v46, v46, v1
	v_mfma_f32_16x16x32_bf16 v[110:113], v[164:167], v[144:147], v[110:113]
	v_mul_f32_e32 v47, v47, v130
	v_mfma_f32_16x16x32_bf16 v[114:117], v[152:155], v[148:151], v[114:117]
	v_mul_f32_e32 v48, v48, v238
	v_mfma_f32_16x16x32_bf16 v[118:121], v[156:159], v[148:151], v[118:121]
	v_mul_f32_e32 v49, v49, v239
	v_mfma_f32_16x16x32_bf16 v[122:125], v[160:163], v[148:151], v[122:125]
	v_cvt_pk_bf16_f32 v46, v46, v47
	v_mfma_f32_16x16x32_bf16 v[126:129], v[164:167], v[148:151], v[126:129]
	v_cvt_pk_bf16_f32 v47, v48, v49
	s_waitcnt vmcnt(7) lgkmcnt(0)
	s_barrier
	v_mfma_f32_16x16x32_bf16 v[66:69], v[184:187], v[168:171], v[66:69]
	ds_read_b128 v[136:139], v219 offset:0
	v_mfma_f32_16x16x32_bf16 v[70:73], v[188:191], v[168:171], v[70:73]
	ds_read_b128 v[140:143], v219 offset:2048
	global_store_dwordx2 v236, v[46:47], s[10:11] offset:96
	v_mfma_f32_16x16x32_bf16 v[74:77], v[192:195], v[168:171], v[74:77]
	ds_read_b128 v[144:147], v219 offset:4096
	v_mfma_f32_16x16x32_bf16 v[78:81], v[196:199], v[168:171], v[78:81]
	ds_read_b128 v[148:151], v219 offset:6144
	s_add_u32 s10, s10, 0x8000
	s_addc_u32 s11, s11, 0
	v_mfma_f32_16x16x32_bf16 v[82:85], v[184:187], v[172:175], v[82:85]
	ds_read_b128 v[152:155], v231 offset:0
	v_mul_f32_e32 v1, s12, v50
	v_mfma_f32_16x16x32_bf16 v[86:89], v[188:191], v[172:175], v[86:89]
	ds_read_b128 v[156:159], v231 offset:2048
	v_mfma_f32_16x16x32_bf16 v[90:93], v[192:195], v[172:175], v[90:93]
	ds_read_b128 v[160:163], v231 offset:4096
	v_mul_f32_e32 v130, s12, v51
	v_mfma_f32_16x16x32_bf16 v[94:97], v[196:199], v[172:175], v[94:97]
	ds_read_b128 v[164:167], v231 offset:6144
	v_mul_f32_e32 v238, s12, v52
	s_mov_b32 m0, s8
	v_mfma_f32_16x16x32_bf16 v[98:101], v[184:187], v[176:179], v[98:101]
	global_load_lds_dwordx4 v200, s[4:5]
	s_add_u32 m0, s8, 0x400
	v_mfma_f32_16x16x32_bf16 v[102:105], v[188:191], v[176:179], v[102:105]
	global_load_lds_dwordx4 v201, s[4:5]
	v_mul_f32_e32 v239, s12, v53
	s_add_u32 m0, s8, 0x800
	v_mfma_f32_16x16x32_bf16 v[106:109], v[192:195], v[176:179], v[106:109]
	global_load_lds_dwordx4 v202, s[4:5]
	s_add_u32 m0, s8, 0xc00
	v_mfma_f32_16x16x32_bf16 v[110:113], v[196:199], v[176:179], v[110:113]
	global_load_lds_dwordx4 v203, s[4:5]
	v_exp_f32_e32 v1, v1
	s_mov_b32 m0, s9
	v_mfma_f32_16x16x32_bf16 v[114:117], v[184:187], v[180:183], v[114:117]
	global_load_lds_dwordx4 v204, s[6:7]
	v_exp_f32_e32 v130, v130
	s_add_u32 m0, s9, 0x400
	v_mfma_f32_16x16x32_bf16 v[118:121], v[188:191], v[180:183], v[118:121]
	global_load_lds_dwordx4 v205, s[6:7]
	v_mfma_f32_16x16x32_bf16 v[122:125], v[192:195], v[180:183], v[122:125]
	s_add_u32 s4, s4, 0x80
	s_addc_u32 s5, s5, 0
	v_exp_f32_e32 v238, v238
	v_mfma_f32_16x16x32_bf16 v[126:129], v[196:199], v[180:183], v[126:129]
	s_add_u32 s6, s6, 0x80
	s_addc_u32 s7, s7, 0
	v_exp_f32_e32 v239, v239
	s_waitcnt lgkmcnt(0)
	v_mfma_f32_16x16x32_bf16 v[66:69], v[152:155], v[136:139], v[66:69]
	ds_read_b128 v[168:171], v228 offset:0
	v_mfma_f32_16x16x32_bf16 v[70:73], v[156:159], v[136:139], v[70:73]
	ds_read_b128 v[172:175], v228 offset:2048
	v_add_f32_e32 v1, 1.0, v1
	v_mfma_f32_16x16x32_bf16 v[74:77], v[160:163], v[136:139], v[74:77]
	ds_read_b128 v[176:179], v228 offset:4096
	v_add_f32_e32 v130, 1.0, v130
	v_mfma_f32_16x16x32_bf16 v[78:81], v[164:167], v[136:139], v[78:81]
	ds_read_b128 v[180:183], v228 offset:6144
	v_add_f32_e32 v238, 1.0, v238
	v_mfma_f32_16x16x32_bf16 v[82:85], v[152:155], v[140:143], v[82:85]
	ds_read_b128 v[184:187], v234 offset:0
	v_add_f32_e32 v239, 1.0, v239
	v_mfma_f32_16x16x32_bf16 v[86:89], v[156:159], v[140:143], v[86:89]
	ds_read_b128 v[188:191], v234 offset:2048
	v_rcp_f32_e32 v1, v1
	v_mfma_f32_16x16x32_bf16 v[90:93], v[160:163], v[140:143], v[90:93]
	ds_read_b128 v[192:195], v234 offset:4096
	v_rcp_f32_e32 v130, v130
	v_mfma_f32_16x16x32_bf16 v[94:97], v[164:167], v[140:143], v[94:97]
	ds_read_b128 v[196:199], v234 offset:6144
	v_rcp_f32_e32 v238, v238
	v_mfma_f32_16x16x32_bf16 v[98:101], v[152:155], v[144:147], v[98:101]
	v_mfma_f32_16x16x32_bf16 v[102:105], v[156:159], v[144:147], v[102:105]
	v_rcp_f32_e32 v239, v239
	v_mfma_f32_16x16x32_bf16 v[106:109], v[160:163], v[144:147], v[106:109]
	v_mul_f32_e32 v50, v50, v1
	v_mfma_f32_16x16x32_bf16 v[110:113], v[164:167], v[144:147], v[110:113]
	v_mul_f32_e32 v51, v51, v130
	v_mfma_f32_16x16x32_bf16 v[114:117], v[152:155], v[148:151], v[114:117]
	v_mul_f32_e32 v52, v52, v238
	v_mfma_f32_16x16x32_bf16 v[118:121], v[156:159], v[148:151], v[118:121]
	v_mul_f32_e32 v53, v53, v239
	v_mfma_f32_16x16x32_bf16 v[122:125], v[160:163], v[148:151], v[122:125]
	v_cvt_pk_bf16_f32 v50, v50, v51
	v_mfma_f32_16x16x32_bf16 v[126:129], v[164:167], v[148:151], v[126:129]
	v_cvt_pk_bf16_f32 v51, v52, v53
	s_waitcnt vmcnt(7) lgkmcnt(0)
	s_barrier
	v_mfma_f32_16x16x32_bf16 v[66:69], v[184:187], v[168:171], v[66:69]
	ds_read_b128 v[136:139], v224 offset:0
	v_mfma_f32_16x16x32_bf16 v[70:73], v[188:191], v[168:171], v[70:73]
	ds_read_b128 v[140:143], v224 offset:2048
	global_store_dwordx2 v236, v[50:51], s[10:11] offset:0
	v_mfma_f32_16x16x32_bf16 v[74:77], v[192:195], v[168:171], v[74:77]
	ds_read_b128 v[144:147], v224 offset:4096
	v_mfma_f32_16x16x32_bf16 v[78:81], v[196:199], v[168:171], v[78:81]
	ds_read_b128 v[148:151], v224 offset:6144
	v_mul_f32_e32 v1, s12, v54
	v_mfma_f32_16x16x32_bf16 v[82:85], v[184:187], v[172:175], v[82:85]
	ds_read_b128 v[152:155], v232 offset:0
	v_mul_f32_e32 v130, s12, v55
	v_mfma_f32_16x16x32_bf16 v[86:89], v[188:191], v[172:175], v[86:89]
	ds_read_b128 v[156:159], v232 offset:2048
	v_mfma_f32_16x16x32_bf16 v[90:93], v[192:195], v[172:175], v[90:93]
	ds_read_b128 v[160:163], v232 offset:4096
	v_mul_f32_e32 v238, s12, v56
	v_mfma_f32_16x16x32_bf16 v[94:97], v[196:199], v[172:175], v[94:97]
	ds_read_b128 v[164:167], v232 offset:6144
	v_mul_f32_e32 v239, s12, v57
	s_add_u32 m0, s8, 0xc000
	v_mfma_f32_16x16x32_bf16 v[98:101], v[184:187], v[176:179], v[98:101]
	global_load_lds_dwordx4 v200, s[4:5]
	s_add_u32 m0, s8, 0xc400
	v_mfma_f32_16x16x32_bf16 v[102:105], v[188:191], v[176:179], v[102:105]
	global_load_lds_dwordx4 v201, s[4:5]
	v_exp_f32_e32 v1, v1
	s_add_u32 m0, s8, 0xc800
	v_mfma_f32_16x16x32_bf16 v[106:109], v[192:195], v[176:179], v[106:109]
	global_load_lds_dwordx4 v202, s[4:5]
	s_add_u32 m0, s8, 0xcc00
	v_mfma_f32_16x16x32_bf16 v[110:113], v[196:199], v[176:179], v[110:113]
	global_load_lds_dwordx4 v203, s[4:5]
	v_exp_f32_e32 v130, v130
	s_add_u32 m0, s9, 0xc000
	v_mfma_f32_16x16x32_bf16 v[114:117], v[184:187], v[180:183], v[114:117]
	global_load_lds_dwordx4 v204, s[6:7]
	v_exp_f32_e32 v238, v238
	s_add_u32 m0, s9, 0xc400
	v_mfma_f32_16x16x32_bf16 v[118:121], v[188:191], v[180:183], v[118:121]
	global_load_lds_dwordx4 v205, s[6:7]
	v_mfma_f32_16x16x32_bf16 v[122:125], v[192:195], v[180:183], v[122:125]
	s_sub_u32 s4, s4, 0x780
	s_subb_u32 s5, s5, 0
	v_exp_f32_e32 v239, v239
	v_mfma_f32_16x16x32_bf16 v[126:129], v[196:199], v[180:183], v[126:129]
	s_add_u32 s6, s6, 0x3f880
	s_addc_u32 s7, s7, 0
	v_add_f32_e32 v1, 1.0, v1
	s_waitcnt lgkmcnt(0)
	v_mfma_f32_16x16x32_bf16 v[66:69], v[152:155], v[136:139], v[66:69]
	ds_read_b128 v[168:171], v229 offset:0
	v_mfma_f32_16x16x32_bf16 v[70:73], v[156:159], v[136:139], v[70:73]
	ds_read_b128 v[172:175], v229 offset:2048
	v_add_f32_e32 v130, 1.0, v130
	v_mfma_f32_16x16x32_bf16 v[74:77], v[160:163], v[136:139], v[74:77]
	ds_read_b128 v[176:179], v229 offset:4096
	v_add_f32_e32 v238, 1.0, v238
	v_mfma_f32_16x16x32_bf16 v[78:81], v[164:167], v[136:139], v[78:81]
	ds_read_b128 v[180:183], v229 offset:6144
	v_add_f32_e32 v239, 1.0, v239
	v_mfma_f32_16x16x32_bf16 v[82:85], v[152:155], v[140:143], v[82:85]
	ds_read_b128 v[184:187], v235 offset:0
	v_rcp_f32_e32 v1, v1
	v_mfma_f32_16x16x32_bf16 v[86:89], v[156:159], v[140:143], v[86:89]
	ds_read_b128 v[188:191], v235 offset:2048
	v_rcp_f32_e32 v130, v130
	v_mfma_f32_16x16x32_bf16 v[90:93], v[160:163], v[140:143], v[90:93]
	ds_read_b128 v[192:195], v235 offset:4096
	v_rcp_f32_e32 v238, v238
	v_mfma_f32_16x16x32_bf16 v[94:97], v[164:167], v[140:143], v[94:97]
	ds_read_b128 v[196:199], v235 offset:6144
	v_rcp_f32_e32 v239, v239
	v_mfma_f32_16x16x32_bf16 v[98:101], v[152:155], v[144:147], v[98:101]
	v_mfma_f32_16x16x32_bf16 v[102:105], v[156:159], v[144:147], v[102:105]
	v_mul_f32_e32 v54, v54, v1
	v_mfma_f32_16x16x32_bf16 v[106:109], v[160:163], v[144:147], v[106:109]
	v_mul_f32_e32 v55, v55, v130
	v_mfma_f32_16x16x32_bf16 v[110:113], v[164:167], v[144:147], v[110:113]
	v_mul_f32_e32 v56, v56, v238
	v_mfma_f32_16x16x32_bf16 v[114:117], v[152:155], v[148:151], v[114:117]
	v_mul_f32_e32 v57, v57, v239
	v_mfma_f32_16x16x32_bf16 v[118:121], v[156:159], v[148:151], v[118:121]
	v_cvt_pk_bf16_f32 v54, v54, v55
	v_mfma_f32_16x16x32_bf16 v[122:125], v[160:163], v[148:151], v[122:125]
	v_cvt_pk_bf16_f32 v55, v56, v57
	v_mfma_f32_16x16x32_bf16 v[126:129], v[164:167], v[148:151], v[126:129]
	global_store_dwordx2 v236, v[54:55], s[10:11] offset:32
	s_waitcnt vmcnt(8) lgkmcnt(0)
	s_barrier
	v_mfma_f32_16x16x32_bf16 v[66:69], v[184:187], v[168:171], v[66:69]
	ds_read_b128 v[136:139], v218 offset:0
	v_mfma_f32_16x16x32_bf16 v[70:73], v[188:191], v[168:171], v[70:73]
	ds_read_b128 v[140:143], v218 offset:2048
	v_mul_f32_e32 v1, s12, v58
	v_mfma_f32_16x16x32_bf16 v[74:77], v[192:195], v[168:171], v[74:77]
	ds_read_b128 v[144:147], v218 offset:4096
	v_mfma_f32_16x16x32_bf16 v[78:81], v[196:199], v[168:171], v[78:81]
	ds_read_b128 v[148:151], v218 offset:6144
	v_mul_f32_e32 v130, s12, v59
	v_mfma_f32_16x16x32_bf16 v[82:85], v[184:187], v[172:175], v[82:85]
	ds_read_b128 v[152:155], v230 offset:0
	v_mul_f32_e32 v238, s12, v60
	v_mfma_f32_16x16x32_bf16 v[86:89], v[188:191], v[172:175], v[86:89]
	ds_read_b128 v[156:159], v230 offset:2048
	v_mfma_f32_16x16x32_bf16 v[90:93], v[192:195], v[172:175], v[90:93]
	ds_read_b128 v[160:163], v230 offset:4096
	v_mul_f32_e32 v239, s12, v61
	v_mfma_f32_16x16x32_bf16 v[94:97], v[196:199], v[172:175], v[94:97]
	ds_read_b128 v[164:167], v230 offset:6144
	v_exp_f32_e32 v1, v1
	v_mfma_f32_16x16x32_bf16 v[98:101], v[184:187], v[176:179], v[98:101]
	v_mfma_f32_16x16x32_bf16 v[102:105], v[188:191], v[176:179], v[102:105]
	v_exp_f32_e32 v130, v130
	v_mfma_f32_16x16x32_bf16 v[106:109], v[192:195], v[176:179], v[106:109]
	v_mfma_f32_16x16x32_bf16 v[110:113], v[196:199], v[176:179], v[110:113]
	v_exp_f32_e32 v238, v238
	v_mfma_f32_16x16x32_bf16 v[114:117], v[184:187], v[180:183], v[114:117]
	v_exp_f32_e32 v239, v239
	v_mfma_f32_16x16x32_bf16 v[118:121], v[188:191], v[180:183], v[118:121]
	v_mfma_f32_16x16x32_bf16 v[122:125], v[192:195], v[180:183], v[122:125]
	v_add_f32_e32 v1, 1.0, v1
	v_mfma_f32_16x16x32_bf16 v[126:129], v[196:199], v[180:183], v[126:129]
	v_add_f32_e32 v130, 1.0, v130
	s_waitcnt lgkmcnt(0)
	v_mfma_f32_16x16x32_bf16 v[66:69], v[152:155], v[136:139], v[66:69]
	ds_read_b128 v[168:171], v225 offset:0
	v_mfma_f32_16x16x32_bf16 v[70:73], v[156:159], v[136:139], v[70:73]
	ds_read_b128 v[172:175], v225 offset:2048
	v_add_f32_e32 v238, 1.0, v238
	v_mfma_f32_16x16x32_bf16 v[74:77], v[160:163], v[136:139], v[74:77]
	ds_read_b128 v[176:179], v225 offset:4096
	v_add_f32_e32 v239, 1.0, v239
	v_mfma_f32_16x16x32_bf16 v[78:81], v[164:167], v[136:139], v[78:81]
	ds_read_b128 v[180:183], v225 offset:6144
	v_rcp_f32_e32 v1, v1
	v_mfma_f32_16x16x32_bf16 v[82:85], v[152:155], v[140:143], v[82:85]
	ds_read_b128 v[184:187], v233 offset:0
	v_rcp_f32_e32 v130, v130
	v_mfma_f32_16x16x32_bf16 v[86:89], v[156:159], v[140:143], v[86:89]
	ds_read_b128 v[188:191], v233 offset:2048
	v_rcp_f32_e32 v238, v238
	v_mfma_f32_16x16x32_bf16 v[90:93], v[160:163], v[140:143], v[90:93]
	ds_read_b128 v[192:195], v233 offset:4096
	v_rcp_f32_e32 v239, v239
	v_mfma_f32_16x16x32_bf16 v[94:97], v[164:167], v[140:143], v[94:97]
	ds_read_b128 v[196:199], v233 offset:6144
	v_mul_f32_e32 v58, v58, v1
	v_mfma_f32_16x16x32_bf16 v[98:101], v[152:155], v[144:147], v[98:101]
	v_mfma_f32_16x16x32_bf16 v[102:105], v[156:159], v[144:147], v[102:105]
	v_mul_f32_e32 v59, v59, v130
	v_mfma_f32_16x16x32_bf16 v[106:109], v[160:163], v[144:147], v[106:109]
	v_mul_f32_e32 v60, v60, v238
	v_mfma_f32_16x16x32_bf16 v[110:113], v[164:167], v[144:147], v[110:113]
	v_mul_f32_e32 v61, v61, v239
	v_mfma_f32_16x16x32_bf16 v[114:117], v[152:155], v[148:151], v[114:117]
	v_cvt_pk_bf16_f32 v58, v58, v59
	v_mfma_f32_16x16x32_bf16 v[118:121], v[156:159], v[148:151], v[118:121]
	v_cvt_pk_bf16_f32 v59, v60, v61
	v_mfma_f32_16x16x32_bf16 v[122:125], v[160:163], v[148:151], v[122:125]
	global_store_dwordx2 v236, v[58:59], s[10:11] offset:64
	v_mfma_f32_16x16x32_bf16 v[126:129], v[164:167], v[148:151], v[126:129]
	v_mul_f32_e32 v1, s12, v62
	s_waitcnt vmcnt(2) lgkmcnt(0)
	s_barrier
	v_mfma_f32_16x16x32_bf16 v[66:69], v[184:187], v[168:171], v[66:69]
	ds_read_b128 v[136:139], v219 offset:0
	v_mfma_f32_16x16x32_bf16 v[70:73], v[188:191], v[168:171], v[70:73]
	ds_read_b128 v[140:143], v219 offset:2048
	v_mul_f32_e32 v130, s12, v63
	v_mfma_f32_16x16x32_bf16 v[74:77], v[192:195], v[168:171], v[74:77]
	ds_read_b128 v[144:147], v219 offset:4096
	v_mfma_f32_16x16x32_bf16 v[78:81], v[196:199], v[168:171], v[78:81]
	ds_read_b128 v[148:151], v219 offset:6144
	v_mul_f32_e32 v238, s12, v64
	v_mfma_f32_16x16x32_bf16 v[82:85], v[184:187], v[172:175], v[82:85]
	ds_read_b128 v[152:155], v231 offset:0
	v_mul_f32_e32 v239, s12, v65
	v_mfma_f32_16x16x32_bf16 v[86:89], v[188:191], v[172:175], v[86:89]
	ds_read_b128 v[156:159], v231 offset:2048
	v_mfma_f32_16x16x32_bf16 v[90:93], v[192:195], v[172:175], v[90:93]
	ds_read_b128 v[160:163], v231 offset:4096
	v_exp_f32_e32 v1, v1
	v_mfma_f32_16x16x32_bf16 v[94:97], v[196:199], v[172:175], v[94:97]
	ds_read_b128 v[164:167], v231 offset:6144
	v_exp_f32_e32 v130, v130
	v_mfma_f32_16x16x32_bf16 v[98:101], v[184:187], v[176:179], v[98:101]
	v_mfma_f32_16x16x32_bf16 v[102:105], v[188:191], v[176:179], v[102:105]
	v_exp_f32_e32 v238, v238
	v_mfma_f32_16x16x32_bf16 v[106:109], v[192:195], v[176:179], v[106:109]
	v_mfma_f32_16x16x32_bf16 v[110:113], v[196:199], v[176:179], v[110:113]
	v_exp_f32_e32 v239, v239
	v_mfma_f32_16x16x32_bf16 v[114:117], v[184:187], v[180:183], v[114:117]
	v_add_f32_e32 v1, 1.0, v1
	v_mfma_f32_16x16x32_bf16 v[118:121], v[188:191], v[180:183], v[118:121]
	v_mfma_f32_16x16x32_bf16 v[122:125], v[192:195], v[180:183], v[122:125]
	v_add_f32_e32 v130, 1.0, v130
	v_mfma_f32_16x16x32_bf16 v[126:129], v[196:199], v[180:183], v[126:129]
	v_add_f32_e32 v238, 1.0, v238
	s_waitcnt lgkmcnt(0)
	v_mfma_f32_16x16x32_bf16 v[66:69], v[152:155], v[136:139], v[66:69]
	ds_read_b128 v[168:171], v228 offset:0
	v_mfma_f32_16x16x32_bf16 v[70:73], v[156:159], v[136:139], v[70:73]
	ds_read_b128 v[172:175], v228 offset:2048
	v_add_f32_e32 v239, 1.0, v239
	v_mfma_f32_16x16x32_bf16 v[74:77], v[160:163], v[136:139], v[74:77]
	ds_read_b128 v[176:179], v228 offset:4096
	v_rcp_f32_e32 v1, v1
	v_mfma_f32_16x16x32_bf16 v[78:81], v[164:167], v[136:139], v[78:81]
	ds_read_b128 v[180:183], v228 offset:6144
	v_rcp_f32_e32 v130, v130
	v_mfma_f32_16x16x32_bf16 v[82:85], v[152:155], v[140:143], v[82:85]
	ds_read_b128 v[184:187], v234 offset:0
	v_mfma_f32_16x16x32_bf16 v[86:89], v[156:159], v[140:143], v[86:89]
	ds_read_b128 v[188:191], v234 offset:2048
	v_rcp_f32_e32 v238, v238
	v_mfma_f32_16x16x32_bf16 v[90:93], v[160:163], v[140:143], v[90:93]
	ds_read_b128 v[192:195], v234 offset:4096
	v_rcp_f32_e32 v239, v239
	v_mfma_f32_16x16x32_bf16 v[94:97], v[164:167], v[140:143], v[94:97]
	ds_read_b128 v[196:199], v234 offset:6144
	v_mul_f32_e32 v62, v62, v1
	v_mfma_f32_16x16x32_bf16 v[98:101], v[152:155], v[144:147], v[98:101]
	v_mfma_f32_16x16x32_bf16 v[102:105], v[156:159], v[144:147], v[102:105]
	v_mul_f32_e32 v63, v63, v130
	v_mfma_f32_16x16x32_bf16 v[106:109], v[160:163], v[144:147], v[106:109]
	v_mul_f32_e32 v64, v64, v238
	v_mfma_f32_16x16x32_bf16 v[110:113], v[164:167], v[144:147], v[110:113]
	v_mul_f32_e32 v65, v65, v239
	v_mfma_f32_16x16x32_bf16 v[114:117], v[152:155], v[148:151], v[114:117]
	v_mfma_f32_16x16x32_bf16 v[118:121], v[156:159], v[148:151], v[118:121]
	v_cvt_pk_bf16_f32 v62, v62, v63
	v_mfma_f32_16x16x32_bf16 v[122:125], v[160:163], v[148:151], v[122:125]
	v_cvt_pk_bf16_f32 v63, v64, v65
	v_mfma_f32_16x16x32_bf16 v[126:129], v[164:167], v[148:151], v[126:129]
	global_store_dwordx2 v236, v[62:63], s[10:11] offset:96
	s_waitcnt lgkmcnt(0)
	v_mfma_f32_16x16x32_bf16 v[66:69], v[184:187], v[168:171], v[66:69]
	v_mfma_f32_16x16x32_bf16 v[70:73], v[188:191], v[168:171], v[70:73]
	v_mfma_f32_16x16x32_bf16 v[74:77], v[192:195], v[168:171], v[74:77]
	v_mfma_f32_16x16x32_bf16 v[78:81], v[196:199], v[168:171], v[78:81]
	v_mfma_f32_16x16x32_bf16 v[82:85], v[184:187], v[172:175], v[82:85]
	v_mfma_f32_16x16x32_bf16 v[86:89], v[188:191], v[172:175], v[86:89]
	v_mfma_f32_16x16x32_bf16 v[90:93], v[192:195], v[172:175], v[90:93]
	v_mfma_f32_16x16x32_bf16 v[94:97], v[196:199], v[172:175], v[94:97]
	v_mfma_f32_16x16x32_bf16 v[98:101], v[184:187], v[176:179], v[98:101]
	v_mfma_f32_16x16x32_bf16 v[102:105], v[188:191], v[176:179], v[102:105]
	v_mfma_f32_16x16x32_bf16 v[106:109], v[192:195], v[176:179], v[106:109]
	v_mfma_f32_16x16x32_bf16 v[110:113], v[196:199], v[176:179], v[110:113]
	v_mfma_f32_16x16x32_bf16 v[114:117], v[184:187], v[180:183], v[114:117]
	v_mfma_f32_16x16x32_bf16 v[118:121], v[188:191], v[180:183], v[118:121]
	v_mfma_f32_16x16x32_bf16 v[122:125], v[192:195], v[180:183], v[122:125]
	v_mfma_f32_16x16x32_bf16 v[126:129], v[196:199], v[180:183], v[126:129]
	s_nop 7
	s_add_u32 s10, s52, 0x100
	s_addc_u32 s11, s53, 0
	v_mul_f32_e32 v1, s12, v66
	v_mul_f32_e32 v130, s12, v67
	v_mul_f32_e32 v238, s12, v68
	v_mul_f32_e32 v239, s12, v69
	v_exp_f32_e32 v1, v1
	v_exp_f32_e32 v130, v130
	v_exp_f32_e32 v238, v238
	v_exp_f32_e32 v239, v239
	v_add_f32_e32 v1, 1.0, v1
	v_add_f32_e32 v130, 1.0, v130
	v_add_f32_e32 v238, 1.0, v238
	v_add_f32_e32 v239, 1.0, v239
	v_rcp_f32_e32 v1, v1
	v_rcp_f32_e32 v130, v130
	v_rcp_f32_e32 v238, v238
	v_rcp_f32_e32 v239, v239
	v_mul_f32_e32 v66, v66, v1
	v_mul_f32_e32 v67, v67, v130
	v_mul_f32_e32 v68, v68, v238
	v_mul_f32_e32 v69, v69, v239
	v_cvt_pk_bf16_f32 v66, v66, v67
	v_cvt_pk_bf16_f32 v67, v68, v69
	global_store_dwordx2 v236, v[66:67], s[10:11] offset:0
	v_mul_f32_e32 v1, s12, v70
	v_mul_f32_e32 v130, s12, v71
	v_mul_f32_e32 v238, s12, v72
	v_mul_f32_e32 v239, s12, v73
	v_exp_f32_e32 v1, v1
	v_exp_f32_e32 v130, v130
	v_exp_f32_e32 v238, v238
	v_exp_f32_e32 v239, v239
	v_add_f32_e32 v1, 1.0, v1
	v_add_f32_e32 v130, 1.0, v130
	v_add_f32_e32 v238, 1.0, v238
	v_add_f32_e32 v239, 1.0, v239
	v_rcp_f32_e32 v1, v1
	v_rcp_f32_e32 v130, v130
	v_rcp_f32_e32 v238, v238
	v_rcp_f32_e32 v239, v239
	v_mul_f32_e32 v70, v70, v1
	v_mul_f32_e32 v71, v71, v130
	v_mul_f32_e32 v72, v72, v238
	v_mul_f32_e32 v73, v73, v239
	v_cvt_pk_bf16_f32 v70, v70, v71
	v_cvt_pk_bf16_f32 v71, v72, v73
	global_store_dwordx2 v236, v[70:71], s[10:11] offset:32
	v_mul_f32_e32 v1, s12, v74
	v_mul_f32_e32 v130, s12, v75
	v_mul_f32_e32 v238, s12, v76
	v_mul_f32_e32 v239, s12, v77
	v_exp_f32_e32 v1, v1
	v_exp_f32_e32 v130, v130
	v_exp_f32_e32 v238, v238
	v_exp_f32_e32 v239, v239
	v_add_f32_e32 v1, 1.0, v1
	v_add_f32_e32 v130, 1.0, v130
	v_add_f32_e32 v238, 1.0, v238
	v_add_f32_e32 v239, 1.0, v239
	v_rcp_f32_e32 v1, v1
	v_rcp_f32_e32 v130, v130
	v_rcp_f32_e32 v238, v238
	v_rcp_f32_e32 v239, v239
	v_mul_f32_e32 v74, v74, v1
	v_mul_f32_e32 v75, v75, v130
	v_mul_f32_e32 v76, v76, v238
	v_mul_f32_e32 v77, v77, v239
	v_cvt_pk_bf16_f32 v74, v74, v75
	v_cvt_pk_bf16_f32 v75, v76, v77
	global_store_dwordx2 v236, v[74:75], s[10:11] offset:64
	v_mul_f32_e32 v1, s12, v78
	v_mul_f32_e32 v130, s12, v79
	v_mul_f32_e32 v238, s12, v80
	v_mul_f32_e32 v239, s12, v81
	v_exp_f32_e32 v1, v1
	v_exp_f32_e32 v130, v130
	v_exp_f32_e32 v238, v238
	v_exp_f32_e32 v239, v239
	v_add_f32_e32 v1, 1.0, v1
	v_add_f32_e32 v130, 1.0, v130
	v_add_f32_e32 v238, 1.0, v238
	v_add_f32_e32 v239, 1.0, v239
	v_rcp_f32_e32 v1, v1
	v_rcp_f32_e32 v130, v130
	v_rcp_f32_e32 v238, v238
	v_rcp_f32_e32 v239, v239
	v_mul_f32_e32 v78, v78, v1
	v_mul_f32_e32 v79, v79, v130
	v_mul_f32_e32 v80, v80, v238
	v_mul_f32_e32 v81, v81, v239
	v_cvt_pk_bf16_f32 v78, v78, v79
	v_cvt_pk_bf16_f32 v79, v80, v81
	global_store_dwordx2 v236, v[78:79], s[10:11] offset:96
	s_add_u32 s10, s10, 0x8000
	s_addc_u32 s11, s11, 0
	v_mul_f32_e32 v1, s12, v82
	v_mul_f32_e32 v130, s12, v83
	v_mul_f32_e32 v238, s12, v84
	v_mul_f32_e32 v239, s12, v85
	v_exp_f32_e32 v1, v1
	v_exp_f32_e32 v130, v130
	v_exp_f32_e32 v238, v238
	v_exp_f32_e32 v239, v239
	v_add_f32_e32 v1, 1.0, v1
	v_add_f32_e32 v130, 1.0, v130
	v_add_f32_e32 v238, 1.0, v238
	v_add_f32_e32 v239, 1.0, v239
	v_rcp_f32_e32 v1, v1
	v_rcp_f32_e32 v130, v130
	v_rcp_f32_e32 v238, v238
	v_rcp_f32_e32 v239, v239
	v_mul_f32_e32 v82, v82, v1
	v_mul_f32_e32 v83, v83, v130
	v_mul_f32_e32 v84, v84, v238
	v_mul_f32_e32 v85, v85, v239
	v_cvt_pk_bf16_f32 v82, v82, v83
	v_cvt_pk_bf16_f32 v83, v84, v85
	global_store_dwordx2 v236, v[82:83], s[10:11] offset:0
	v_mul_f32_e32 v1, s12, v86
	v_mul_f32_e32 v130, s12, v87
	v_mul_f32_e32 v238, s12, v88
	v_mul_f32_e32 v239, s12, v89
	v_exp_f32_e32 v1, v1
	v_exp_f32_e32 v130, v130
	v_exp_f32_e32 v238, v238
	v_exp_f32_e32 v239, v239
	v_add_f32_e32 v1, 1.0, v1
	v_add_f32_e32 v130, 1.0, v130
	v_add_f32_e32 v238, 1.0, v238
	v_add_f32_e32 v239, 1.0, v239
	v_rcp_f32_e32 v1, v1
	v_rcp_f32_e32 v130, v130
	v_rcp_f32_e32 v238, v238
	v_rcp_f32_e32 v239, v239
	v_mul_f32_e32 v86, v86, v1
	v_mul_f32_e32 v87, v87, v130
	v_mul_f32_e32 v88, v88, v238
	v_mul_f32_e32 v89, v89, v239
	v_cvt_pk_bf16_f32 v86, v86, v87
	v_cvt_pk_bf16_f32 v87, v88, v89
	global_store_dwordx2 v236, v[86:87], s[10:11] offset:32
	v_mul_f32_e32 v1, s12, v90
	v_mul_f32_e32 v130, s12, v91
	v_mul_f32_e32 v238, s12, v92
	v_mul_f32_e32 v239, s12, v93
	v_exp_f32_e32 v1, v1
	v_exp_f32_e32 v130, v130
	v_exp_f32_e32 v238, v238
	v_exp_f32_e32 v239, v239
	v_add_f32_e32 v1, 1.0, v1
	v_add_f32_e32 v130, 1.0, v130
	v_add_f32_e32 v238, 1.0, v238
	v_add_f32_e32 v239, 1.0, v239
	v_rcp_f32_e32 v1, v1
	v_rcp_f32_e32 v130, v130
	v_rcp_f32_e32 v238, v238
	v_rcp_f32_e32 v239, v239
	v_mul_f32_e32 v90, v90, v1
	v_mul_f32_e32 v91, v91, v130
	v_mul_f32_e32 v92, v92, v238
	v_mul_f32_e32 v93, v93, v239
	v_cvt_pk_bf16_f32 v90, v90, v91
	v_cvt_pk_bf16_f32 v91, v92, v93
	global_store_dwordx2 v236, v[90:91], s[10:11] offset:64
	v_mul_f32_e32 v1, s12, v94
	v_mul_f32_e32 v130, s12, v95
	v_mul_f32_e32 v238, s12, v96
	v_mul_f32_e32 v239, s12, v97
	v_exp_f32_e32 v1, v1
	v_exp_f32_e32 v130, v130
	v_exp_f32_e32 v238, v238
	v_exp_f32_e32 v239, v239
	v_add_f32_e32 v1, 1.0, v1
	v_add_f32_e32 v130, 1.0, v130
	v_add_f32_e32 v238, 1.0, v238
	v_add_f32_e32 v239, 1.0, v239
	v_rcp_f32_e32 v1, v1
	v_rcp_f32_e32 v130, v130
	v_rcp_f32_e32 v238, v238
	v_rcp_f32_e32 v239, v239
	v_mul_f32_e32 v94, v94, v1
	v_mul_f32_e32 v95, v95, v130
	v_mul_f32_e32 v96, v96, v238
	v_mul_f32_e32 v97, v97, v239
	v_cvt_pk_bf16_f32 v94, v94, v95
	v_cvt_pk_bf16_f32 v95, v96, v97
	global_store_dwordx2 v236, v[94:95], s[10:11] offset:96
	s_add_u32 s10, s10, 0x8000
	s_addc_u32 s11, s11, 0
	v_mul_f32_e32 v1, s12, v98
	v_mul_f32_e32 v130, s12, v99
	v_mul_f32_e32 v238, s12, v100
	v_mul_f32_e32 v239, s12, v101
	v_exp_f32_e32 v1, v1
	v_exp_f32_e32 v130, v130
	v_exp_f32_e32 v238, v238
	v_exp_f32_e32 v239, v239
	v_add_f32_e32 v1, 1.0, v1
	v_add_f32_e32 v130, 1.0, v130
	v_add_f32_e32 v238, 1.0, v238
	v_add_f32_e32 v239, 1.0, v239
	v_rcp_f32_e32 v1, v1
	v_rcp_f32_e32 v130, v130
	v_rcp_f32_e32 v238, v238
	v_rcp_f32_e32 v239, v239
	v_mul_f32_e32 v98, v98, v1
	v_mul_f32_e32 v99, v99, v130
	v_mul_f32_e32 v100, v100, v238
	v_mul_f32_e32 v101, v101, v239
	v_cvt_pk_bf16_f32 v98, v98, v99
	v_cvt_pk_bf16_f32 v99, v100, v101
	global_store_dwordx2 v236, v[98:99], s[10:11] offset:0
	v_mul_f32_e32 v1, s12, v102
	v_mul_f32_e32 v130, s12, v103
	v_mul_f32_e32 v238, s12, v104
	v_mul_f32_e32 v239, s12, v105
	v_exp_f32_e32 v1, v1
	v_exp_f32_e32 v130, v130
	v_exp_f32_e32 v238, v238
	v_exp_f32_e32 v239, v239
	v_add_f32_e32 v1, 1.0, v1
	v_add_f32_e32 v130, 1.0, v130
	v_add_f32_e32 v238, 1.0, v238
	v_add_f32_e32 v239, 1.0, v239
	v_rcp_f32_e32 v1, v1
	v_rcp_f32_e32 v130, v130
	v_rcp_f32_e32 v238, v238
	v_rcp_f32_e32 v239, v239
	v_mul_f32_e32 v102, v102, v1
	v_mul_f32_e32 v103, v103, v130
	v_mul_f32_e32 v104, v104, v238
	v_mul_f32_e32 v105, v105, v239
	v_cvt_pk_bf16_f32 v102, v102, v103
	v_cvt_pk_bf16_f32 v103, v104, v105
	global_store_dwordx2 v236, v[102:103], s[10:11] offset:32
	v_mul_f32_e32 v1, s12, v106
	v_mul_f32_e32 v130, s12, v107
	v_mul_f32_e32 v238, s12, v108
	v_mul_f32_e32 v239, s12, v109
	v_exp_f32_e32 v1, v1
	v_exp_f32_e32 v130, v130
	v_exp_f32_e32 v238, v238
	v_exp_f32_e32 v239, v239
	v_add_f32_e32 v1, 1.0, v1
	v_add_f32_e32 v130, 1.0, v130
	v_add_f32_e32 v238, 1.0, v238
	v_add_f32_e32 v239, 1.0, v239
	v_rcp_f32_e32 v1, v1
	v_rcp_f32_e32 v130, v130
	v_rcp_f32_e32 v238, v238
	v_rcp_f32_e32 v239, v239
	v_mul_f32_e32 v106, v106, v1
	v_mul_f32_e32 v107, v107, v130
	v_mul_f32_e32 v108, v108, v238
	v_mul_f32_e32 v109, v109, v239
	v_cvt_pk_bf16_f32 v106, v106, v107
	v_cvt_pk_bf16_f32 v107, v108, v109
	global_store_dwordx2 v236, v[106:107], s[10:11] offset:64
	v_mul_f32_e32 v1, s12, v110
	v_mul_f32_e32 v130, s12, v111
	v_mul_f32_e32 v238, s12, v112
	v_mul_f32_e32 v239, s12, v113
	v_exp_f32_e32 v1, v1
	v_exp_f32_e32 v130, v130
	v_exp_f32_e32 v238, v238
	v_exp_f32_e32 v239, v239
	v_add_f32_e32 v1, 1.0, v1
	v_add_f32_e32 v130, 1.0, v130
	v_add_f32_e32 v238, 1.0, v238
	v_add_f32_e32 v239, 1.0, v239
	v_rcp_f32_e32 v1, v1
	v_rcp_f32_e32 v130, v130
	v_rcp_f32_e32 v238, v238
	v_rcp_f32_e32 v239, v239
	v_mul_f32_e32 v110, v110, v1
	v_mul_f32_e32 v111, v111, v130
	v_mul_f32_e32 v112, v112, v238
	v_mul_f32_e32 v113, v113, v239
	v_cvt_pk_bf16_f32 v110, v110, v111
	v_cvt_pk_bf16_f32 v111, v112, v113
	global_store_dwordx2 v236, v[110:111], s[10:11] offset:96
	s_add_u32 s10, s10, 0x8000
	s_addc_u32 s11, s11, 0
	v_mul_f32_e32 v1, s12, v114
	v_mul_f32_e32 v130, s12, v115
	v_mul_f32_e32 v238, s12, v116
	v_mul_f32_e32 v239, s12, v117
	v_exp_f32_e32 v1, v1
	v_exp_f32_e32 v130, v130
	v_exp_f32_e32 v238, v238
	v_exp_f32_e32 v239, v239
	v_add_f32_e32 v1, 1.0, v1
	v_add_f32_e32 v130, 1.0, v130
	v_add_f32_e32 v238, 1.0, v238
	v_add_f32_e32 v239, 1.0, v239
	v_rcp_f32_e32 v1, v1
	v_rcp_f32_e32 v130, v130
	v_rcp_f32_e32 v238, v238
	v_rcp_f32_e32 v239, v239
	v_mul_f32_e32 v114, v114, v1
	v_mul_f32_e32 v115, v115, v130
	v_mul_f32_e32 v116, v116, v238
	v_mul_f32_e32 v117, v117, v239
	v_cvt_pk_bf16_f32 v114, v114, v115
	v_cvt_pk_bf16_f32 v115, v116, v117
	global_store_dwordx2 v236, v[114:115], s[10:11] offset:0
	v_mul_f32_e32 v1, s12, v118
	v_mul_f32_e32 v130, s12, v119
	v_mul_f32_e32 v238, s12, v120
	v_mul_f32_e32 v239, s12, v121
	v_exp_f32_e32 v1, v1
	v_exp_f32_e32 v130, v130
	v_exp_f32_e32 v238, v238
	v_exp_f32_e32 v239, v239
	v_add_f32_e32 v1, 1.0, v1
	v_add_f32_e32 v130, 1.0, v130
	v_add_f32_e32 v238, 1.0, v238
	v_add_f32_e32 v239, 1.0, v239
	v_rcp_f32_e32 v1, v1
	v_rcp_f32_e32 v130, v130
	v_rcp_f32_e32 v238, v238
	v_rcp_f32_e32 v239, v239
	v_mul_f32_e32 v118, v118, v1
	v_mul_f32_e32 v119, v119, v130
	v_mul_f32_e32 v120, v120, v238
	v_mul_f32_e32 v121, v121, v239
	v_cvt_pk_bf16_f32 v118, v118, v119
	v_cvt_pk_bf16_f32 v119, v120, v121
	global_store_dwordx2 v236, v[118:119], s[10:11] offset:32
	v_mul_f32_e32 v1, s12, v122
	v_mul_f32_e32 v130, s12, v123
	v_mul_f32_e32 v238, s12, v124
	v_mul_f32_e32 v239, s12, v125
	v_exp_f32_e32 v1, v1
	v_exp_f32_e32 v130, v130
	v_exp_f32_e32 v238, v238
	v_exp_f32_e32 v239, v239
	v_add_f32_e32 v1, 1.0, v1
	v_add_f32_e32 v130, 1.0, v130
	v_add_f32_e32 v238, 1.0, v238
	v_add_f32_e32 v239, 1.0, v239
	v_rcp_f32_e32 v1, v1
	v_rcp_f32_e32 v130, v130
	v_rcp_f32_e32 v238, v238
	v_rcp_f32_e32 v239, v239
	v_mul_f32_e32 v122, v122, v1
	v_mul_f32_e32 v123, v123, v130
	v_mul_f32_e32 v124, v124, v238
	v_mul_f32_e32 v125, v125, v239
	v_cvt_pk_bf16_f32 v122, v122, v123
	v_cvt_pk_bf16_f32 v123, v124, v125
	global_store_dwordx2 v236, v[122:123], s[10:11] offset:64
	v_mul_f32_e32 v1, s12, v126
	v_mul_f32_e32 v130, s12, v127
	v_mul_f32_e32 v238, s12, v128
	v_mul_f32_e32 v239, s12, v129
	v_exp_f32_e32 v1, v1
	v_exp_f32_e32 v130, v130
	v_exp_f32_e32 v238, v238
	v_exp_f32_e32 v239, v239
	v_add_f32_e32 v1, 1.0, v1
	v_add_f32_e32 v130, 1.0, v130
	v_add_f32_e32 v238, 1.0, v238
	v_add_f32_e32 v239, 1.0, v239
	v_rcp_f32_e32 v1, v1
	v_rcp_f32_e32 v130, v130
	v_rcp_f32_e32 v238, v238
	v_rcp_f32_e32 v239, v239
	v_mul_f32_e32 v126, v126, v1
	v_mul_f32_e32 v127, v127, v130
	v_mul_f32_e32 v128, v128, v238
	v_mul_f32_e32 v129, v129, v239
	v_cvt_pk_bf16_f32 v126, v126, v127
	v_cvt_pk_bf16_f32 v127, v128, v129
	global_store_dwordx2 v236, v[126:127], s[10:11] offset:96
	s_branch .La1_done
.La1_p:
	s_mul_i32 s51, s1, 0x220000
	s_add_u32 s52, s28, s51
	s_addc_u32 s53, s29, 0
	s_add_u32 s52, s52, 0x2000
	s_addc_u32 s53, s53, 0
	s_mov_b32 m0, s8
	s_nop 0
	global_load_lds_dwordx4 v200, s[4:5]
	s_add_u32 m0, s8, 0x400
	s_nop 0
	global_load_lds_dwordx4 v201, s[4:5]
	s_add_u32 m0, s8, 0x800
	s_nop 0
	global_load_lds_dwordx4 v202, s[4:5]
	s_add_u32 m0, s8, 0xc00
	s_nop 0
	global_load_lds_dwordx4 v203, s[4:5]
	s_mov_b32 m0, s9
	s_nop 0
	global_load_lds_dwordx4 v204, s[6:7]
	s_add_u32 m0, s9, 0x400
	s_nop 0
	global_load_lds_dwordx4 v205, s[6:7]
	s_add_u32 s4, s4, 0x80
	s_addc_u32 s5, s5, 0
	s_add_u32 s6, s6, 0x80
	s_addc_u32 s7, s7, 0
	s_add_u32 m0, s8, 0xc000
	s_nop 0
	global_load_lds_dwordx4 v200, s[4:5]
	s_add_u32 m0, s8, 0xc400
	s_nop 0
	global_load_lds_dwordx4 v201, s[4:5]
	s_add_u32 m0, s8, 0xc800
	s_nop 0
	global_load_lds_dwordx4 v202, s[4:5]
	s_add_u32 m0, s8, 0xcc00
	s_nop 0
	global_load_lds_dwordx4 v203, s[4:5]
	s_add_u32 m0, s9, 0xc000
	s_nop 0
	global_load_lds_dwordx4 v204, s[6:7]
	s_add_u32 m0, s9, 0xc400
	s_nop 0
	global_load_lds_dwordx4 v205, s[6:7]
	s_add_u32 s4, s4, 0x80
	s_addc_u32 s5, s5, 0
	s_add_u32 s6, s6, 0x80
	s_addc_u32 s7, s7, 0
	s_add_u32 m0, s8, 0x18000
	s_nop 0
	global_load_lds_dwordx4 v200, s[4:5]
	s_add_u32 m0, s8, 0x18400
	s_nop 0
	global_load_lds_dwordx4 v201, s[4:5]
	s_add_u32 m0, s8, 0x18800
	s_nop 0
	global_load_lds_dwordx4 v202, s[4:5]
	s_add_u32 m0, s8, 0x18c00
	s_nop 0
	global_load_lds_dwordx4 v203, s[4:5]
	s_add_u32 m0, s9, 0x18000
	s_nop 0
	global_load_lds_dwordx4 v204, s[6:7]
	s_add_u32 m0, s9, 0x18400
	s_nop 0
	global_load_lds_dwordx4 v205, s[6:7]
	s_add_u32 s4, s4, 0x80
	s_addc_u32 s5, s5, 0
	s_add_u32 s6, s6, 0x80
	s_addc_u32 s7, s7, 0
	s_waitcnt vmcnt(12)
	s_barrier
	ds_read_b128 v[136:139], v218 offset:0
	ds_read_b128 v[140:143], v218 offset:2048
	ds_read_b128 v[144:147], v218 offset:4096
	ds_read_b128 v[148:151], v218 offset:6144
	ds_read_b128 v[152:155], v230 offset:0
	ds_read_b128 v[156:159], v230 offset:2048
	ds_read_b128 v[160:163], v230 offset:4096
	ds_read_b128 v[164:167], v230 offset:6144
	s_waitcnt lgkmcnt(0)
	v_mfma_f32_16x16x32_bf16 v[2:5], v[152:155], v[136:139], 0
	ds_read_b128 v[168:171], v225 offset:0
	v_mfma_f32_16x16x32_bf16 v[6:9], v[156:159], v[136:139], 0
	ds_read_b128 v[172:175], v225 offset:2048
	v_mfma_f32_16x16x32_bf16 v[10:13], v[160:163], v[136:139], 0
	ds_read_b128 v[176:179], v225 offset:4096
	v_mfma_f32_16x16x32_bf16 v[14:17], v[164:167], v[136:139], 0
	ds_read_b128 v[180:183], v225 offset:6144
	v_mfma_f32_16x16x32_bf16 v[18:21], v[152:155], v[140:143], 0
	ds_read_b128 v[184:187], v233 offset:0
	v_mfma_f32_16x16x32_bf16 v[22:25], v[156:159], v[140:143], 0
	ds_read_b128 v[188:191], v233 offset:2048
	v_mfma_f32_16x16x32_bf16 v[26:29], v[160:163], v[140:143], 0
	ds_read_b128 v[192:195], v233 offset:4096
	v_mfma_f32_16x16x32_bf16 v[30:33], v[164:167], v[140:143], 0
	ds_read_b128 v[196:199], v233 offset:6144
	v_mfma_f32_16x16x32_bf16 v[34:37], v[152:155], v[144:147], 0
	v_mfma_f32_16x16x32_bf16 v[38:41], v[156:159], v[144:147], 0
	v_mfma_f32_16x16x32_bf16 v[42:45], v[160:163], v[144:147], 0
	v_mfma_f32_16x16x32_bf16 v[46:49], v[164:167], v[144:147], 0
	v_mfma_f32_16x16x32_bf16 v[50:53], v[152:155], v[148:151], 0
	v_mfma_f32_16x16x32_bf16 v[54:57], v[156:159], v[148:151], 0
	v_mfma_f32_16x16x32_bf16 v[58:61], v[160:163], v[148:151], 0
	v_mfma_f32_16x16x32_bf16 v[62:65], v[164:167], v[148:151], 0
	s_waitcnt vmcnt(6) lgkmcnt(0)
	s_barrier
	v_mfma_f32_16x16x32_bf16 v[2:5], v[184:187], v[168:171], v[2:5]
	ds_read_b128 v[136:139], v219 offset:0
	v_mfma_f32_16x16x32_bf16 v[6:9], v[188:191], v[168:171], v[6:9]
	ds_read_b128 v[140:143], v219 offset:2048
	v_mfma_f32_16x16x32_bf16 v[10:13], v[192:195], v[168:171], v[10:13]
	ds_read_b128 v[144:147], v219 offset:4096
	v_mfma_f32_16x16x32_bf16 v[14:17], v[196:199], v[168:171], v[14:17]
	ds_read_b128 v[148:151], v219 offset:6144
	v_mfma_f32_16x16x32_bf16 v[18:21], v[184:187], v[172:175], v[18:21]
	ds_read_b128 v[152:155], v231 offset:0
	v_mfma_f32_16x16x32_bf16 v[22:25], v[188:191], v[172:175], v[22:25]
	ds_read_b128 v[156:159], v231 offset:2048
	v_mfma_f32_16x16x32_bf16 v[26:29], v[192:195], v[172:175], v[26:29]
	ds_read_b128 v[160:163], v231 offset:4096
	v_mfma_f32_16x16x32_bf16 v[30:33], v[196:199], v[172:175], v[30:33]
	ds_read_b128 v[164:167], v231 offset:6144
	s_mov_b32 m0, s8
	v_mfma_f32_16x16x32_bf16 v[34:37], v[184:187], v[176:179], v[34:37]
	global_load_lds_dwordx4 v200, s[4:5]
	s_add_u32 m0, s8, 0x400
	v_mfma_f32_16x16x32_bf16 v[38:41], v[188:191], v[176:179], v[38:41]
	global_load_lds_dwordx4 v201, s[4:5]
	s_add_u32 m0, s8, 0x800
	v_mfma_f32_16x16x32_bf16 v[42:45], v[192:195], v[176:179], v[42:45]
	global_load_lds_dwordx4 v202, s[4:5]
	s_add_u32 m0, s8, 0xc00
	v_mfma_f32_16x16x32_bf16 v[46:49], v[196:199], v[176:179], v[46:49]
	global_load_lds_dwordx4 v203, s[4:5]
	s_mov_b32 m0, s9
	v_mfma_f32_16x16x32_bf16 v[50:53], v[184:187], v[180:183], v[50:53]
	global_load_lds_dwordx4 v204, s[6:7]
	s_add_u32 m0, s9, 0x400
	v_mfma_f32_16x16x32_bf16 v[54:57], v[188:191], v[180:183], v[54:57]
	global_load_lds_dwordx4 v205, s[6:7]
	v_mfma_f32_16x16x32_bf16 v[58:61], v[192:195], v[180:183], v[58:61]
	s_add_u32 s4, s4, 0x80
	s_addc_u32 s5, s5, 0
	v_mfma_f32_16x16x32_bf16 v[62:65], v[196:199], v[180:183], v[62:65]
	s_add_u32 s6, s6, 0x80
	s_addc_u32 s7, s7, 0
	s_waitcnt lgkmcnt(0)
	v_mfma_f32_16x16x32_bf16 v[2:5], v[152:155], v[136:139], v[2:5]
	ds_read_b128 v[168:171], v228 offset:0
	v_mfma_f32_16x16x32_bf16 v[6:9], v[156:159], v[136:139], v[6:9]
	ds_read_b128 v[172:175], v228 offset:2048
	v_mfma_f32_16x16x32_bf16 v[10:13], v[160:163], v[136:139], v[10:13]
	ds_read_b128 v[176:179], v228 offset:4096
	v_mfma_f32_16x16x32_bf16 v[14:17], v[164:167], v[136:139], v[14:17]
	ds_read_b128 v[180:183], v228 offset:6144
	v_mfma_f32_16x16x32_bf16 v[18:21], v[152:155], v[140:143], v[18:21]
	ds_read_b128 v[184:187], v234 offset:0
	v_mfma_f32_16x16x32_bf16 v[22:25], v[156:159], v[140:143], v[22:25]
	ds_read_b128 v[188:191], v234 offset:2048
	v_mfma_f32_16x16x32_bf16 v[26:29], v[160:163], v[140:143], v[26:29]
	ds_read_b128 v[192:195], v234 offset:4096
	v_mfma_f32_16x16x32_bf16 v[30:33], v[164:167], v[140:143], v[30:33]
	ds_read_b128 v[196:199], v234 offset:6144
	v_mfma_f32_16x16x32_bf16 v[34:37], v[152:155], v[144:147], v[34:37]
	v_mfma_f32_16x16x32_bf16 v[38:41], v[156:159], v[144:147], v[38:41]
	v_mfma_f32_16x16x32_bf16 v[42:45], v[160:163], v[144:147], v[42:45]
	v_mfma_f32_16x16x32_bf16 v[46:49], v[164:167], v[144:147], v[46:49]
	v_mfma_f32_16x16x32_bf16 v[50:53], v[152:155], v[148:151], v[50:53]
	v_mfma_f32_16x16x32_bf16 v[54:57], v[156:159], v[148:151], v[54:57]
	v_mfma_f32_16x16x32_bf16 v[58:61], v[160:163], v[148:151], v[58:61]
	v_mfma_f32_16x16x32_bf16 v[62:65], v[164:167], v[148:151], v[62:65]
	s_waitcnt vmcnt(6) lgkmcnt(0)
	s_barrier
	v_mfma_f32_16x16x32_bf16 v[2:5], v[184:187], v[168:171], v[2:5]
	ds_read_b128 v[136:139], v224 offset:0
	v_mfma_f32_16x16x32_bf16 v[6:9], v[188:191], v[168:171], v[6:9]
	ds_read_b128 v[140:143], v224 offset:2048
	v_mfma_f32_16x16x32_bf16 v[10:13], v[192:195], v[168:171], v[10:13]
	ds_read_b128 v[144:147], v224 offset:4096
	v_mfma_f32_16x16x32_bf16 v[14:17], v[196:199], v[168:171], v[14:17]
	ds_read_b128 v[148:151], v224 offset:6144
	v_mfma_f32_16x16x32_bf16 v[18:21], v[184:187], v[172:175], v[18:21]
	ds_read_b128 v[152:155], v232 offset:0
	v_mfma_f32_16x16x32_bf16 v[22:25], v[188:191], v[172:175], v[22:25]
	ds_read_b128 v[156:159], v232 offset:2048
	v_mfma_f32_16x16x32_bf16 v[26:29], v[192:195], v[172:175], v[26:29]
	ds_read_b128 v[160:163], v232 offset:4096
	v_mfma_f32_16x16x32_bf16 v[30:33], v[196:199], v[172:175], v[30:33]
	ds_read_b128 v[164:167], v232 offset:6144
	s_add_u32 m0, s8, 0xc000
	v_mfma_f32_16x16x32_bf16 v[34:37], v[184:187], v[176:179], v[34:37]
	global_load_lds_dwordx4 v200, s[4:5]
	s_add_u32 m0, s8, 0xc400
	v_mfma_f32_16x16x32_bf16 v[38:41], v[188:191], v[176:179], v[38:41]
	global_load_lds_dwordx4 v201, s[4:5]
	s_add_u32 m0, s8, 0xc800
	v_mfma_f32_16x16x32_bf16 v[42:45], v[192:195], v[176:179], v[42:45]
	global_load_lds_dwordx4 v202, s[4:5]
	s_add_u32 m0, s8, 0xcc00
	v_mfma_f32_16x16x32_bf16 v[46:49], v[196:199], v[176:179], v[46:49]
	global_load_lds_dwordx4 v203, s[4:5]
	s_add_u32 m0, s9, 0xc000
	v_mfma_f32_16x16x32_bf16 v[50:53], v[184:187], v[180:183], v[50:53]
	global_load_lds_dwordx4 v204, s[6:7]
	s_add_u32 m0, s9, 0xc400
	v_mfma_f32_16x16x32_bf16 v[54:57], v[188:191], v[180:183], v[54:57]
	global_load_lds_dwordx4 v205, s[6:7]
	v_mfma_f32_16x16x32_bf16 v[58:61], v[192:195], v[180:183], v[58:61]
	s_add_u32 s4, s4, 0x80
	s_addc_u32 s5, s5, 0
	v_mfma_f32_16x16x32_bf16 v[62:65], v[196:199], v[180:183], v[62:65]
	s_add_u32 s6, s6, 0x80
	s_addc_u32 s7, s7, 0
	s_waitcnt lgkmcnt(0)
	v_mfma_f32_16x16x32_bf16 v[2:5], v[152:155], v[136:139], v[2:5]
	ds_read_b128 v[168:171], v229 offset:0
	v_mfma_f32_16x16x32_bf16 v[6:9], v[156:159], v[136:139], v[6:9]
	ds_read_b128 v[172:175], v229 offset:2048
	v_mfma_f32_16x16x32_bf16 v[10:13], v[160:163], v[136:139], v[10:13]
	ds_read_b128 v[176:179], v229 offset:4096
	v_mfma_f32_16x16x32_bf16 v[14:17], v[164:167], v[136:139], v[14:17]
	ds_read_b128 v[180:183], v229 offset:6144
	v_mfma_f32_16x16x32_bf16 v[18:21], v[152:155], v[140:143], v[18:21]
	ds_read_b128 v[184:187], v235 offset:0
	v_mfma_f32_16x16x32_bf16 v[22:25], v[156:159], v[140:143], v[22:25]
	ds_read_b128 v[188:191], v235 offset:2048
	v_mfma_f32_16x16x32_bf16 v[26:29], v[160:163], v[140:143], v[26:29]
	ds_read_b128 v[192:195], v235 offset:4096
	v_mfma_f32_16x16x32_bf16 v[30:33], v[164:167], v[140:143], v[30:33]
	ds_read_b128 v[196:199], v235 offset:6144
	v_mfma_f32_16x16x32_bf16 v[34:37], v[152:155], v[144:147], v[34:37]
	v_mfma_f32_16x16x32_bf16 v[38:41], v[156:159], v[144:147], v[38:41]
	v_mfma_f32_16x16x32_bf16 v[42:45], v[160:163], v[144:147], v[42:45]
	v_mfma_f32_16x16x32_bf16 v[46:49], v[164:167], v[144:147], v[46:49]
	v_mfma_f32_16x16x32_bf16 v[50:53], v[152:155], v[148:151], v[50:53]
	v_mfma_f32_16x16x32_bf16 v[54:57], v[156:159], v[148:151], v[54:57]
	v_mfma_f32_16x16x32_bf16 v[58:61], v[160:163], v[148:151], v[58:61]
	v_mfma_f32_16x16x32_bf16 v[62:65], v[164:167], v[148:151], v[62:65]
	s_waitcnt vmcnt(6) lgkmcnt(0)
	s_barrier
	v_mfma_f32_16x16x32_bf16 v[2:5], v[184:187], v[168:171], v[2:5]
	ds_read_b128 v[136:139], v218 offset:0
	v_mfma_f32_16x16x32_bf16 v[6:9], v[188:191], v[168:171], v[6:9]
	ds_read_b128 v[140:143], v218 offset:2048
	v_mfma_f32_16x16x32_bf16 v[10:13], v[192:195], v[168:171], v[10:13]
	ds_read_b128 v[144:147], v218 offset:4096
	v_mfma_f32_16x16x32_bf16 v[14:17], v[196:199], v[168:171], v[14:17]
	ds_read_b128 v[148:151], v218 offset:6144
	v_mfma_f32_16x16x32_bf16 v[18:21], v[184:187], v[172:175], v[18:21]
	ds_read_b128 v[152:155], v230 offset:0
	v_mfma_f32_16x16x32_bf16 v[22:25], v[188:191], v[172:175], v[22:25]
	ds_read_b128 v[156:159], v230 offset:2048
	v_mfma_f32_16x16x32_bf16 v[26:29], v[192:195], v[172:175], v[26:29]
	ds_read_b128 v[160:163], v230 offset:4096
	v_mfma_f32_16x16x32_bf16 v[30:33], v[196:199], v[172:175], v[30:33]
	ds_read_b128 v[164:167], v230 offset:6144
	s_add_u32 m0, s8, 0x18000
	v_mfma_f32_16x16x32_bf16 v[34:37], v[184:187], v[176:179], v[34:37]
	global_load_lds_dwordx4 v200, s[4:5]
	s_add_u32 m0, s8, 0x18400
	v_mfma_f32_16x16x32_bf16 v[38:41], v[188:191], v[176:179], v[38:41]
	global_load_lds_dwordx4 v201, s[4:5]
	s_add_u32 m0, s8, 0x18800
	v_mfma_f32_16x16x32_bf16 v[42:45], v[192:195], v[176:179], v[42:45]
	global_load_lds_dwordx4 v202, s[4:5]
	s_add_u32 m0, s8, 0x18c00
	v_mfma_f32_16x16x32_bf16 v[46:49], v[196:199], v[176:179], v[46:49]
	global_load_lds_dwordx4 v203, s[4:5]
	s_add_u32 m0, s9, 0x18000
	v_mfma_f32_16x16x32_bf16 v[50:53], v[184:187], v[180:183], v[50:53]
	global_load_lds_dwordx4 v204, s[6:7]
	s_add_u32 m0, s9, 0x18400
	v_mfma_f32_16x16x32_bf16 v[54:57], v[188:191], v[180:183], v[54:57]
	global_load_lds_dwordx4 v205, s[6:7]
	v_mfma_f32_16x16x32_bf16 v[58:61], v[192:195], v[180:183], v[58:61]
	s_add_u32 s4, s4, 0x80
	s_addc_u32 s5, s5, 0
	v_mfma_f32_16x16x32_bf16 v[62:65], v[196:199], v[180:183], v[62:65]
	s_add_u32 s6, s6, 0x80
	s_addc_u32 s7, s7, 0
	s_waitcnt lgkmcnt(0)
	v_mfma_f32_16x16x32_bf16 v[2:5], v[152:155], v[136:139], v[2:5]
	ds_read_b128 v[168:171], v225 offset:0
	v_mfma_f32_16x16x32_bf16 v[6:9], v[156:159], v[136:139], v[6:9]
	ds_read_b128 v[172:175], v225 offset:2048
	v_mfma_f32_16x16x32_bf16 v[10:13], v[160:163], v[136:139], v[10:13]
	ds_read_b128 v[176:179], v225 offset:4096
	v_mfma_f32_16x16x32_bf16 v[14:17], v[164:167], v[136:139], v[14:17]
	ds_read_b128 v[180:183], v225 offset:6144
	v_mfma_f32_16x16x32_bf16 v[18:21], v[152:155], v[140:143], v[18:21]
	ds_read_b128 v[184:187], v233 offset:0
	v_mfma_f32_16x16x32_bf16 v[22:25], v[156:159], v[140:143], v[22:25]
	ds_read_b128 v[188:191], v233 offset:2048
	v_mfma_f32_16x16x32_bf16 v[26:29], v[160:163], v[140:143], v[26:29]
	ds_read_b128 v[192:195], v233 offset:4096
	v_mfma_f32_16x16x32_bf16 v[30:33], v[164:167], v[140:143], v[30:33]
	ds_read_b128 v[196:199], v233 offset:6144
	v_mfma_f32_16x16x32_bf16 v[34:37], v[152:155], v[144:147], v[34:37]
	v_mfma_f32_16x16x32_bf16 v[38:41], v[156:159], v[144:147], v[38:41]
	v_mfma_f32_16x16x32_bf16 v[42:45], v[160:163], v[144:147], v[42:45]
	v_mfma_f32_16x16x32_bf16 v[46:49], v[164:167], v[144:147], v[46:49]
	v_mfma_f32_16x16x32_bf16 v[50:53], v[152:155], v[148:151], v[50:53]
	v_mfma_f32_16x16x32_bf16 v[54:57], v[156:159], v[148:151], v[54:57]
	v_mfma_f32_16x16x32_bf16 v[58:61], v[160:163], v[148:151], v[58:61]
	v_mfma_f32_16x16x32_bf16 v[62:65], v[164:167], v[148:151], v[62:65]
	s_waitcnt vmcnt(6) lgkmcnt(0)
	s_barrier
	v_mfma_f32_16x16x32_bf16 v[2:5], v[184:187], v[168:171], v[2:5]
	ds_read_b128 v[136:139], v219 offset:0
	v_mfma_f32_16x16x32_bf16 v[6:9], v[188:191], v[168:171], v[6:9]
	ds_read_b128 v[140:143], v219 offset:2048
	v_mfma_f32_16x16x32_bf16 v[10:13], v[192:195], v[168:171], v[10:13]
	ds_read_b128 v[144:147], v219 offset:4096
	v_mfma_f32_16x16x32_bf16 v[14:17], v[196:199], v[168:171], v[14:17]
	ds_read_b128 v[148:151], v219 offset:6144
	v_mfma_f32_16x16x32_bf16 v[18:21], v[184:187], v[172:175], v[18:21]
	ds_read_b128 v[152:155], v231 offset:0
	v_mfma_f32_16x16x32_bf16 v[22:25], v[188:191], v[172:175], v[22:25]
	ds_read_b128 v[156:159], v231 offset:2048
	v_mfma_f32_16x16x32_bf16 v[26:29], v[192:195], v[172:175], v[26:29]
	ds_read_b128 v[160:163], v231 offset:4096
	v_mfma_f32_16x16x32_bf16 v[30:33], v[196:199], v[172:175], v[30:33]
	ds_read_b128 v[164:167], v231 offset:6144
	s_mov_b32 m0, s8
	v_mfma_f32_16x16x32_bf16 v[34:37], v[184:187], v[176:179], v[34:37]
	global_load_lds_dwordx4 v200, s[4:5]
	s_add_u32 m0, s8, 0x400
	v_mfma_f32_16x16x32_bf16 v[38:41], v[188:191], v[176:179], v[38:41]
	global_load_lds_dwordx4 v201, s[4:5]
	s_add_u32 m0, s8, 0x800
	v_mfma_f32_16x16x32_bf16 v[42:45], v[192:195], v[176:179], v[42:45]
	global_load_lds_dwordx4 v202, s[4:5]
	s_add_u32 m0, s8, 0xc00
	v_mfma_f32_16x16x32_bf16 v[46:49], v[196:199], v[176:179], v[46:49]
	global_load_lds_dwordx4 v203, s[4:5]
	s_mov_b32 m0, s9
	v_mfma_f32_16x16x32_bf16 v[50:53], v[184:187], v[180:183], v[50:53]
	global_load_lds_dwordx4 v204, s[6:7]
	s_add_u32 m0, s9, 0x400
	v_mfma_f32_16x16x32_bf16 v[54:57], v[188:191], v[180:183], v[54:57]
	global_load_lds_dwordx4 v205, s[6:7]
	v_mfma_f32_16x16x32_bf16 v[58:61], v[192:195], v[180:183], v[58:61]
	s_add_u32 s4, s4, 0x80
	s_addc_u32 s5, s5, 0
	v_mfma_f32_16x16x32_bf16 v[62:65], v[196:199], v[180:183], v[62:65]
	s_add_u32 s6, s6, 0x80
	s_addc_u32 s7, s7, 0
	s_waitcnt lgkmcnt(0)
	v_mfma_f32_16x16x32_bf16 v[2:5], v[152:155], v[136:139], v[2:5]
	ds_read_b128 v[168:171], v228 offset:0
	v_mfma_f32_16x16x32_bf16 v[6:9], v[156:159], v[136:139], v[6:9]
	ds_read_b128 v[172:175], v228 offset:2048
	v_mfma_f32_16x16x32_bf16 v[10:13], v[160:163], v[136:139], v[10:13]
	ds_read_b128 v[176:179], v228 offset:4096
	v_mfma_f32_16x16x32_bf16 v[14:17], v[164:167], v[136:139], v[14:17]
	ds_read_b128 v[180:183], v228 offset:6144
	v_mfma_f32_16x16x32_bf16 v[18:21], v[152:155], v[140:143], v[18:21]
	ds_read_b128 v[184:187], v234 offset:0
	v_mfma_f32_16x16x32_bf16 v[22:25], v[156:159], v[140:143], v[22:25]
	ds_read_b128 v[188:191], v234 offset:2048
	v_mfma_f32_16x16x32_bf16 v[26:29], v[160:163], v[140:143], v[26:29]
	ds_read_b128 v[192:195], v234 offset:4096
	v_mfma_f32_16x16x32_bf16 v[30:33], v[164:167], v[140:143], v[30:33]
	ds_read_b128 v[196:199], v234 offset:6144
	v_mfma_f32_16x16x32_bf16 v[34:37], v[152:155], v[144:147], v[34:37]
	v_mfma_f32_16x16x32_bf16 v[38:41], v[156:159], v[144:147], v[38:41]
	v_mfma_f32_16x16x32_bf16 v[42:45], v[160:163], v[144:147], v[42:45]
	v_mfma_f32_16x16x32_bf16 v[46:49], v[164:167], v[144:147], v[46:49]
	v_mfma_f32_16x16x32_bf16 v[50:53], v[152:155], v[148:151], v[50:53]
	v_mfma_f32_16x16x32_bf16 v[54:57], v[156:159], v[148:151], v[54:57]
	v_mfma_f32_16x16x32_bf16 v[58:61], v[160:163], v[148:151], v[58:61]
	v_mfma_f32_16x16x32_bf16 v[62:65], v[164:167], v[148:151], v[62:65]
	s_waitcnt vmcnt(6) lgkmcnt(0)
	s_barrier
	v_mfma_f32_16x16x32_bf16 v[2:5], v[184:187], v[168:171], v[2:5]
	ds_read_b128 v[136:139], v224 offset:0
	v_mfma_f32_16x16x32_bf16 v[6:9], v[188:191], v[168:171], v[6:9]
	ds_read_b128 v[140:143], v224 offset:2048
	v_mfma_f32_16x16x32_bf16 v[10:13], v[192:195], v[168:171], v[10:13]
	ds_read_b128 v[144:147], v224 offset:4096
	v_mfma_f32_16x16x32_bf16 v[14:17], v[196:199], v[168:171], v[14:17]
	ds_read_b128 v[148:151], v224 offset:6144
	v_mfma_f32_16x16x32_bf16 v[18:21], v[184:187], v[172:175], v[18:21]
	ds_read_b128 v[152:155], v232 offset:0
	v_mfma_f32_16x16x32_bf16 v[22:25], v[188:191], v[172:175], v[22:25]
	ds_read_b128 v[156:159], v232 offset:2048
	v_mfma_f32_16x16x32_bf16 v[26:29], v[192:195], v[172:175], v[26:29]
	ds_read_b128 v[160:163], v232 offset:4096
	v_mfma_f32_16x16x32_bf16 v[30:33], v[196:199], v[172:175], v[30:33]
	ds_read_b128 v[164:167], v232 offset:6144
	s_add_u32 m0, s8, 0xc000
	v_mfma_f32_16x16x32_bf16 v[34:37], v[184:187], v[176:179], v[34:37]
	global_load_lds_dwordx4 v200, s[4:5]
	s_add_u32 m0, s8, 0xc400
	v_mfma_f32_16x16x32_bf16 v[38:41], v[188:191], v[176:179], v[38:41]
	global_load_lds_dwordx4 v201, s[4:5]
	s_add_u32 m0, s8, 0xc800
	v_mfma_f32_16x16x32_bf16 v[42:45], v[192:195], v[176:179], v[42:45]
	global_load_lds_dwordx4 v202, s[4:5]
	s_add_u32 m0, s8, 0xcc00
	v_mfma_f32_16x16x32_bf16 v[46:49], v[196:199], v[176:179], v[46:49]
	global_load_lds_dwordx4 v203, s[4:5]
	s_add_u32 m0, s9, 0xc000
	v_mfma_f32_16x16x32_bf16 v[50:53], v[184:187], v[180:183], v[50:53]
	global_load_lds_dwordx4 v204, s[6:7]
	s_add_u32 m0, s9, 0xc400
	v_mfma_f32_16x16x32_bf16 v[54:57], v[188:191], v[180:183], v[54:57]
	global_load_lds_dwordx4 v205, s[6:7]
	v_mfma_f32_16x16x32_bf16 v[58:61], v[192:195], v[180:183], v[58:61]
	s_add_u32 s4, s4, 0x80
	s_addc_u32 s5, s5, 0
	v_mfma_f32_16x16x32_bf16 v[62:65], v[196:199], v[180:183], v[62:65]
	s_add_u32 s6, s6, 0x80
	s_addc_u32 s7, s7, 0
	s_waitcnt lgkmcnt(0)
	v_mfma_f32_16x16x32_bf16 v[2:5], v[152:155], v[136:139], v[2:5]
	ds_read_b128 v[168:171], v229 offset:0
	v_mfma_f32_16x16x32_bf16 v[6:9], v[156:159], v[136:139], v[6:9]
	ds_read_b128 v[172:175], v229 offset:2048
	v_mfma_f32_16x16x32_bf16 v[10:13], v[160:163], v[136:139], v[10:13]
	ds_read_b128 v[176:179], v229 offset:4096
	v_mfma_f32_16x16x32_bf16 v[14:17], v[164:167], v[136:139], v[14:17]
	ds_read_b128 v[180:183], v229 offset:6144
	v_mfma_f32_16x16x32_bf16 v[18:21], v[152:155], v[140:143], v[18:21]
	ds_read_b128 v[184:187], v235 offset:0
	v_mfma_f32_16x16x32_bf16 v[22:25], v[156:159], v[140:143], v[22:25]
	ds_read_b128 v[188:191], v235 offset:2048
	v_mfma_f32_16x16x32_bf16 v[26:29], v[160:163], v[140:143], v[26:29]
	ds_read_b128 v[192:195], v235 offset:4096
	v_mfma_f32_16x16x32_bf16 v[30:33], v[164:167], v[140:143], v[30:33]
	ds_read_b128 v[196:199], v235 offset:6144
	v_mfma_f32_16x16x32_bf16 v[34:37], v[152:155], v[144:147], v[34:37]
	v_mfma_f32_16x16x32_bf16 v[38:41], v[156:159], v[144:147], v[38:41]
	v_mfma_f32_16x16x32_bf16 v[42:45], v[160:163], v[144:147], v[42:45]
	v_mfma_f32_16x16x32_bf16 v[46:49], v[164:167], v[144:147], v[46:49]
	v_mfma_f32_16x16x32_bf16 v[50:53], v[152:155], v[148:151], v[50:53]
	v_mfma_f32_16x16x32_bf16 v[54:57], v[156:159], v[148:151], v[54:57]
	v_mfma_f32_16x16x32_bf16 v[58:61], v[160:163], v[148:151], v[58:61]
	v_mfma_f32_16x16x32_bf16 v[62:65], v[164:167], v[148:151], v[62:65]
	s_waitcnt vmcnt(6) lgkmcnt(0)
	s_barrier
	v_mfma_f32_16x16x32_bf16 v[2:5], v[184:187], v[168:171], v[2:5]
	ds_read_b128 v[136:139], v218 offset:0
	v_mfma_f32_16x16x32_bf16 v[6:9], v[188:191], v[168:171], v[6:9]
	ds_read_b128 v[140:143], v218 offset:2048
	v_mfma_f32_16x16x32_bf16 v[10:13], v[192:195], v[168:171], v[10:13]
	ds_read_b128 v[144:147], v218 offset:4096
	v_mfma_f32_16x16x32_bf16 v[14:17], v[196:199], v[168:171], v[14:17]
	ds_read_b128 v[148:151], v218 offset:6144
	v_mfma_f32_16x16x32_bf16 v[18:21], v[184:187], v[172:175], v[18:21]
	ds_read_b128 v[152:155], v230 offset:0
	v_mfma_f32_16x16x32_bf16 v[22:25], v[188:191], v[172:175], v[22:25]
	ds_read_b128 v[156:159], v230 offset:2048
	v_mfma_f32_16x16x32_bf16 v[26:29], v[192:195], v[172:175], v[26:29]
	ds_read_b128 v[160:163], v230 offset:4096
	v_mfma_f32_16x16x32_bf16 v[30:33], v[196:199], v[172:175], v[30:33]
	ds_read_b128 v[164:167], v230 offset:6144
	s_add_u32 m0, s8, 0x18000
	v_mfma_f32_16x16x32_bf16 v[34:37], v[184:187], v[176:179], v[34:37]
	global_load_lds_dwordx4 v200, s[4:5]
	s_add_u32 m0, s8, 0x18400
	v_mfma_f32_16x16x32_bf16 v[38:41], v[188:191], v[176:179], v[38:41]
	global_load_lds_dwordx4 v201, s[4:5]
	s_add_u32 m0, s8, 0x18800
	v_mfma_f32_16x16x32_bf16 v[42:45], v[192:195], v[176:179], v[42:45]
	global_load_lds_dwordx4 v202, s[4:5]
	s_add_u32 m0, s8, 0x18c00
	v_mfma_f32_16x16x32_bf16 v[46:49], v[196:199], v[176:179], v[46:49]
	global_load_lds_dwordx4 v203, s[4:5]
	s_add_u32 m0, s9, 0x18000
	v_mfma_f32_16x16x32_bf16 v[50:53], v[184:187], v[180:183], v[50:53]
	global_load_lds_dwordx4 v204, s[6:7]
	s_add_u32 m0, s9, 0x18400
	v_mfma_f32_16x16x32_bf16 v[54:57], v[188:191], v[180:183], v[54:57]
	global_load_lds_dwordx4 v205, s[6:7]
	v_mfma_f32_16x16x32_bf16 v[58:61], v[192:195], v[180:183], v[58:61]
	s_add_u32 s4, s4, 0x80
	s_addc_u32 s5, s5, 0
	v_mfma_f32_16x16x32_bf16 v[62:65], v[196:199], v[180:183], v[62:65]
	s_add_u32 s6, s6, 0x80
	s_addc_u32 s7, s7, 0
	s_waitcnt lgkmcnt(0)
	v_mfma_f32_16x16x32_bf16 v[2:5], v[152:155], v[136:139], v[2:5]
	ds_read_b128 v[168:171], v225 offset:0
	v_mfma_f32_16x16x32_bf16 v[6:9], v[156:159], v[136:139], v[6:9]
	ds_read_b128 v[172:175], v225 offset:2048
	v_mfma_f32_16x16x32_bf16 v[10:13], v[160:163], v[136:139], v[10:13]
	ds_read_b128 v[176:179], v225 offset:4096
	v_mfma_f32_16x16x32_bf16 v[14:17], v[164:167], v[136:139], v[14:17]
	ds_read_b128 v[180:183], v225 offset:6144
	v_mfma_f32_16x16x32_bf16 v[18:21], v[152:155], v[140:143], v[18:21]
	ds_read_b128 v[184:187], v233 offset:0
	v_mfma_f32_16x16x32_bf16 v[22:25], v[156:159], v[140:143], v[22:25]
	ds_read_b128 v[188:191], v233 offset:2048
	v_mfma_f32_16x16x32_bf16 v[26:29], v[160:163], v[140:143], v[26:29]
	ds_read_b128 v[192:195], v233 offset:4096
	v_mfma_f32_16x16x32_bf16 v[30:33], v[164:167], v[140:143], v[30:33]
	ds_read_b128 v[196:199], v233 offset:6144
	v_mfma_f32_16x16x32_bf16 v[34:37], v[152:155], v[144:147], v[34:37]
	v_mfma_f32_16x16x32_bf16 v[38:41], v[156:159], v[144:147], v[38:41]
	v_mfma_f32_16x16x32_bf16 v[42:45], v[160:163], v[144:147], v[42:45]
	v_mfma_f32_16x16x32_bf16 v[46:49], v[164:167], v[144:147], v[46:49]
	v_mfma_f32_16x16x32_bf16 v[50:53], v[152:155], v[148:151], v[50:53]
	v_mfma_f32_16x16x32_bf16 v[54:57], v[156:159], v[148:151], v[54:57]
	v_mfma_f32_16x16x32_bf16 v[58:61], v[160:163], v[148:151], v[58:61]
	v_mfma_f32_16x16x32_bf16 v[62:65], v[164:167], v[148:151], v[62:65]
	s_waitcnt vmcnt(6) lgkmcnt(0)
	s_barrier
	v_mfma_f32_16x16x32_bf16 v[2:5], v[184:187], v[168:171], v[2:5]
	ds_read_b128 v[136:139], v219 offset:0
	v_mfma_f32_16x16x32_bf16 v[6:9], v[188:191], v[168:171], v[6:9]
	ds_read_b128 v[140:143], v219 offset:2048
	v_mfma_f32_16x16x32_bf16 v[10:13], v[192:195], v[168:171], v[10:13]
	ds_read_b128 v[144:147], v219 offset:4096
	v_mfma_f32_16x16x32_bf16 v[14:17], v[196:199], v[168:171], v[14:17]
	ds_read_b128 v[148:151], v219 offset:6144
	v_mfma_f32_16x16x32_bf16 v[18:21], v[184:187], v[172:175], v[18:21]
	ds_read_b128 v[152:155], v231 offset:0
	v_mfma_f32_16x16x32_bf16 v[22:25], v[188:191], v[172:175], v[22:25]
	ds_read_b128 v[156:159], v231 offset:2048
	v_mfma_f32_16x16x32_bf16 v[26:29], v[192:195], v[172:175], v[26:29]
	ds_read_b128 v[160:163], v231 offset:4096
	v_mfma_f32_16x16x32_bf16 v[30:33], v[196:199], v[172:175], v[30:33]
	ds_read_b128 v[164:167], v231 offset:6144
	s_mov_b32 m0, s8
	v_mfma_f32_16x16x32_bf16 v[34:37], v[184:187], v[176:179], v[34:37]
	global_load_lds_dwordx4 v200, s[4:5]
	s_add_u32 m0, s8, 0x400
	v_mfma_f32_16x16x32_bf16 v[38:41], v[188:191], v[176:179], v[38:41]
	global_load_lds_dwordx4 v201, s[4:5]
	s_add_u32 m0, s8, 0x800
	v_mfma_f32_16x16x32_bf16 v[42:45], v[192:195], v[176:179], v[42:45]
	global_load_lds_dwordx4 v202, s[4:5]
	s_add_u32 m0, s8, 0xc00
	v_mfma_f32_16x16x32_bf16 v[46:49], v[196:199], v[176:179], v[46:49]
	global_load_lds_dwordx4 v203, s[4:5]
	s_mov_b32 m0, s9
	v_mfma_f32_16x16x32_bf16 v[50:53], v[184:187], v[180:183], v[50:53]
	global_load_lds_dwordx4 v204, s[6:7]
	s_add_u32 m0, s9, 0x400
	v_mfma_f32_16x16x32_bf16 v[54:57], v[188:191], v[180:183], v[54:57]
	global_load_lds_dwordx4 v205, s[6:7]
	v_mfma_f32_16x16x32_bf16 v[58:61], v[192:195], v[180:183], v[58:61]
	s_add_u32 s4, s4, 0x80
	s_addc_u32 s5, s5, 0
	v_mfma_f32_16x16x32_bf16 v[62:65], v[196:199], v[180:183], v[62:65]
	s_add_u32 s6, s6, 0x80
	s_addc_u32 s7, s7, 0
	s_waitcnt lgkmcnt(0)
	v_mfma_f32_16x16x32_bf16 v[2:5], v[152:155], v[136:139], v[2:5]
	ds_read_b128 v[168:171], v228 offset:0
	v_mfma_f32_16x16x32_bf16 v[6:9], v[156:159], v[136:139], v[6:9]
	ds_read_b128 v[172:175], v228 offset:2048
	v_mfma_f32_16x16x32_bf16 v[10:13], v[160:163], v[136:139], v[10:13]
	ds_read_b128 v[176:179], v228 offset:4096
	v_mfma_f32_16x16x32_bf16 v[14:17], v[164:167], v[136:139], v[14:17]
	ds_read_b128 v[180:183], v228 offset:6144
	v_mfma_f32_16x16x32_bf16 v[18:21], v[152:155], v[140:143], v[18:21]
	ds_read_b128 v[184:187], v234 offset:0
	v_mfma_f32_16x16x32_bf16 v[22:25], v[156:159], v[140:143], v[22:25]
	ds_read_b128 v[188:191], v234 offset:2048
	v_mfma_f32_16x16x32_bf16 v[26:29], v[160:163], v[140:143], v[26:29]
	ds_read_b128 v[192:195], v234 offset:4096
	v_mfma_f32_16x16x32_bf16 v[30:33], v[164:167], v[140:143], v[30:33]
	ds_read_b128 v[196:199], v234 offset:6144
	v_mfma_f32_16x16x32_bf16 v[34:37], v[152:155], v[144:147], v[34:37]
	v_mfma_f32_16x16x32_bf16 v[38:41], v[156:159], v[144:147], v[38:41]
	v_mfma_f32_16x16x32_bf16 v[42:45], v[160:163], v[144:147], v[42:45]
	v_mfma_f32_16x16x32_bf16 v[46:49], v[164:167], v[144:147], v[46:49]
	v_mfma_f32_16x16x32_bf16 v[50:53], v[152:155], v[148:151], v[50:53]
	v_mfma_f32_16x16x32_bf16 v[54:57], v[156:159], v[148:151], v[54:57]
	v_mfma_f32_16x16x32_bf16 v[58:61], v[160:163], v[148:151], v[58:61]
	v_mfma_f32_16x16x32_bf16 v[62:65], v[164:167], v[148:151], v[62:65]
	s_waitcnt vmcnt(6) lgkmcnt(0)
	s_barrier
	v_mfma_f32_16x16x32_bf16 v[2:5], v[184:187], v[168:171], v[2:5]
	ds_read_b128 v[136:139], v224 offset:0
	v_mfma_f32_16x16x32_bf16 v[6:9], v[188:191], v[168:171], v[6:9]
	ds_read_b128 v[140:143], v224 offset:2048
	v_mfma_f32_16x16x32_bf16 v[10:13], v[192:195], v[168:171], v[10:13]
	ds_read_b128 v[144:147], v224 offset:4096
	v_mfma_f32_16x16x32_bf16 v[14:17], v[196:199], v[168:171], v[14:17]
	ds_read_b128 v[148:151], v224 offset:6144
	v_mfma_f32_16x16x32_bf16 v[18:21], v[184:187], v[172:175], v[18:21]
	ds_read_b128 v[152:155], v232 offset:0
	v_mfma_f32_16x16x32_bf16 v[22:25], v[188:191], v[172:175], v[22:25]
	ds_read_b128 v[156:159], v232 offset:2048
	v_mfma_f32_16x16x32_bf16 v[26:29], v[192:195], v[172:175], v[26:29]
	ds_read_b128 v[160:163], v232 offset:4096
	v_mfma_f32_16x16x32_bf16 v[30:33], v[196:199], v[172:175], v[30:33]
	ds_read_b128 v[164:167], v232 offset:6144
	s_add_u32 m0, s8, 0xc000
	v_mfma_f32_16x16x32_bf16 v[34:37], v[184:187], v[176:179], v[34:37]
	global_load_lds_dwordx4 v200, s[4:5]
	s_add_u32 m0, s8, 0xc400
	v_mfma_f32_16x16x32_bf16 v[38:41], v[188:191], v[176:179], v[38:41]
	global_load_lds_dwordx4 v201, s[4:5]
	s_add_u32 m0, s8, 0xc800
	v_mfma_f32_16x16x32_bf16 v[42:45], v[192:195], v[176:179], v[42:45]
	global_load_lds_dwordx4 v202, s[4:5]
	s_add_u32 m0, s8, 0xcc00
	v_mfma_f32_16x16x32_bf16 v[46:49], v[196:199], v[176:179], v[46:49]
	global_load_lds_dwordx4 v203, s[4:5]
	s_add_u32 m0, s9, 0xc000
	v_mfma_f32_16x16x32_bf16 v[50:53], v[184:187], v[180:183], v[50:53]
	global_load_lds_dwordx4 v204, s[6:7]
	s_add_u32 m0, s9, 0xc400
	v_mfma_f32_16x16x32_bf16 v[54:57], v[188:191], v[180:183], v[54:57]
	global_load_lds_dwordx4 v205, s[6:7]
	v_mfma_f32_16x16x32_bf16 v[58:61], v[192:195], v[180:183], v[58:61]
	s_add_u32 s4, s4, 0x80
	s_addc_u32 s5, s5, 0
	v_mfma_f32_16x16x32_bf16 v[62:65], v[196:199], v[180:183], v[62:65]
	s_add_u32 s6, s6, 0x80
	s_addc_u32 s7, s7, 0
	s_waitcnt lgkmcnt(0)
	v_mfma_f32_16x16x32_bf16 v[2:5], v[152:155], v[136:139], v[2:5]
	ds_read_b128 v[168:171], v229 offset:0
	v_mfma_f32_16x16x32_bf16 v[6:9], v[156:159], v[136:139], v[6:9]
	ds_read_b128 v[172:175], v229 offset:2048
	v_mfma_f32_16x16x32_bf16 v[10:13], v[160:163], v[136:139], v[10:13]
	ds_read_b128 v[176:179], v229 offset:4096
	v_mfma_f32_16x16x32_bf16 v[14:17], v[164:167], v[136:139], v[14:17]
	ds_read_b128 v[180:183], v229 offset:6144
	v_mfma_f32_16x16x32_bf16 v[18:21], v[152:155], v[140:143], v[18:21]
	ds_read_b128 v[184:187], v235 offset:0
	v_mfma_f32_16x16x32_bf16 v[22:25], v[156:159], v[140:143], v[22:25]
	ds_read_b128 v[188:191], v235 offset:2048
	v_mfma_f32_16x16x32_bf16 v[26:29], v[160:163], v[140:143], v[26:29]
	ds_read_b128 v[192:195], v235 offset:4096
	v_mfma_f32_16x16x32_bf16 v[30:33], v[164:167], v[140:143], v[30:33]
	ds_read_b128 v[196:199], v235 offset:6144
	v_mfma_f32_16x16x32_bf16 v[34:37], v[152:155], v[144:147], v[34:37]
	v_mfma_f32_16x16x32_bf16 v[38:41], v[156:159], v[144:147], v[38:41]
	v_mfma_f32_16x16x32_bf16 v[42:45], v[160:163], v[144:147], v[42:45]
	v_mfma_f32_16x16x32_bf16 v[46:49], v[164:167], v[144:147], v[46:49]
	v_mfma_f32_16x16x32_bf16 v[50:53], v[152:155], v[148:151], v[50:53]
	v_mfma_f32_16x16x32_bf16 v[54:57], v[156:159], v[148:151], v[54:57]
	v_mfma_f32_16x16x32_bf16 v[58:61], v[160:163], v[148:151], v[58:61]
	v_mfma_f32_16x16x32_bf16 v[62:65], v[164:167], v[148:151], v[62:65]
	s_waitcnt vmcnt(6) lgkmcnt(0)
	s_barrier
	v_mfma_f32_16x16x32_bf16 v[2:5], v[184:187], v[168:171], v[2:5]
	ds_read_b128 v[136:139], v218 offset:0
	v_mfma_f32_16x16x32_bf16 v[6:9], v[188:191], v[168:171], v[6:9]
	ds_read_b128 v[140:143], v218 offset:2048
	v_mfma_f32_16x16x32_bf16 v[10:13], v[192:195], v[168:171], v[10:13]
	ds_read_b128 v[144:147], v218 offset:4096
	v_mfma_f32_16x16x32_bf16 v[14:17], v[196:199], v[168:171], v[14:17]
	ds_read_b128 v[148:151], v218 offset:6144
	v_mfma_f32_16x16x32_bf16 v[18:21], v[184:187], v[172:175], v[18:21]
	ds_read_b128 v[152:155], v230 offset:0
	v_mfma_f32_16x16x32_bf16 v[22:25], v[188:191], v[172:175], v[22:25]
	ds_read_b128 v[156:159], v230 offset:2048
	v_mfma_f32_16x16x32_bf16 v[26:29], v[192:195], v[172:175], v[26:29]
	ds_read_b128 v[160:163], v230 offset:4096
	v_mfma_f32_16x16x32_bf16 v[30:33], v[196:199], v[172:175], v[30:33]
	ds_read_b128 v[164:167], v230 offset:6144
	s_add_u32 m0, s8, 0x18000
	v_mfma_f32_16x16x32_bf16 v[34:37], v[184:187], v[176:179], v[34:37]
	global_load_lds_dwordx4 v200, s[4:5]
	s_add_u32 m0, s8, 0x18400
	v_mfma_f32_16x16x32_bf16 v[38:41], v[188:191], v[176:179], v[38:41]
	global_load_lds_dwordx4 v201, s[4:5]
	s_add_u32 m0, s8, 0x18800
	v_mfma_f32_16x16x32_bf16 v[42:45], v[192:195], v[176:179], v[42:45]
	global_load_lds_dwordx4 v202, s[4:5]
	s_add_u32 m0, s8, 0x18c00
	v_mfma_f32_16x16x32_bf16 v[46:49], v[196:199], v[176:179], v[46:49]
	global_load_lds_dwordx4 v203, s[4:5]
	s_add_u32 m0, s9, 0x18000
	v_mfma_f32_16x16x32_bf16 v[50:53], v[184:187], v[180:183], v[50:53]
	global_load_lds_dwordx4 v204, s[6:7]
	s_add_u32 m0, s9, 0x18400
	v_mfma_f32_16x16x32_bf16 v[54:57], v[188:191], v[180:183], v[54:57]
	global_load_lds_dwordx4 v205, s[6:7]
	v_mfma_f32_16x16x32_bf16 v[58:61], v[192:195], v[180:183], v[58:61]
	s_add_u32 s4, s4, 0x80
	s_addc_u32 s5, s5, 0
	v_mfma_f32_16x16x32_bf16 v[62:65], v[196:199], v[180:183], v[62:65]
	s_add_u32 s6, s6, 0x80
	s_addc_u32 s7, s7, 0
	s_waitcnt lgkmcnt(0)
	v_mfma_f32_16x16x32_bf16 v[2:5], v[152:155], v[136:139], v[2:5]
	ds_read_b128 v[168:171], v225 offset:0
	v_mfma_f32_16x16x32_bf16 v[6:9], v[156:159], v[136:139], v[6:9]
	ds_read_b128 v[172:175], v225 offset:2048
	v_mfma_f32_16x16x32_bf16 v[10:13], v[160:163], v[136:139], v[10:13]
	ds_read_b128 v[176:179], v225 offset:4096
	v_mfma_f32_16x16x32_bf16 v[14:17], v[164:167], v[136:139], v[14:17]
	ds_read_b128 v[180:183], v225 offset:6144
	v_mfma_f32_16x16x32_bf16 v[18:21], v[152:155], v[140:143], v[18:21]
	ds_read_b128 v[184:187], v233 offset:0
	v_mfma_f32_16x16x32_bf16 v[22:25], v[156:159], v[140:143], v[22:25]
	ds_read_b128 v[188:191], v233 offset:2048
	v_mfma_f32_16x16x32_bf16 v[26:29], v[160:163], v[140:143], v[26:29]
	ds_read_b128 v[192:195], v233 offset:4096
	v_mfma_f32_16x16x32_bf16 v[30:33], v[164:167], v[140:143], v[30:33]
	ds_read_b128 v[196:199], v233 offset:6144
	v_mfma_f32_16x16x32_bf16 v[34:37], v[152:155], v[144:147], v[34:37]
	v_mfma_f32_16x16x32_bf16 v[38:41], v[156:159], v[144:147], v[38:41]
	v_mfma_f32_16x16x32_bf16 v[42:45], v[160:163], v[144:147], v[42:45]
	v_mfma_f32_16x16x32_bf16 v[46:49], v[164:167], v[144:147], v[46:49]
	v_mfma_f32_16x16x32_bf16 v[50:53], v[152:155], v[148:151], v[50:53]
	v_mfma_f32_16x16x32_bf16 v[54:57], v[156:159], v[148:151], v[54:57]
	v_mfma_f32_16x16x32_bf16 v[58:61], v[160:163], v[148:151], v[58:61]
	v_mfma_f32_16x16x32_bf16 v[62:65], v[164:167], v[148:151], v[62:65]
	s_waitcnt vmcnt(6) lgkmcnt(0)
	s_barrier
	v_mfma_f32_16x16x32_bf16 v[2:5], v[184:187], v[168:171], v[2:5]
	ds_read_b128 v[136:139], v219 offset:0
	v_mfma_f32_16x16x32_bf16 v[6:9], v[188:191], v[168:171], v[6:9]
	ds_read_b128 v[140:143], v219 offset:2048
	v_mfma_f32_16x16x32_bf16 v[10:13], v[192:195], v[168:171], v[10:13]
	ds_read_b128 v[144:147], v219 offset:4096
	v_mfma_f32_16x16x32_bf16 v[14:17], v[196:199], v[168:171], v[14:17]
	ds_read_b128 v[148:151], v219 offset:6144
	v_mfma_f32_16x16x32_bf16 v[18:21], v[184:187], v[172:175], v[18:21]
	ds_read_b128 v[152:155], v231 offset:0
	v_mfma_f32_16x16x32_bf16 v[22:25], v[188:191], v[172:175], v[22:25]
	ds_read_b128 v[156:159], v231 offset:2048
	v_mfma_f32_16x16x32_bf16 v[26:29], v[192:195], v[172:175], v[26:29]
	ds_read_b128 v[160:163], v231 offset:4096
	v_mfma_f32_16x16x32_bf16 v[30:33], v[196:199], v[172:175], v[30:33]
	ds_read_b128 v[164:167], v231 offset:6144
	s_mov_b32 m0, s8
	v_mfma_f32_16x16x32_bf16 v[34:37], v[184:187], v[176:179], v[34:37]
	global_load_lds_dwordx4 v200, s[4:5]
	s_add_u32 m0, s8, 0x400
	v_mfma_f32_16x16x32_bf16 v[38:41], v[188:191], v[176:179], v[38:41]
	global_load_lds_dwordx4 v201, s[4:5]
	s_add_u32 m0, s8, 0x800
	v_mfma_f32_16x16x32_bf16 v[42:45], v[192:195], v[176:179], v[42:45]
	global_load_lds_dwordx4 v202, s[4:5]
	s_add_u32 m0, s8, 0xc00
	v_mfma_f32_16x16x32_bf16 v[46:49], v[196:199], v[176:179], v[46:49]
	global_load_lds_dwordx4 v203, s[4:5]
	s_mov_b32 m0, s9
	v_mfma_f32_16x16x32_bf16 v[50:53], v[184:187], v[180:183], v[50:53]
	global_load_lds_dwordx4 v204, s[6:7]
	s_add_u32 m0, s9, 0x400
	v_mfma_f32_16x16x32_bf16 v[54:57], v[188:191], v[180:183], v[54:57]
	global_load_lds_dwordx4 v205, s[6:7]
	v_mfma_f32_16x16x32_bf16 v[58:61], v[192:195], v[180:183], v[58:61]
	s_add_u32 s4, s4, 0x80
	s_addc_u32 s5, s5, 0
	v_mfma_f32_16x16x32_bf16 v[62:65], v[196:199], v[180:183], v[62:65]
	s_add_u32 s6, s6, 0x80
	s_addc_u32 s7, s7, 0
	s_waitcnt lgkmcnt(0)
	v_mfma_f32_16x16x32_bf16 v[2:5], v[152:155], v[136:139], v[2:5]
	ds_read_b128 v[168:171], v228 offset:0
	v_mfma_f32_16x16x32_bf16 v[6:9], v[156:159], v[136:139], v[6:9]
	ds_read_b128 v[172:175], v228 offset:2048
	v_mfma_f32_16x16x32_bf16 v[10:13], v[160:163], v[136:139], v[10:13]
	ds_read_b128 v[176:179], v228 offset:4096
	v_mfma_f32_16x16x32_bf16 v[14:17], v[164:167], v[136:139], v[14:17]
	ds_read_b128 v[180:183], v228 offset:6144
	v_mfma_f32_16x16x32_bf16 v[18:21], v[152:155], v[140:143], v[18:21]
	ds_read_b128 v[184:187], v234 offset:0
	v_mfma_f32_16x16x32_bf16 v[22:25], v[156:159], v[140:143], v[22:25]
	ds_read_b128 v[188:191], v234 offset:2048
	v_mfma_f32_16x16x32_bf16 v[26:29], v[160:163], v[140:143], v[26:29]
	ds_read_b128 v[192:195], v234 offset:4096
	v_mfma_f32_16x16x32_bf16 v[30:33], v[164:167], v[140:143], v[30:33]
	ds_read_b128 v[196:199], v234 offset:6144
	v_mfma_f32_16x16x32_bf16 v[34:37], v[152:155], v[144:147], v[34:37]
	v_mfma_f32_16x16x32_bf16 v[38:41], v[156:159], v[144:147], v[38:41]
	v_mfma_f32_16x16x32_bf16 v[42:45], v[160:163], v[144:147], v[42:45]
	v_mfma_f32_16x16x32_bf16 v[46:49], v[164:167], v[144:147], v[46:49]
	v_mfma_f32_16x16x32_bf16 v[50:53], v[152:155], v[148:151], v[50:53]
	v_mfma_f32_16x16x32_bf16 v[54:57], v[156:159], v[148:151], v[54:57]
	v_mfma_f32_16x16x32_bf16 v[58:61], v[160:163], v[148:151], v[58:61]
	v_mfma_f32_16x16x32_bf16 v[62:65], v[164:167], v[148:151], v[62:65]
	s_waitcnt vmcnt(6) lgkmcnt(0)
	s_barrier
	v_mfma_f32_16x16x32_bf16 v[2:5], v[184:187], v[168:171], v[2:5]
	ds_read_b128 v[136:139], v224 offset:0
	v_mfma_f32_16x16x32_bf16 v[6:9], v[188:191], v[168:171], v[6:9]
	ds_read_b128 v[140:143], v224 offset:2048
	v_mfma_f32_16x16x32_bf16 v[10:13], v[192:195], v[168:171], v[10:13]
	ds_read_b128 v[144:147], v224 offset:4096
	v_mfma_f32_16x16x32_bf16 v[14:17], v[196:199], v[168:171], v[14:17]
	ds_read_b128 v[148:151], v224 offset:6144
	v_mfma_f32_16x16x32_bf16 v[18:21], v[184:187], v[172:175], v[18:21]
	ds_read_b128 v[152:155], v232 offset:0
	v_mfma_f32_16x16x32_bf16 v[22:25], v[188:191], v[172:175], v[22:25]
	ds_read_b128 v[156:159], v232 offset:2048
	v_mfma_f32_16x16x32_bf16 v[26:29], v[192:195], v[172:175], v[26:29]
	ds_read_b128 v[160:163], v232 offset:4096
	v_mfma_f32_16x16x32_bf16 v[30:33], v[196:199], v[172:175], v[30:33]
	ds_read_b128 v[164:167], v232 offset:6144
	s_add_u32 m0, s8, 0xc000
	v_mfma_f32_16x16x32_bf16 v[34:37], v[184:187], v[176:179], v[34:37]
	global_load_lds_dwordx4 v200, s[4:5]
	s_add_u32 m0, s8, 0xc400
	v_mfma_f32_16x16x32_bf16 v[38:41], v[188:191], v[176:179], v[38:41]
	global_load_lds_dwordx4 v201, s[4:5]
	s_add_u32 m0, s8, 0xc800
	v_mfma_f32_16x16x32_bf16 v[42:45], v[192:195], v[176:179], v[42:45]
	global_load_lds_dwordx4 v202, s[4:5]
	s_add_u32 m0, s8, 0xcc00
	v_mfma_f32_16x16x32_bf16 v[46:49], v[196:199], v[176:179], v[46:49]
	global_load_lds_dwordx4 v203, s[4:5]
	s_add_u32 m0, s9, 0xc000
	v_mfma_f32_16x16x32_bf16 v[50:53], v[184:187], v[180:183], v[50:53]
	global_load_lds_dwordx4 v204, s[6:7]
	s_add_u32 m0, s9, 0xc400
	v_mfma_f32_16x16x32_bf16 v[54:57], v[188:191], v[180:183], v[54:57]
	global_load_lds_dwordx4 v205, s[6:7]
	v_mfma_f32_16x16x32_bf16 v[58:61], v[192:195], v[180:183], v[58:61]
	s_add_u32 s4, s4, 0x80
	s_addc_u32 s5, s5, 0
	v_mfma_f32_16x16x32_bf16 v[62:65], v[196:199], v[180:183], v[62:65]
	s_add_u32 s6, s6, 0x80
	s_addc_u32 s7, s7, 0
	s_waitcnt lgkmcnt(0)
	v_mfma_f32_16x16x32_bf16 v[2:5], v[152:155], v[136:139], v[2:5]
	ds_read_b128 v[168:171], v229 offset:0
	v_mfma_f32_16x16x32_bf16 v[6:9], v[156:159], v[136:139], v[6:9]
	ds_read_b128 v[172:175], v229 offset:2048
	v_mfma_f32_16x16x32_bf16 v[10:13], v[160:163], v[136:139], v[10:13]
	ds_read_b128 v[176:179], v229 offset:4096
	v_mfma_f32_16x16x32_bf16 v[14:17], v[164:167], v[136:139], v[14:17]
	ds_read_b128 v[180:183], v229 offset:6144
	v_mfma_f32_16x16x32_bf16 v[18:21], v[152:155], v[140:143], v[18:21]
	ds_read_b128 v[184:187], v235 offset:0
	v_mfma_f32_16x16x32_bf16 v[22:25], v[156:159], v[140:143], v[22:25]
	ds_read_b128 v[188:191], v235 offset:2048
	v_mfma_f32_16x16x32_bf16 v[26:29], v[160:163], v[140:143], v[26:29]
	ds_read_b128 v[192:195], v235 offset:4096
	v_mfma_f32_16x16x32_bf16 v[30:33], v[164:167], v[140:143], v[30:33]
	ds_read_b128 v[196:199], v235 offset:6144
	v_mfma_f32_16x16x32_bf16 v[34:37], v[152:155], v[144:147], v[34:37]
	v_mfma_f32_16x16x32_bf16 v[38:41], v[156:159], v[144:147], v[38:41]
	v_mfma_f32_16x16x32_bf16 v[42:45], v[160:163], v[144:147], v[42:45]
	v_mfma_f32_16x16x32_bf16 v[46:49], v[164:167], v[144:147], v[46:49]
	v_mfma_f32_16x16x32_bf16 v[50:53], v[152:155], v[148:151], v[50:53]
	v_mfma_f32_16x16x32_bf16 v[54:57], v[156:159], v[148:151], v[54:57]
	v_mfma_f32_16x16x32_bf16 v[58:61], v[160:163], v[148:151], v[58:61]
	v_mfma_f32_16x16x32_bf16 v[62:65], v[164:167], v[148:151], v[62:65]
	s_waitcnt vmcnt(6) lgkmcnt(0)
	s_barrier
	v_mfma_f32_16x16x32_bf16 v[2:5], v[184:187], v[168:171], v[2:5]
	ds_read_b128 v[136:139], v218 offset:0
	v_mfma_f32_16x16x32_bf16 v[6:9], v[188:191], v[168:171], v[6:9]
	ds_read_b128 v[140:143], v218 offset:2048
	v_mfma_f32_16x16x32_bf16 v[10:13], v[192:195], v[168:171], v[10:13]
	ds_read_b128 v[144:147], v218 offset:4096
	v_mfma_f32_16x16x32_bf16 v[14:17], v[196:199], v[168:171], v[14:17]
	ds_read_b128 v[148:151], v218 offset:6144
	v_mfma_f32_16x16x32_bf16 v[18:21], v[184:187], v[172:175], v[18:21]
	ds_read_b128 v[152:155], v230 offset:0
	v_mfma_f32_16x16x32_bf16 v[22:25], v[188:191], v[172:175], v[22:25]
	ds_read_b128 v[156:159], v230 offset:2048
	v_mfma_f32_16x16x32_bf16 v[26:29], v[192:195], v[172:175], v[26:29]
	ds_read_b128 v[160:163], v230 offset:4096
	v_mfma_f32_16x16x32_bf16 v[30:33], v[196:199], v[172:175], v[30:33]
	ds_read_b128 v[164:167], v230 offset:6144
	s_add_u32 m0, s8, 0x18000
	v_mfma_f32_16x16x32_bf16 v[34:37], v[184:187], v[176:179], v[34:37]
	global_load_lds_dwordx4 v200, s[4:5]
	s_add_u32 m0, s8, 0x18400
	v_mfma_f32_16x16x32_bf16 v[38:41], v[188:191], v[176:179], v[38:41]
	global_load_lds_dwordx4 v201, s[4:5]
	s_add_u32 m0, s8, 0x18800
	v_mfma_f32_16x16x32_bf16 v[42:45], v[192:195], v[176:179], v[42:45]
	global_load_lds_dwordx4 v202, s[4:5]
	s_add_u32 m0, s8, 0x18c00
	v_mfma_f32_16x16x32_bf16 v[46:49], v[196:199], v[176:179], v[46:49]
	global_load_lds_dwordx4 v203, s[4:5]
	s_add_u32 m0, s9, 0x18000
	v_mfma_f32_16x16x32_bf16 v[50:53], v[184:187], v[180:183], v[50:53]
	global_load_lds_dwordx4 v204, s[6:7]
	s_add_u32 m0, s9, 0x18400
	v_mfma_f32_16x16x32_bf16 v[54:57], v[188:191], v[180:183], v[54:57]
	global_load_lds_dwordx4 v205, s[6:7]
	v_mfma_f32_16x16x32_bf16 v[58:61], v[192:195], v[180:183], v[58:61]
	s_add_u32 s4, s4, 0x80
	s_addc_u32 s5, s5, 0
	v_mfma_f32_16x16x32_bf16 v[62:65], v[196:199], v[180:183], v[62:65]
	s_add_u32 s6, s6, 0x80
	s_addc_u32 s7, s7, 0
	s_waitcnt lgkmcnt(0)
	v_mfma_f32_16x16x32_bf16 v[2:5], v[152:155], v[136:139], v[2:5]
	ds_read_b128 v[168:171], v225 offset:0
	v_mfma_f32_16x16x32_bf16 v[6:9], v[156:159], v[136:139], v[6:9]
	ds_read_b128 v[172:175], v225 offset:2048
	v_mfma_f32_16x16x32_bf16 v[10:13], v[160:163], v[136:139], v[10:13]
	ds_read_b128 v[176:179], v225 offset:4096
	v_mfma_f32_16x16x32_bf16 v[14:17], v[164:167], v[136:139], v[14:17]
	ds_read_b128 v[180:183], v225 offset:6144
	v_mfma_f32_16x16x32_bf16 v[18:21], v[152:155], v[140:143], v[18:21]
	ds_read_b128 v[184:187], v233 offset:0
	v_mfma_f32_16x16x32_bf16 v[22:25], v[156:159], v[140:143], v[22:25]
	ds_read_b128 v[188:191], v233 offset:2048
	v_mfma_f32_16x16x32_bf16 v[26:29], v[160:163], v[140:143], v[26:29]
	ds_read_b128 v[192:195], v233 offset:4096
	v_mfma_f32_16x16x32_bf16 v[30:33], v[164:167], v[140:143], v[30:33]
	ds_read_b128 v[196:199], v233 offset:6144
	v_mfma_f32_16x16x32_bf16 v[34:37], v[152:155], v[144:147], v[34:37]
	v_mfma_f32_16x16x32_bf16 v[38:41], v[156:159], v[144:147], v[38:41]
	v_mfma_f32_16x16x32_bf16 v[42:45], v[160:163], v[144:147], v[42:45]
	v_mfma_f32_16x16x32_bf16 v[46:49], v[164:167], v[144:147], v[46:49]
	v_mfma_f32_16x16x32_bf16 v[50:53], v[152:155], v[148:151], v[50:53]
	v_mfma_f32_16x16x32_bf16 v[54:57], v[156:159], v[148:151], v[54:57]
	v_mfma_f32_16x16x32_bf16 v[58:61], v[160:163], v[148:151], v[58:61]
	v_mfma_f32_16x16x32_bf16 v[62:65], v[164:167], v[148:151], v[62:65]
	s_waitcnt vmcnt(6) lgkmcnt(0)
	s_barrier
	v_mfma_f32_16x16x32_bf16 v[2:5], v[184:187], v[168:171], v[2:5]
	ds_read_b128 v[136:139], v219 offset:0
	v_mfma_f32_16x16x32_bf16 v[6:9], v[188:191], v[168:171], v[6:9]
	ds_read_b128 v[140:143], v219 offset:2048
	v_mfma_f32_16x16x32_bf16 v[10:13], v[192:195], v[168:171], v[10:13]
	ds_read_b128 v[144:147], v219 offset:4096
	v_mfma_f32_16x16x32_bf16 v[14:17], v[196:199], v[168:171], v[14:17]
	ds_read_b128 v[148:151], v219 offset:6144
	v_mfma_f32_16x16x32_bf16 v[18:21], v[184:187], v[172:175], v[18:21]
	ds_read_b128 v[152:155], v231 offset:0
	v_mfma_f32_16x16x32_bf16 v[22:25], v[188:191], v[172:175], v[22:25]
	ds_read_b128 v[156:159], v231 offset:2048
	v_mfma_f32_16x16x32_bf16 v[26:29], v[192:195], v[172:175], v[26:29]
	ds_read_b128 v[160:163], v231 offset:4096
	v_mfma_f32_16x16x32_bf16 v[30:33], v[196:199], v[172:175], v[30:33]
	ds_read_b128 v[164:167], v231 offset:6144
	s_mov_b32 m0, s8
	v_mfma_f32_16x16x32_bf16 v[34:37], v[184:187], v[176:179], v[34:37]
	global_load_lds_dwordx4 v200, s[4:5]
	s_add_u32 m0, s8, 0x400
	v_mfma_f32_16x16x32_bf16 v[38:41], v[188:191], v[176:179], v[38:41]
	global_load_lds_dwordx4 v201, s[4:5]
	s_add_u32 m0, s8, 0x800
	v_mfma_f32_16x16x32_bf16 v[42:45], v[192:195], v[176:179], v[42:45]
	global_load_lds_dwordx4 v202, s[4:5]
	s_add_u32 m0, s8, 0xc00
	v_mfma_f32_16x16x32_bf16 v[46:49], v[196:199], v[176:179], v[46:49]
	global_load_lds_dwordx4 v203, s[4:5]
	s_mov_b32 m0, s9
	v_mfma_f32_16x16x32_bf16 v[50:53], v[184:187], v[180:183], v[50:53]
	global_load_lds_dwordx4 v204, s[6:7]
	s_add_u32 m0, s9, 0x400
	v_mfma_f32_16x16x32_bf16 v[54:57], v[188:191], v[180:183], v[54:57]
	global_load_lds_dwordx4 v205, s[6:7]
	v_mfma_f32_16x16x32_bf16 v[58:61], v[192:195], v[180:183], v[58:61]
	s_sub_u32 s4, s4, 0x780
	s_subb_u32 s5, s5, 0
	v_mfma_f32_16x16x32_bf16 v[62:65], v[196:199], v[180:183], v[62:65]
	s_add_u32 s6, s6, 0x3f880
	s_addc_u32 s7, s7, 0
	s_waitcnt lgkmcnt(0)
	v_mfma_f32_16x16x32_bf16 v[2:5], v[152:155], v[136:139], v[2:5]
	ds_read_b128 v[168:171], v228 offset:0
	v_mfma_f32_16x16x32_bf16 v[6:9], v[156:159], v[136:139], v[6:9]
	ds_read_b128 v[172:175], v228 offset:2048
	v_mfma_f32_16x16x32_bf16 v[10:13], v[160:163], v[136:139], v[10:13]
	ds_read_b128 v[176:179], v228 offset:4096
	v_mfma_f32_16x16x32_bf16 v[14:17], v[164:167], v[136:139], v[14:17]
	ds_read_b128 v[180:183], v228 offset:6144
	v_mfma_f32_16x16x32_bf16 v[18:21], v[152:155], v[140:143], v[18:21]
	ds_read_b128 v[184:187], v234 offset:0
	v_mfma_f32_16x16x32_bf16 v[22:25], v[156:159], v[140:143], v[22:25]
	ds_read_b128 v[188:191], v234 offset:2048
	v_mfma_f32_16x16x32_bf16 v[26:29], v[160:163], v[140:143], v[26:29]
	ds_read_b128 v[192:195], v234 offset:4096
	v_mfma_f32_16x16x32_bf16 v[30:33], v[164:167], v[140:143], v[30:33]
	ds_read_b128 v[196:199], v234 offset:6144
	v_mfma_f32_16x16x32_bf16 v[34:37], v[152:155], v[144:147], v[34:37]
	v_mfma_f32_16x16x32_bf16 v[38:41], v[156:159], v[144:147], v[38:41]
	v_mfma_f32_16x16x32_bf16 v[42:45], v[160:163], v[144:147], v[42:45]
	v_mfma_f32_16x16x32_bf16 v[46:49], v[164:167], v[144:147], v[46:49]
	v_mfma_f32_16x16x32_bf16 v[50:53], v[152:155], v[148:151], v[50:53]
	v_mfma_f32_16x16x32_bf16 v[54:57], v[156:159], v[148:151], v[54:57]
	v_mfma_f32_16x16x32_bf16 v[58:61], v[160:163], v[148:151], v[58:61]
	v_mfma_f32_16x16x32_bf16 v[62:65], v[164:167], v[148:151], v[62:65]
	s_waitcnt vmcnt(6) lgkmcnt(0)
	s_barrier
	v_mfma_f32_16x16x32_bf16 v[2:5], v[184:187], v[168:171], v[2:5]
	ds_read_b128 v[136:139], v224 offset:0
	v_mfma_f32_16x16x32_bf16 v[6:9], v[188:191], v[168:171], v[6:9]
	ds_read_b128 v[140:143], v224 offset:2048
	v_mfma_f32_16x16x32_bf16 v[10:13], v[192:195], v[168:171], v[10:13]
	ds_read_b128 v[144:147], v224 offset:4096
	v_mfma_f32_16x16x32_bf16 v[14:17], v[196:199], v[168:171], v[14:17]
	ds_read_b128 v[148:151], v224 offset:6144
	v_mfma_f32_16x16x32_bf16 v[18:21], v[184:187], v[172:175], v[18:21]
	ds_read_b128 v[152:155], v232 offset:0
	v_mfma_f32_16x16x32_bf16 v[22:25], v[188:191], v[172:175], v[22:25]
	ds_read_b128 v[156:159], v232 offset:2048
	v_mfma_f32_16x16x32_bf16 v[26:29], v[192:195], v[172:175], v[26:29]
	ds_read_b128 v[160:163], v232 offset:4096
	v_mfma_f32_16x16x32_bf16 v[30:33], v[196:199], v[172:175], v[30:33]
	ds_read_b128 v[164:167], v232 offset:6144
	v_mfma_f32_16x16x32_bf16 v[34:37], v[184:187], v[176:179], v[34:37]
	v_mfma_f32_16x16x32_bf16 v[38:41], v[188:191], v[176:179], v[38:41]
	v_mfma_f32_16x16x32_bf16 v[42:45], v[192:195], v[176:179], v[42:45]
	v_mfma_f32_16x16x32_bf16 v[46:49], v[196:199], v[176:179], v[46:49]
	v_mfma_f32_16x16x32_bf16 v[50:53], v[184:187], v[180:183], v[50:53]
	v_mfma_f32_16x16x32_bf16 v[54:57], v[188:191], v[180:183], v[54:57]
	v_mfma_f32_16x16x32_bf16 v[58:61], v[192:195], v[180:183], v[58:61]
	v_mfma_f32_16x16x32_bf16 v[62:65], v[196:199], v[180:183], v[62:65]
	s_waitcnt lgkmcnt(0)
	v_mfma_f32_16x16x32_bf16 v[2:5], v[152:155], v[136:139], v[2:5]
	ds_read_b128 v[168:171], v229 offset:0
	v_mfma_f32_16x16x32_bf16 v[6:9], v[156:159], v[136:139], v[6:9]
	ds_read_b128 v[172:175], v229 offset:2048
	v_mfma_f32_16x16x32_bf16 v[10:13], v[160:163], v[136:139], v[10:13]
	ds_read_b128 v[176:179], v229 offset:4096
	v_mfma_f32_16x16x32_bf16 v[14:17], v[164:167], v[136:139], v[14:17]
	ds_read_b128 v[180:183], v229 offset:6144
	v_mfma_f32_16x16x32_bf16 v[18:21], v[152:155], v[140:143], v[18:21]
	ds_read_b128 v[184:187], v235 offset:0
	v_mfma_f32_16x16x32_bf16 v[22:25], v[156:159], v[140:143], v[22:25]
	ds_read_b128 v[188:191], v235 offset:2048
	v_mfma_f32_16x16x32_bf16 v[26:29], v[160:163], v[140:143], v[26:29]
	ds_read_b128 v[192:195], v235 offset:4096
	v_mfma_f32_16x16x32_bf16 v[30:33], v[164:167], v[140:143], v[30:33]
	ds_read_b128 v[196:199], v235 offset:6144
	v_mfma_f32_16x16x32_bf16 v[34:37], v[152:155], v[144:147], v[34:37]
	v_mfma_f32_16x16x32_bf16 v[38:41], v[156:159], v[144:147], v[38:41]
	v_mfma_f32_16x16x32_bf16 v[42:45], v[160:163], v[144:147], v[42:45]
	v_mfma_f32_16x16x32_bf16 v[46:49], v[164:167], v[144:147], v[46:49]
	v_mfma_f32_16x16x32_bf16 v[50:53], v[152:155], v[148:151], v[50:53]
	v_mfma_f32_16x16x32_bf16 v[54:57], v[156:159], v[148:151], v[54:57]
	v_mfma_f32_16x16x32_bf16 v[58:61], v[160:163], v[148:151], v[58:61]
	v_mfma_f32_16x16x32_bf16 v[62:65], v[164:167], v[148:151], v[62:65]
	s_waitcnt vmcnt(0) lgkmcnt(0)
	s_barrier
	v_mfma_f32_16x16x32_bf16 v[2:5], v[184:187], v[168:171], v[2:5]
	ds_read_b128 v[136:139], v218 offset:0
	v_mfma_f32_16x16x32_bf16 v[6:9], v[188:191], v[168:171], v[6:9]
	ds_read_b128 v[140:143], v218 offset:2048
	v_mfma_f32_16x16x32_bf16 v[10:13], v[192:195], v[168:171], v[10:13]
	ds_read_b128 v[144:147], v218 offset:4096
	v_mfma_f32_16x16x32_bf16 v[14:17], v[196:199], v[168:171], v[14:17]
	ds_read_b128 v[148:151], v218 offset:6144
	v_mfma_f32_16x16x32_bf16 v[18:21], v[184:187], v[172:175], v[18:21]
	ds_read_b128 v[152:155], v230 offset:0
	v_mfma_f32_16x16x32_bf16 v[22:25], v[188:191], v[172:175], v[22:25]
	ds_read_b128 v[156:159], v230 offset:2048
	v_mfma_f32_16x16x32_bf16 v[26:29], v[192:195], v[172:175], v[26:29]
	ds_read_b128 v[160:163], v230 offset:4096
	v_mfma_f32_16x16x32_bf16 v[30:33], v[196:199], v[172:175], v[30:33]
	ds_read_b128 v[164:167], v230 offset:6144
	v_mfma_f32_16x16x32_bf16 v[34:37], v[184:187], v[176:179], v[34:37]
	v_mfma_f32_16x16x32_bf16 v[38:41], v[188:191], v[176:179], v[38:41]
	v_mfma_f32_16x16x32_bf16 v[42:45], v[192:195], v[176:179], v[42:45]
	v_mfma_f32_16x16x32_bf16 v[46:49], v[196:199], v[176:179], v[46:49]
	v_mfma_f32_16x16x32_bf16 v[50:53], v[184:187], v[180:183], v[50:53]
	v_mfma_f32_16x16x32_bf16 v[54:57], v[188:191], v[180:183], v[54:57]
	v_mfma_f32_16x16x32_bf16 v[58:61], v[192:195], v[180:183], v[58:61]
	v_mfma_f32_16x16x32_bf16 v[62:65], v[196:199], v[180:183], v[62:65]
	s_waitcnt lgkmcnt(0)
	v_mfma_f32_16x16x32_bf16 v[2:5], v[152:155], v[136:139], v[2:5]
	ds_read_b128 v[168:171], v225 offset:0
	v_mfma_f32_16x16x32_bf16 v[6:9], v[156:159], v[136:139], v[6:9]
	ds_read_b128 v[172:175], v225 offset:2048
	v_mfma_f32_16x16x32_bf16 v[10:13], v[160:163], v[136:139], v[10:13]
	ds_read_b128 v[176:179], v225 offset:4096
	v_mfma_f32_16x16x32_bf16 v[14:17], v[164:167], v[136:139], v[14:17]
	ds_read_b128 v[180:183], v225 offset:6144
	v_mfma_f32_16x16x32_bf16 v[18:21], v[152:155], v[140:143], v[18:21]
	ds_read_b128 v[184:187], v233 offset:0
	v_mfma_f32_16x16x32_bf16 v[22:25], v[156:159], v[140:143], v[22:25]
	ds_read_b128 v[188:191], v233 offset:2048
	v_mfma_f32_16x16x32_bf16 v[26:29], v[160:163], v[140:143], v[26:29]
	ds_read_b128 v[192:195], v233 offset:4096
	v_mfma_f32_16x16x32_bf16 v[30:33], v[164:167], v[140:143], v[30:33]
	ds_read_b128 v[196:199], v233 offset:6144
	v_mfma_f32_16x16x32_bf16 v[34:37], v[152:155], v[144:147], v[34:37]
	v_mfma_f32_16x16x32_bf16 v[38:41], v[156:159], v[144:147], v[38:41]
	v_mfma_f32_16x16x32_bf16 v[42:45], v[160:163], v[144:147], v[42:45]
	v_mfma_f32_16x16x32_bf16 v[46:49], v[164:167], v[144:147], v[46:49]
	v_mfma_f32_16x16x32_bf16 v[50:53], v[152:155], v[148:151], v[50:53]
	v_mfma_f32_16x16x32_bf16 v[54:57], v[156:159], v[148:151], v[54:57]
	v_mfma_f32_16x16x32_bf16 v[58:61], v[160:163], v[148:151], v[58:61]
	v_mfma_f32_16x16x32_bf16 v[62:65], v[164:167], v[148:151], v[62:65]
	s_waitcnt lgkmcnt(0)
	v_mfma_f32_16x16x32_bf16 v[2:5], v[184:187], v[168:171], v[2:5]
	v_mfma_f32_16x16x32_bf16 v[6:9], v[188:191], v[168:171], v[6:9]
	v_mfma_f32_16x16x32_bf16 v[10:13], v[192:195], v[168:171], v[10:13]
	v_mfma_f32_16x16x32_bf16 v[14:17], v[196:199], v[168:171], v[14:17]
	v_mfma_f32_16x16x32_bf16 v[18:21], v[184:187], v[172:175], v[18:21]
	v_mfma_f32_16x16x32_bf16 v[22:25], v[188:191], v[172:175], v[22:25]
	v_mfma_f32_16x16x32_bf16 v[26:29], v[192:195], v[172:175], v[26:29]
	v_mfma_f32_16x16x32_bf16 v[30:33], v[196:199], v[172:175], v[30:33]
	v_mfma_f32_16x16x32_bf16 v[34:37], v[184:187], v[176:179], v[34:37]
	v_mfma_f32_16x16x32_bf16 v[38:41], v[188:191], v[176:179], v[38:41]
	v_mfma_f32_16x16x32_bf16 v[42:45], v[192:195], v[176:179], v[42:45]
	v_mfma_f32_16x16x32_bf16 v[46:49], v[196:199], v[176:179], v[46:49]
	v_mfma_f32_16x16x32_bf16 v[50:53], v[184:187], v[180:183], v[50:53]
	v_mfma_f32_16x16x32_bf16 v[54:57], v[188:191], v[180:183], v[54:57]
	v_mfma_f32_16x16x32_bf16 v[58:61], v[192:195], v[180:183], v[58:61]
	v_mfma_f32_16x16x32_bf16 v[62:65], v[196:199], v[180:183], v[62:65]
	s_nop 7
	s_add_u32 s10, s52, 0x0
	s_addc_u32 s11, s53, 0
	global_store_dwordx4 v237, v[2:5], s[10:11] offset:0
	global_store_dwordx4 v237, v[6:9], s[10:11] offset:64
	global_store_dwordx4 v237, v[10:13], s[10:11] offset:128
	global_store_dwordx4 v237, v[14:17], s[10:11] offset:192
	s_add_u32 s10, s10, 0x22000
	s_addc_u32 s11, s11, 0
	global_store_dwordx4 v237, v[18:21], s[10:11] offset:0
	global_store_dwordx4 v237, v[22:25], s[10:11] offset:64
	global_store_dwordx4 v237, v[26:29], s[10:11] offset:128
	global_store_dwordx4 v237, v[30:33], s[10:11] offset:192
	s_add_u32 s10, s10, 0x22000
	s_addc_u32 s11, s11, 0
	global_store_dwordx4 v237, v[34:37], s[10:11] offset:0
	global_store_dwordx4 v237, v[38:41], s[10:11] offset:64
	global_store_dwordx4 v237, v[42:45], s[10:11] offset:128
	global_store_dwordx4 v237, v[46:49], s[10:11] offset:192
	s_add_u32 s10, s10, 0x22000
	s_addc_u32 s11, s11, 0
	global_store_dwordx4 v237, v[50:53], s[10:11] offset:0
	global_store_dwordx4 v237, v[54:57], s[10:11] offset:64
	global_store_dwordx4 v237, v[58:61], s[10:11] offset:128
	global_store_dwordx4 v237, v[62:65], s[10:11] offset:192
.La1_done:
	s_waitcnt vmcnt(0)
	s_barrier
	v_mov_b32_e32 v238, s20
	v_mov_b32_e32 v239, s21
	v_mov_b32_e32 v1, 0x200f0
	ds_write_b64 v1, v[238:239]
	v_readlane_b32 s60, v254, 32
	v_readlane_b32 s54, v254, 34
	v_readlane_b32 s62, v254, 36
	v_readlane_b32 s70, v254, 38
	v_readlane_b32 s76, v254, 40
	v_readlane_b32 s86, v254, 42
	v_readlane_b32 s94, v254, 44
	v_readlane_b32 s58, v254, 46
	v_readlane_b32 s56, v254, 48
	v_readlane_b32 s61, v254, 33
	v_readlane_b32 s55, v254, 35
	v_readlane_b32 s63, v254, 37
	v_readlane_b32 s71, v254, 39
	v_readlane_b32 s77, v254, 41
	v_readlane_b32 s87, v254, 43
	v_readlane_b32 s95, v254, 45
	v_readlane_b32 s59, v254, 47
	v_readlane_b32 s57, v254, 49
	s_waitcnt lgkmcnt(0)
	s_branch .LBB0_419

.LBB0_513:
	s_or_b64 exec, exec, s[10:11]
	s_waitcnt lgkmcnt(0)
	s_barrier
	ds_read_b128 v[192:195], v101
	ds_read_b128 v[196:199], v101 offset:64
	ds_read_b128 v[244:247], v101 offset:4608
	ds_read_b128 v[248:251], v101 offset:4672
	global_load_dwordx4 v[94:97], v[102:103], off
	global_load_dwordx4 v[82:85], v[104:105], off
	global_load_dwordx4 v[90:93], v[106:107], off
	global_load_dwordx4 v[62:65], v[112:113], off
	global_load_dwordx4 v[18:21], v[126:127], off
	global_load_dwordx4 v[70:73], v[110:111], off
	global_load_dwordx4 v[42:45], v[118:119], off
	global_load_dwordx4 v[34:37], v[120:121], off
	global_load_dwordx4 v[2:5], v[128:129], off
	global_load_dwordx4 v[50:53], v[108:109], off
	global_load_dwordx4 v[38:41], v[122:123], off
	global_load_dwordx4 v[66:69], v[114:115], off
	global_load_dwordx4 v[30:33], v[124:125], off
	global_load_dwordx4 v[58:61], v[116:117], off
	global_load_dwordx4 v[14:17], v[136:137], off
	global_load_dwordx4 v[6:9], v[138:139], off
	global_load_dwordx4 v[22:25], v[102:103], off offset:64
	global_load_dwordx4 v[26:29], v[140:141], off
	global_load_dwordx4 v[46:49], v[142:143], off
	global_load_dwordx4 v[54:57], v[146:147], off
	global_load_dwordx4 v[74:77], v[126:127], off offset:64
	global_load_dwordx4 v[78:81], v[110:111], off offset:64
	global_load_dwordx4 v[86:89], v[118:119], off offset:64
	global_load_dwordx4 v[186:189], v[152:153], off
	v_or_b32_e32 v243, v10, v1
	v_cmp_gt_i32_e32 vcc, s37, v243
	v_cndmask_b32_e32 v11, v213, v214, vcc
	s_waitcnt lgkmcnt(0)
	s_waitcnt vmcnt(23)
	v_mfma_f32_16x16x32_bf16 v[94:97], v[94:97], v[192:195], 0
	s_waitcnt vmcnt(22)
	v_mfma_f32_16x16x32_bf16 v[82:85], v[82:85], v[192:195], 0
	s_waitcnt vmcnt(21)
	v_mfma_f32_16x16x32_bf16 v[90:93], v[90:93], v[244:247], 0
	s_waitcnt vmcnt(20)
	v_mfma_f32_16x16x32_bf16 v[62:65], v[62:65], v[192:195], 0
	s_waitcnt vmcnt(19)
	v_mfma_f32_16x16x32_bf16 v[18:21], v[18:21], v[192:195], 0
	s_waitcnt vmcnt(18)
	v_mfma_f32_16x16x32_bf16 v[70:73], v[70:73], v[192:195], 0
	s_waitcnt vmcnt(17)
	v_mfma_f32_16x16x32_bf16 v[42:45], v[42:45], v[192:195], 0
	s_waitcnt vmcnt(16)
	v_mfma_f32_16x16x32_bf16 v[34:37], v[34:37], v[192:195], 0
	s_waitcnt vmcnt(15)
	v_mfma_f32_16x16x32_bf16 v[2:5], v[2:5], v[192:195], 0
	s_waitcnt vmcnt(14)
	v_mfma_f32_16x16x32_bf16 v[50:53], v[50:53], v[244:247], 0
	s_waitcnt vmcnt(13)
	v_mfma_f32_16x16x32_bf16 v[38:41], v[38:41], v[244:247], 0
	s_waitcnt vmcnt(12)
	v_mfma_f32_16x16x32_bf16 v[66:69], v[66:69], v[244:247], 0
	s_waitcnt vmcnt(11)
	v_mfma_f32_16x16x32_bf16 v[30:33], v[30:33], v[244:247], 0
	s_waitcnt vmcnt(10)
	v_mfma_f32_16x16x32_bf16 v[58:61], v[58:61], v[244:247], 0
	s_waitcnt vmcnt(9)
	v_mfma_f32_16x16x32_bf16 v[14:17], v[14:17], v[244:247], 0
	s_waitcnt vmcnt(8)
	v_mfma_f32_16x16x32_bf16 v[6:9], v[6:9], v[244:247], 0
	s_waitcnt vmcnt(7)
	v_mfma_f32_16x16x32_bf16 v[94:97], v[22:25], v[196:199], v[94:97]
	global_load_dwordx4 v[22:25], v[158:159], off
	s_waitcnt vmcnt(7)
	v_mfma_f32_16x16x32_bf16 v[82:85], v[26:29], v[196:199], v[82:85]
	global_load_dwordx4 v[26:29], v[144:145], off
	s_waitcnt vmcnt(7)
	v_mfma_f32_16x16x32_bf16 v[90:93], v[46:49], v[248:251], v[90:93]
	global_load_dwordx4 v[46:49], v[154:155], off
	s_waitcnt vmcnt(7)
	v_mfma_f32_16x16x32_bf16 v[62:65], v[54:57], v[196:199], v[62:65]
	global_load_dwordx4 v[54:57], v[148:149], off
	s_waitcnt vmcnt(7)
	v_mfma_f32_16x16x32_bf16 v[18:21], v[74:77], v[196:199], v[18:21]
	global_load_dwordx4 v[74:77], v[156:157], off
	s_waitcnt vmcnt(7)
	v_mfma_f32_16x16x32_bf16 v[70:73], v[78:81], v[196:199], v[70:73]
	global_load_dwordx4 v[78:81], v[150:151], off
	s_waitcnt vmcnt(7)
	v_mfma_f32_16x16x32_bf16 v[42:45], v[86:89], v[196:199], v[42:45]
	global_load_dwordx4 v[86:89], v[160:161], off
	s_waitcnt vmcnt(7)
	v_mfma_f32_16x16x32_bf16 v[34:37], v[186:189], v[196:199], v[34:37]
	global_load_dwordx4 v[186:189], v[162:163], off
	s_waitcnt vmcnt(7)
	v_mfma_f32_16x16x32_bf16 v[2:5], v[22:25], v[196:199], v[2:5]
	s_waitcnt vmcnt(6)
	v_mfma_f32_16x16x32_bf16 v[50:53], v[26:29], v[248:251], v[50:53]
	s_waitcnt vmcnt(5)
	v_mfma_f32_16x16x32_bf16 v[38:41], v[46:49], v[248:251], v[38:41]
	s_waitcnt vmcnt(4)
	v_mfma_f32_16x16x32_bf16 v[66:69], v[54:57], v[248:251], v[66:69]
	s_waitcnt vmcnt(3)
	v_mfma_f32_16x16x32_bf16 v[30:33], v[74:77], v[248:251], v[30:33]
	s_waitcnt vmcnt(2)
	v_mfma_f32_16x16x32_bf16 v[58:61], v[78:81], v[248:251], v[58:61]
	s_waitcnt vmcnt(1)
	v_mfma_f32_16x16x32_bf16 v[14:17], v[86:89], v[248:251], v[14:17]
	s_waitcnt vmcnt(0)
	v_mfma_f32_16x16x32_bf16 v[6:9], v[186:189], v[248:251], v[6:9]
	v_cndmask_b32_e32 v12, v215, v216, vcc
	v_bitop3_b32 v130, v12, v10, v1 bitop3:0xe0
	v_mov_b64_e32 v[12:13], s[28:29]
	v_cndmask_b32_e64 v22, 10, 8, vcc
	v_and_b32_e32 v10, v11, v10
	v_mad_i64_i32 v[12:13], s[10:11], v243, s36, v[12:13]
	v_lshlrev_b64 v[22:23], v22, v[98:99]
	v_ashrrev_i32_e32 v11, 31, v10
	v_lshl_add_u64 v[22:23], v[22:23], 0, v[130:131]
	v_lshl_add_u64 v[190:191], v[12:13], 0, s[92:93]
	v_lshl_add_u64 v[204:205], v[10:11], 2, v[22:23]
	v_lshl_add_u64 v[10:11], v[190:191], 0, v[164:165]
	v_lshl_add_u64 v[188:189], v[12:13], 0, v[164:165]
	global_load_dwordx4 v[86:89], v[10:11], off
	global_load_dwordx4 v[46:49], v[188:189], off offset:3072
	flat_load_dwordx4 v[192:195], v[166:167]
	flat_load_dwordx4 v[196:199], v[166:167] offset:64
	global_load_dwordx4 v[54:57], v[188:189], off offset:3136
	global_load_dwordx4 v[26:29], v[188:189], off offset:3200
	flat_load_dwordx4 v[244:247], v[166:167] offset:128
	global_load_dwordx4 v[10:13], v[188:189], off offset:3264
	flat_load_dwordx4 v[248:251], v[166:167] offset:192
	global_load_dwordx4 v[74:77], v[188:189], off offset:2048
	flat_load_dwordx4 v[78:81], v[174:175]
	flat_load_dwordx4 v[22:25], v[176:177]
	v_mad_u64_u32 v[186:187], s[10:11], v204, s66, v[182:183]
	v_mad_i32_i24 v187, v205, s66, v187
	s_mov_b32 s10, 0x800000
	s_waitcnt vmcnt(0)
	global_store_dwordx4 v[186:187], v[86:89], off offset:512
	s_waitcnt lgkmcnt(0)
	s_nop 0
	v_pk_mul_f32 v[86:87], v[48:49], v[194:195]
	v_pk_mul_f32 v[224:225], v[46:47], v[192:193]
	v_pk_mul_f32 v[88:89], v[86:87], v[86:87]
	v_pk_mul_f32 v[192:193], v[224:225], v[224:225]
	v_pk_mul_f32 v[200:201], v[56:57], v[198:199]
	v_pk_mov_b32 v[194:195], v[192:193], v[88:89] op_sel:[1,0]
	v_mov_b32_e32 v193, v89
	v_pk_mul_f32 v[202:203], v[54:55], v[196:197]
	v_pk_add_f32 v[88:89], v[194:195], v[192:193]
	v_pk_mul_f32 v[192:193], v[200:201], v[200:201]
	v_pk_mul_f32 v[194:195], v[202:203], v[202:203]
	v_pk_mul_f32 v[198:199], v[26:27], v[244:245]
	v_pk_mov_b32 v[196:197], v[194:195], v[192:193] op_sel:[1,0]
	v_mov_b32_e32 v195, v193
	v_pk_add_f32 v[218:219], v[196:197], v[194:195]
	v_pk_mul_f32 v[194:195], v[10:11], v[248:249]
	v_pk_add_f32 v[88:89], v[88:89], v[88:89] op_sel:[0,1] op_sel_hi:[1,0]
	v_pk_add_f32 v[218:219], v[218:219], v[218:219] op_sel:[0,1] op_sel_hi:[1,0]
	v_pk_mul_f32 v[196:197], v[28:29], v[246:247]
	v_mul_f32_e32 v89, v194, v194
	v_mul_f32_e32 v219, v195, v195
	v_mul_f32_e32 v130, v199, v199
	v_pk_add_f32 v[88:89], v[88:89], v[218:219]
	v_pk_fma_f32 v[218:219], v[198:199], v[198:199], v[130:131] op_sel_hi:[1,1,0]
	v_mul_f32_e32 v130, v197, v197
	v_pk_mul_f32 v[192:193], v[12:13], v[250:251]
	v_pk_fma_f32 v[244:245], v[196:197], v[196:197], v[130:131] op_sel_hi:[1,1,0]
	v_mul_f32_e32 v219, v192, v192
	v_mul_f32_e32 v245, v193, v193
	v_pk_add_f32 v[218:219], v[218:219], v[244:245]
	v_xor_b32_e32 v130, 16, v217
	v_pk_add_f32 v[88:89], v[88:89], v[218:219]
	s_nop 0
	v_add_f32_e32 v88, v88, v89
	v_and_b32_e32 v89, 64, v217
	v_add_u32_e32 v89, 64, v89
	v_cmp_lt_i32_e32 vcc, v130, v89
	s_nop 1
	v_cndmask_b32_e32 v130, v217, v130, vcc
	v_lshlrev_b32_e32 v244, 2, v130
	ds_bpermute_b32 v130, v244, v88
	s_waitcnt lgkmcnt(0)
	v_add_f32_e32 v88, v88, v130
	v_xor_b32_e32 v130, 32, v217
	v_cmp_lt_i32_e32 vcc, v130, v89
	s_nop 1
	v_cndmask_b32_e32 v89, v217, v130, vcc
	v_lshlrev_b32_e32 v245, 2, v89
	ds_bpermute_b32 v89, v245, v88
	s_waitcnt lgkmcnt(0)
	v_add_f32_e32 v88, v88, v89
	v_add_f32_e32 v88, 0x2b8cbccc, v88
	v_mul_f32_e32 v89, 0x4b800000, v88
	v_cmp_gt_f32_e32 vcc, s10, v88
	s_nop 1
	v_cndmask_b32_e32 v88, v88, v89, vcc
	v_rsq_f32_e32 v88, v88
	s_nop 0
	v_mul_f32_e32 v89, 0x45800000, v88
	v_cndmask_b32_e32 v130, v88, v89, vcc
	v_pk_mul_f32 v[88:89], v[86:87], v[130:131] op_sel_hi:[1,0]
	v_pk_mul_f32 v[86:87], v[224:225], v[130:131] op_sel_hi:[1,0]
	global_store_dwordx4 v[186:187], v[74:77], off
	global_store_dwordx4 v[186:187], v[86:89], off offset:256
	ds_read_b128 v[246:249], v255
	s_waitcnt lgkmcnt(0)
	v_add_f32_e32 v218, v94, v246
	v_add_f32_e32 v219, v95, v247
	v_add_f32_e32 v224, v96, v248
	v_add_f32_e32 v96, v97, v249
	ds_read_b128 v[246:249], v255 offset:128
	v_mul_f32_e32 v97, 0xbfb8aa3b, v218
	v_exp_f32_e32 v97, v97
	v_mad_u64_u32 v[94:95], s[10:11], v204, s66, v[184:185]
	v_mad_i32_i24 v95, v205, s66, v95
	v_add_f32_e32 v97, 1.0, v97
	v_div_scale_f32 v204, s[10:11], v97, v97, s45
	v_rcp_f32_e32 v205, v204
	v_mul_f32_e32 v224, 0xbfb8aa3b, v224
	v_exp_f32_e32 v224, v224
	v_mul_f32_e32 v96, 0xbfb8aa3b, v96
	v_fma_f32 v218, -v204, v205, 1.0
	v_fmac_f32_e32 v205, v218, v205
	v_div_scale_f32 v218, vcc, s45, v97, s45
	v_mul_f32_e32 v225, v218, v205
	v_add_f32_e32 v224, 1.0, v224
	v_exp_f32_e32 v96, v96
	s_waitcnt lgkmcnt(0)
	v_add_f32_e32 v90, v90, v246
	v_fma_f32 v246, -v204, v225, v218
	v_fmac_f32_e32 v225, v246, v205
	v_fma_f32 v204, -v204, v225, v218
	v_div_fmas_f32 v204, v204, v205, v225
	v_mul_f32_e32 v205, 0xbfb8aa3b, v219
	v_exp_f32_e32 v205, v205
	v_add_f32_e32 v91, v91, v247
	v_mul_f32_e32 v90, 0xbfb8aa3b, v90
	v_mul_f32_e32 v91, 0xbfb8aa3b, v91
	v_add_f32_e32 v205, 1.0, v205
	v_div_scale_f32 v218, s[10:11], v205, v205, s45
	v_rcp_f32_e32 v219, v218
	v_exp_f32_e32 v90, v90
	v_exp_f32_e32 v91, v91
	v_add_f32_e32 v92, v92, v248
	v_fma_f32 v225, -v218, v219, 1.0
	v_fmac_f32_e32 v219, v225, v219
	v_div_scale_f32 v225, vcc, s45, v205, s45
	v_mul_f32_e32 v246, v225, v219
	v_fma_f32 v247, -v218, v246, v225
	v_fmac_f32_e32 v246, v247, v219
	v_fma_f32 v218, -v218, v246, v225
	v_pk_add_f32 v[90:91], v[90:91], 1.0 op_sel_hi:[1,0]
	v_div_fmas_f32 v218, v218, v219, v246
	v_div_scale_f32 v219, s[10:11], v91, v91, 1.0
	v_rcp_f32_e32 v225, v219
	v_add_f32_e32 v93, v93, v249
	v_add_f32_e32 v96, 1.0, v96
	v_div_fixup_f32 v97, v204, v97, s45
	v_fma_f32 v246, -v219, v225, 1.0
	v_fmac_f32_e32 v225, v246, v225
	v_div_scale_f32 v246, vcc, 1.0, v91, 1.0
	v_mul_f32_e32 v247, v246, v225
	v_fma_f32 v248, -v219, v247, v246
	v_fmac_f32_e32 v247, v248, v225
	v_fma_f32 v219, -v219, v247, v246
	v_div_fmas_f32 v219, v219, v225, v247
	v_div_scale_f32 v225, s[10:11], v90, v90, 1.0
	v_rcp_f32_e32 v246, v225
	v_mul_f32_e32 v97, 0x3fb8aa3b, v97
	v_div_fixup_f32 v204, v218, v205, s45
	v_mul_f32_e32 v204, 0x3fb8aa3b, v204
	v_fma_f32 v247, -v225, v246, 1.0
	v_fmac_f32_e32 v246, v247, v246
	v_div_scale_f32 v247, vcc, 1.0, v90, 1.0
	v_mul_f32_e32 v248, v247, v246
	v_fma_f32 v249, -v225, v248, v247
	v_fmac_f32_e32 v248, v249, v246
	v_fma_f32 v225, -v225, v248, v247
	v_div_fmas_f32 v225, v225, v246, v248
	v_div_scale_f32 v246, s[10:11], v224, v224, s45
	v_rcp_f32_e32 v247, v246
	s_nop 0
	v_fma_f32 v248, -v246, v247, 1.0
	v_fmac_f32_e32 v247, v248, v247
	v_div_scale_f32 v248, vcc, s45, v224, s45
	v_mul_f32_e32 v249, v248, v247
	v_fma_f32 v250, -v246, v249, v248
	v_fmac_f32_e32 v249, v250, v247
	v_fma_f32 v246, -v246, v249, v248
	v_div_fmas_f32 v248, v246, v247, v249
	v_div_scale_f32 v246, s[10:11], v96, v96, s45
	v_rcp_f32_e32 v247, v246
	s_nop 0
	v_fma_f32 v249, -v246, v247, 1.0
	v_fmac_f32_e32 v247, v249, v247
	v_div_scale_f32 v249, vcc, s45, v96, s45
	v_mul_f32_e32 v250, v249, v247
	v_fma_f32 v251, -v246, v250, v249
	v_fmac_f32_e32 v250, v251, v247
	v_fma_f32 v246, -v246, v250, v249
	v_div_fmas_f32 v249, v246, v247, v250
	v_exp_f32_e32 v246, v97
	v_div_fixup_f32 v97, v248, v224, s45
	v_div_fixup_f32 v96, v249, v96, s45
	v_mul_f32_e32 v97, 0x3fb8aa3b, v97
	v_mul_f32_e32 v96, 0x3fb8aa3b, v96
	v_exp_f32_e32 v248, v97
	v_exp_f32_e32 v249, v96
	v_div_fixup_f32 v97, v219, v91, 1.0
	v_div_fixup_f32 v96, v225, v90, 1.0
	v_mul_f32_e32 v90, 0xbfb8aa3b, v92
	v_mul_f32_e32 v91, 0xbfb8aa3b, v93
	v_exp_f32_e32 v90, v90
	v_exp_f32_e32 v91, v91
	v_exp_f32_e32 v247, v204
	v_pk_add_f32 v[90:91], v[90:91], 1.0 op_sel_hi:[1,0]
	s_nop 0
	v_div_scale_f32 v92, s[10:11], v91, v91, 1.0
	v_rcp_f32_e32 v93, v92
	global_store_dwordx4 v[94:95], v[246:249], off
	v_fma_f32 v204, -v92, v93, 1.0
	v_fmac_f32_e32 v93, v204, v93
	v_div_scale_f32 v204, vcc, 1.0, v91, 1.0
	v_mul_f32_e32 v205, v204, v93
	v_fma_f32 v218, -v92, v205, v204
	v_fmac_f32_e32 v205, v218, v93
	v_fma_f32 v92, -v92, v205, v204
	v_div_fmas_f32 v92, v92, v93, v205
	v_div_scale_f32 v93, s[10:11], v90, v90, 1.0
	v_rcp_f32_e32 v204, v93
	s_nop 0
	v_fma_f32 v205, -v93, v204, 1.0
	v_fmac_f32_e32 v204, v205, v204
	v_div_scale_f32 v205, vcc, 1.0, v90, 1.0
	v_mul_f32_e32 v218, v205, v204
	v_fma_f32 v219, -v93, v218, v205
	v_fmac_f32_e32 v218, v219, v204
	v_fma_f32 v93, -v93, v218, v205
	v_div_fmas_f32 v93, v93, v204, v218
	v_div_fixup_f32 v205, v92, v91, 1.0
	v_div_fixup_f32 v204, v93, v90, 1.0
	v_xor_b32_e32 v91, 0x80000000, v97
	v_xor_b32_e32 v90, 0x80000000, v96
	v_xor_b32_e32 v93, 0x80000000, v205
	v_xor_b32_e32 v92, 0x80000000, v204
	v_pk_mul_f32 v[92:93], v[88:89], v[92:93]
	v_pk_mul_f32 v[90:91], v[86:87], v[90:91]
	global_store_dwordx4 v[94:95], v[90:93], off offset:256
	s_nop 1
	v_pk_add_f32 v[90:91], v[96:97], -1.0 op_sel_hi:[1,0]
	v_pk_add_f32 v[92:93], v[204:205], -1.0 op_sel_hi:[1,0]
	v_pk_fma_f32 v[90:91], v[78:79], v[90:91], 1.0 op_sel_hi:[1,1,0]
	v_pk_fma_f32 v[92:93], v[80:81], v[92:93], 1.0 op_sel_hi:[1,1,0]
	v_pk_mul_f32 v[90:91], v[46:47], v[90:91]
	v_pk_mul_f32 v[92:93], v[48:49], v[92:93]
	global_store_dwordx4 v[94:95], v[90:93], off offset:512
	ds_read_b128 v[246:249], v255 offset:64
	s_waitcnt lgkmcnt(0)
	v_add_f32_e32 v96, v82, v246
	v_add_f32_e32 v97, v83, v247
	v_add_f32_e32 v204, v84, v248
	v_add_f32_e32 v205, v85, v249
	ds_read_b128 v[82:85], v255 offset:192
	s_waitcnt lgkmcnt(0)
	v_add_f32_e32 v50, v50, v82
	v_mul_f32_e32 v82, 0xbfb8aa3b, v96
	v_exp_f32_e32 v82, v82
	v_add_f32_e32 v52, v52, v84
	v_add_f32_e32 v51, v51, v83
	v_add_f32_e32 v53, v53, v85
	v_add_f32_e32 v84, 1.0, v82
	v_div_scale_f32 v82, s[10:11], v84, v84, s45
	v_rcp_f32_e32 v83, v82
	v_mul_f32_e32 v50, 0xbfb8aa3b, v50
	v_mul_f32_e32 v51, 0xbfb8aa3b, v51
	v_exp_f32_e32 v50, v50
	v_fma_f32 v85, -v82, v83, 1.0
	v_fmac_f32_e32 v83, v85, v83
	v_div_scale_f32 v85, vcc, s45, v84, s45
	v_mul_f32_e32 v96, v85, v83
	v_fma_f32 v218, -v82, v96, v85
	v_fmac_f32_e32 v96, v218, v83
	v_fma_f32 v82, -v82, v96, v85
	v_div_fmas_f32 v85, v82, v83, v96
	v_mul_f32_e32 v82, 0xbfb8aa3b, v97
	v_exp_f32_e32 v82, v82
	v_exp_f32_e32 v51, v51
	v_mul_f32_e32 v52, 0xbfb8aa3b, v52
	v_mul_f32_e32 v53, 0xbfb8aa3b, v53
	v_add_f32_e32 v96, 1.0, v82
	v_div_scale_f32 v82, s[10:11], v96, v96, s45
	v_rcp_f32_e32 v83, v82
	v_pk_add_f32 v[50:51], v[50:51], 1.0 op_sel_hi:[1,0]
	v_exp_f32_e32 v52, v52
	v_exp_f32_e32 v53, v53
	v_fma_f32 v97, -v82, v83, 1.0
	v_fmac_f32_e32 v83, v97, v83
	v_div_scale_f32 v97, vcc, s45, v96, s45
	v_mul_f32_e32 v218, v97, v83
	v_fma_f32 v219, -v82, v218, v97
	v_fmac_f32_e32 v218, v219, v83
	v_fma_f32 v82, -v82, v218, v97
	v_div_fmas_f32 v97, v82, v83, v218
	v_div_scale_f32 v82, s[10:11], v51, v51, 1.0
	v_rcp_f32_e32 v83, v82
	v_pk_add_f32 v[52:53], v[52:53], 1.0 op_sel_hi:[1,0]
	v_fma_f32 v218, -v82, v83, 1.0
	v_fmac_f32_e32 v83, v218, v83
	v_div_scale_f32 v218, vcc, 1.0, v51, 1.0
	v_mul_f32_e32 v219, v218, v83
	v_fma_f32 v224, -v82, v219, v218
	v_fmac_f32_e32 v219, v224, v83
	v_fma_f32 v82, -v82, v219, v218
	v_div_fmas_f32 v82, v82, v83, v219
	v_div_scale_f32 v83, s[10:11], v50, v50, 1.0
	v_rcp_f32_e32 v218, v83
	v_div_fixup_f32 v51, v82, v51, 1.0
	v_mul_f32_e32 v82, 0xbfb8aa3b, v204
	v_exp_f32_e32 v82, v82
	v_fma_f32 v219, -v83, v218, 1.0
	v_fmac_f32_e32 v218, v219, v218
	v_div_scale_f32 v219, vcc, 1.0, v50, 1.0
	v_mul_f32_e32 v224, v219, v218
	v_fma_f32 v225, -v83, v224, v219
	v_fmac_f32_e32 v224, v225, v218
	v_fma_f32 v83, -v83, v224, v219
	v_add_f32_e32 v204, 1.0, v82
	v_div_fmas_f32 v83, v83, v218, v224
	v_div_scale_f32 v82, s[10:11], v204, v204, s45
	v_div_fixup_f32 v50, v83, v50, 1.0
	v_rcp_f32_e32 v83, v82
	s_nop 0
	v_fma_f32 v218, -v82, v83, 1.0
	v_fmac_f32_e32 v83, v218, v83
	v_div_scale_f32 v218, vcc, s45, v204, s45
	v_mul_f32_e32 v219, v218, v83
	v_fma_f32 v224, -v82, v219, v218
	v_fmac_f32_e32 v219, v224, v83
	v_fma_f32 v82, -v82, v219, v218
	v_div_fmas_f32 v218, v82, v83, v219
	v_mul_f32_e32 v82, 0xbfb8aa3b, v205
	v_exp_f32_e32 v82, v82
	s_nop 0
	v_add_f32_e32 v205, 1.0, v82
	v_div_scale_f32 v82, s[10:11], v205, v205, s45
	v_rcp_f32_e32 v83, v82
	s_nop 0
	v_fma_f32 v219, -v82, v83, 1.0
	v_fmac_f32_e32 v83, v219, v83
	v_div_scale_f32 v219, vcc, s45, v205, s45
	v_mul_f32_e32 v224, v219, v83
	v_fma_f32 v225, -v82, v224, v219
	v_fmac_f32_e32 v224, v225, v83
	v_fma_f32 v82, -v82, v224, v219
	v_div_fmas_f32 v219, v82, v83, v224
	v_div_scale_f32 v82, s[10:11], v53, v53, 1.0
	v_rcp_f32_e32 v83, v82
	s_nop 0
	v_fma_f32 v224, -v82, v83, 1.0
	v_fmac_f32_e32 v83, v224, v83
	v_div_scale_f32 v224, vcc, 1.0, v53, 1.0
	v_mul_f32_e32 v225, v224, v83
	v_fma_f32 v246, -v82, v225, v224
	v_fmac_f32_e32 v225, v246, v83
	v_fma_f32 v82, -v82, v225, v224
	v_div_fmas_f32 v82, v82, v83, v225
	v_div_scale_f32 v83, s[10:11], v52, v52, 1.0
	v_rcp_f32_e32 v224, v83
	v_div_fixup_f32 v53, v82, v53, 1.0
	s_mov_b32 s10, 0x1800000
	v_fma_f32 v225, -v83, v224, 1.0
	v_fmac_f32_e32 v224, v225, v224
	v_div_scale_f32 v225, vcc, 1.0, v52, 1.0
	v_mul_f32_e32 v246, v225, v224
	v_fma_f32 v247, -v83, v246, v225
	v_fmac_f32_e32 v246, v247, v224
	v_fma_f32 v83, -v83, v246, v225
	v_div_fmas_f32 v83, v83, v224, v246
	v_div_fixup_f32 v52, v83, v52, 1.0
	v_pk_add_f32 v[82:83], v[50:51], -1.0 op_sel_hi:[1,0]
	v_xor_b32_e32 v51, 0x80000000, v51
	v_pk_fma_f32 v[78:79], v[78:79], v[82:83], 1.0 op_sel_hi:[1,1,0]
	v_pk_add_f32 v[82:83], v[52:53], -1.0 op_sel_hi:[1,0]
	v_pk_mul_f32 v[46:47], v[46:47], v[78:79]
	v_pk_fma_f32 v[80:81], v[80:81], v[82:83], 1.0 op_sel_hi:[1,1,0]
	v_div_fixup_f32 v78, v85, v84, s45
	v_pk_mul_f32 v[48:49], v[48:49], v[80:81]
	v_div_fixup_f32 v79, v97, v96, s45
	v_div_fixup_f32 v80, v218, v204, s45
	v_div_fixup_f32 v81, v219, v205, s45
	v_mul_f32_e32 v78, 0x3fb8aa3b, v78
	v_mul_f32_e32 v79, 0x3fb8aa3b, v79
	v_mul_f32_e32 v80, 0x3fb8aa3b, v80
	v_mul_f32_e32 v81, 0x3fb8aa3b, v81
	v_exp_f32_e32 v78, v78
	v_exp_f32_e32 v79, v79
	v_exp_f32_e32 v80, v80
	v_exp_f32_e32 v81, v81
	v_add_co_u32_e32 v82, vcc, s10, v94
	v_xor_b32_e32 v50, 0x80000000, v50
	v_xor_b32_e32 v53, 0x80000000, v53
	v_xor_b32_e32 v52, 0x80000000, v52
	v_addc_co_u32_e32 v83, vcc, 0, v95, vcc
	v_pk_mul_f32 v[52:53], v[88:89], v[52:53]
	v_pk_mul_f32 v[50:51], v[86:87], v[50:51]
	global_store_dwordx4 v[82:83], v[78:81], off
	global_store_dwordx4 v[82:83], v[50:53], off offset:256
	v_mul_f32_e32 v88, v74, v46
	v_mul_f32_e32 v89, v75, v47
	global_store_dwordx4 v[82:83], v[46:49], off offset:512
	v_mul_f32_e32 v84, v74, v90
	v_mul_f32_e32 v85, v75, v91
	v_lshl_add_u64 v[46:47], v[168:169], 2, v[190:191]
	v_mul_f32_e32 v86, v76, v92
	v_mul_f32_e32 v87, v77, v93
	v_mul_f32_e32 v90, v76, v48
	v_mul_f32_e32 v91, v77, v49
	global_load_dwordx4 v[74:77], v[46:47], off
	s_nop 0
	global_load_dwordx4 v[46:49], v[188:189], off offset:2112
	flat_load_dwordx4 v[78:81], v[174:175] offset:64
	flat_load_dwordx4 v[50:53], v[176:177] offset:64
	s_waitcnt vmcnt(0)
	global_store_dwordx4 v[186:187], v[74:77], off offset:576
	s_nop 1
	v_pk_mul_f32 v[76:77], v[200:201], v[130:131] op_sel_hi:[1,0]
	v_pk_mul_f32 v[74:75], v[202:203], v[130:131] op_sel_hi:[1,0]
	global_store_dwordx4 v[186:187], v[46:49], off offset:64
	global_store_dwordx4 v[186:187], v[74:77], off offset:320
	ds_read_b128 v[200:203], v255 offset:16
	s_waitcnt lgkmcnt(0)
	v_add_f32_e32 v92, v70, v200
	v_add_f32_e32 v93, v71, v201
	v_add_f32_e32 v96, v72, v202
	v_add_f32_e32 v97, v73, v203
	ds_read_b128 v[70:73], v255 offset:144
	s_waitcnt lgkmcnt(0)
	v_add_f32_e32 v72, v68, v72
	v_mul_f32_e32 v68, 0xbfb8aa3b, v92
	v_exp_f32_e32 v68, v68
	v_add_f32_e32 v73, v69, v73
	v_add_f32_e32 v66, v66, v70
	v_add_f32_e32 v67, v67, v71
	v_add_f32_e32 v68, 1.0, v68
	v_div_scale_f32 v69, s[10:11], v68, v68, s45
	v_rcp_f32_e32 v70, v69
	v_mul_f32_e32 v66, 0xbfb8aa3b, v66
	v_mul_f32_e32 v67, 0xbfb8aa3b, v67
	v_exp_f32_e32 v66, v66
	v_fma_f32 v71, -v69, v70, 1.0
	v_fmac_f32_e32 v70, v71, v70
	v_div_scale_f32 v71, vcc, s45, v68, s45
	v_mul_f32_e32 v92, v71, v70
	v_fma_f32 v200, -v69, v92, v71
	v_fmac_f32_e32 v92, v200, v70
	v_fma_f32 v69, -v69, v92, v71
	v_div_fmas_f32 v69, v69, v70, v92
	v_mul_f32_e32 v70, 0xbfb8aa3b, v93
	v_exp_f32_e32 v70, v70
	v_exp_f32_e32 v67, v67
	v_add_f32_e32 v92, 1.0, v70
	v_div_scale_f32 v70, s[10:11], v92, v92, s45
	v_rcp_f32_e32 v71, v70
	s_nop 0
	v_fma_f32 v93, -v70, v71, 1.0
	v_fmac_f32_e32 v71, v93, v71
	v_div_scale_f32 v93, vcc, s45, v92, s45
	v_mul_f32_e32 v200, v93, v71
	v_fma_f32 v201, -v70, v200, v93
	v_fmac_f32_e32 v200, v201, v71
	v_fma_f32 v70, -v70, v200, v93
	v_div_fmas_f32 v93, v70, v71, v200
	v_pk_add_f32 v[70:71], v[66:67], 1.0 op_sel_hi:[1,0]
	s_nop 0
	v_div_scale_f32 v66, s[10:11], v71, v71, 1.0
	v_rcp_f32_e32 v67, v66
	s_nop 0
	v_fma_f32 v200, -v66, v67, 1.0
	v_fmac_f32_e32 v67, v200, v67
	v_div_scale_f32 v200, vcc, 1.0, v71, 1.0
	v_mul_f32_e32 v201, v200, v67
	v_fma_f32 v202, -v66, v201, v200
	v_fmac_f32_e32 v201, v202, v67
	v_fma_f32 v66, -v66, v201, v200
	v_div_fmas_f32 v200, v66, v67, v201
	v_div_scale_f32 v66, s[10:11], v70, v70, 1.0
	v_rcp_f32_e32 v67, v66
	v_div_fixup_f32 v71, v200, v71, 1.0
	v_fma_f32 v201, -v66, v67, 1.0
	v_fmac_f32_e32 v67, v201, v67
	v_div_scale_f32 v201, vcc, 1.0, v70, 1.0
	v_mul_f32_e32 v202, v201, v67
	v_fma_f32 v203, -v66, v202, v201
	v_fmac_f32_e32 v202, v203, v67
	v_fma_f32 v66, -v66, v202, v201
	v_div_fmas_f32 v201, v66, v67, v202
	v_mul_f32_e32 v66, 0xbfb8aa3b, v96
	v_exp_f32_e32 v66, v66
	v_div_fixup_f32 v70, v201, v70, 1.0
	v_add_f32_e32 v96, 1.0, v66
	v_div_scale_f32 v66, s[10:11], v96, v96, s45
	v_rcp_f32_e32 v67, v66
	s_nop 0
	v_fma_f32 v202, -v66, v67, 1.0
	v_fmac_f32_e32 v67, v202, v67
	v_div_scale_f32 v202, vcc, s45, v96, s45
	v_mul_f32_e32 v203, v202, v67
	v_fma_f32 v204, -v66, v203, v202
	v_fmac_f32_e32 v203, v204, v67
	v_fma_f32 v66, -v66, v203, v202
	v_div_fmas_f32 v202, v66, v67, v203
	v_mul_f32_e32 v66, 0xbfb8aa3b, v97
	v_exp_f32_e32 v66, v66
	s_nop 0
	v_add_f32_e32 v97, 1.0, v66
	v_div_scale_f32 v66, s[10:11], v97, v97, s45
	v_rcp_f32_e32 v67, v66
	s_nop 0
	v_fma_f32 v203, -v66, v67, 1.0
	v_fmac_f32_e32 v67, v203, v67
	v_div_scale_f32 v203, vcc, s45, v97, s45
	v_mul_f32_e32 v204, v203, v67
	v_fma_f32 v205, -v66, v204, v203
	v_fmac_f32_e32 v204, v205, v67
	v_fma_f32 v66, -v66, v204, v203
	v_div_fmas_f32 v203, v66, v67, v204
	v_div_fixup_f32 v66, v69, v68, s45
	v_div_fixup_f32 v67, v93, v92, s45
	v_div_fixup_f32 v68, v202, v96, s45
	v_div_fixup_f32 v69, v203, v97, s45
	v_mul_f32_e32 v66, 0x3fb8aa3b, v66
	v_mul_f32_e32 v67, 0x3fb8aa3b, v67
	v_mul_f32_e32 v68, 0x3fb8aa3b, v68
	v_mul_f32_e32 v69, 0x3fb8aa3b, v69
	v_exp_f32_e32 v66, v66
	v_exp_f32_e32 v67, v67
	v_exp_f32_e32 v68, v68
	v_exp_f32_e32 v69, v69
	global_store_dwordx4 v[94:95], v[66:69], off offset:64
	s_nop 1
	v_mul_f32_e32 v66, 0xbfb8aa3b, v72
	v_mul_f32_e32 v67, 0xbfb8aa3b, v73
	v_exp_f32_e32 v66, v66
	v_exp_f32_e32 v67, v67
	s_nop 0
	v_pk_add_f32 v[66:67], v[66:67], 1.0 op_sel_hi:[1,0]
	s_nop 0
	v_div_scale_f32 v68, s[10:11], v67, v67, 1.0
	v_rcp_f32_e32 v69, v68
	s_nop 0
	v_fma_f32 v72, -v68, v69, 1.0
	v_fmac_f32_e32 v69, v72, v69
	v_div_scale_f32 v72, vcc, 1.0, v67, 1.0
	v_mul_f32_e32 v73, v72, v69
	v_fma_f32 v92, -v68, v73, v72
	v_fmac_f32_e32 v73, v92, v69
	v_fma_f32 v68, -v68, v73, v72
	v_div_fmas_f32 v68, v68, v69, v73
	v_div_scale_f32 v69, s[10:11], v66, v66, 1.0
	v_rcp_f32_e32 v72, v69
	s_nop 0
	v_fma_f32 v73, -v69, v72, 1.0
	v_fmac_f32_e32 v72, v73, v72
	v_div_scale_f32 v73, vcc, 1.0, v66, 1.0
	v_mul_f32_e32 v92, v73, v72
	v_fma_f32 v93, -v69, v92, v73
	v_fmac_f32_e32 v92, v93, v72
	v_fma_f32 v69, -v69, v92, v73
	v_div_fmas_f32 v69, v69, v72, v92
	v_div_fixup_f32 v73, v68, v67, 1.0
	v_div_fixup_f32 v72, v69, v66, 1.0
	v_xor_b32_e32 v67, 0x80000000, v71
	v_xor_b32_e32 v66, 0x80000000, v70
	v_xor_b32_e32 v69, 0x80000000, v73
	v_xor_b32_e32 v68, 0x80000000, v72
	v_pk_mul_f32 v[68:69], v[76:77], v[68:69]
	v_pk_mul_f32 v[66:67], v[74:75], v[66:67]
	global_store_dwordx4 v[94:95], v[66:69], off offset:320
	s_nop 1
	v_pk_add_f32 v[66:67], v[70:71], -1.0 op_sel_hi:[1,0]
	v_pk_add_f32 v[68:69], v[72:73], -1.0 op_sel_hi:[1,0]
	v_pk_fma_f32 v[66:67], v[78:79], v[66:67], 1.0 op_sel_hi:[1,1,0]
	v_pk_fma_f32 v[68:69], v[80:81], v[68:69], 1.0 op_sel_hi:[1,1,0]
	v_pk_mul_f32 v[66:67], v[54:55], v[66:67]
	v_pk_mul_f32 v[68:69], v[56:57], v[68:69]
	global_store_dwordx4 v[94:95], v[66:69], off offset:576
	ds_read_b128 v[70:73], v255 offset:80
	s_waitcnt lgkmcnt(0)
	v_add_f32_e32 v70, v62, v70
	v_add_f32_e32 v71, v63, v71
	v_add_f32_e32 v72, v64, v72
	v_add_f32_e32 v73, v65, v73
	ds_read_b128 v[62:65], v255 offset:208
	s_waitcnt lgkmcnt(0)
	v_add_f32_e32 v58, v58, v62
	v_mul_f32_e32 v62, 0xbfb8aa3b, v70
	v_exp_f32_e32 v62, v62
	v_add_f32_e32 v59, v59, v63
	v_add_f32_e32 v60, v60, v64
	v_add_f32_e32 v61, v61, v65
	v_add_f32_e32 v70, 1.0, v62
	v_div_scale_f32 v62, s[10:11], v70, v70, s45
	v_rcp_f32_e32 v63, v62
	v_mul_f32_e32 v58, 0xbfb8aa3b, v58
	v_mul_f32_e32 v59, 0xbfb8aa3b, v59
	v_exp_f32_e32 v58, v58
	v_fma_f32 v64, -v62, v63, 1.0
	v_fmac_f32_e32 v63, v64, v63
	v_div_scale_f32 v64, vcc, s45, v70, s45
	v_mul_f32_e32 v65, v64, v63
	v_fma_f32 v92, -v62, v65, v64
	v_fmac_f32_e32 v65, v92, v63
	v_fma_f32 v62, -v62, v65, v64
	v_div_fmas_f32 v92, v62, v63, v65
	v_mul_f32_e32 v62, 0xbfb8aa3b, v71
	v_exp_f32_e32 v62, v62
	v_exp_f32_e32 v59, v59
	v_mul_f32_e32 v60, 0xbfb8aa3b, v60
	v_mul_f32_e32 v61, 0xbfb8aa3b, v61
	v_add_f32_e32 v71, 1.0, v62
	v_div_scale_f32 v62, s[10:11], v71, v71, s45
	v_rcp_f32_e32 v63, v62
	v_pk_add_f32 v[58:59], v[58:59], 1.0 op_sel_hi:[1,0]
	v_exp_f32_e32 v60, v60
	v_exp_f32_e32 v61, v61
	v_fma_f32 v64, -v62, v63, 1.0
	v_fmac_f32_e32 v63, v64, v63
	v_div_scale_f32 v64, vcc, s45, v71, s45
	v_mul_f32_e32 v65, v64, v63
	v_fma_f32 v93, -v62, v65, v64
	v_fmac_f32_e32 v65, v93, v63
	v_fma_f32 v62, -v62, v65, v64
	v_div_fmas_f32 v93, v62, v63, v65
	v_div_scale_f32 v62, s[10:11], v59, v59, 1.0
	v_rcp_f32_e32 v63, v62
	v_pk_add_f32 v[60:61], v[60:61], 1.0 op_sel_hi:[1,0]
	v_fma_f32 v64, -v62, v63, 1.0
	v_fmac_f32_e32 v63, v64, v63
	v_div_scale_f32 v64, vcc, 1.0, v59, 1.0
	v_mul_f32_e32 v65, v64, v63
	v_fma_f32 v96, -v62, v65, v64
	v_fmac_f32_e32 v65, v96, v63
	v_fma_f32 v62, -v62, v65, v64
	v_div_fmas_f32 v62, v62, v63, v65
	v_div_scale_f32 v63, s[10:11], v58, v58, 1.0
	v_rcp_f32_e32 v64, v63
	v_div_fixup_f32 v59, v62, v59, 1.0
	v_mul_f32_e32 v62, 0xbfb8aa3b, v72
	v_exp_f32_e32 v62, v62
	v_fma_f32 v65, -v63, v64, 1.0
	v_fmac_f32_e32 v64, v65, v64
	v_div_scale_f32 v65, vcc, 1.0, v58, 1.0
	v_mul_f32_e32 v96, v65, v64
	v_fma_f32 v97, -v63, v96, v65
	v_fmac_f32_e32 v96, v97, v64
	v_fma_f32 v63, -v63, v96, v65
	v_add_f32_e32 v72, 1.0, v62
	v_div_fmas_f32 v63, v63, v64, v96
	v_div_scale_f32 v62, s[10:11], v72, v72, s45
	v_div_fixup_f32 v58, v63, v58, 1.0
	v_rcp_f32_e32 v63, v62
	s_nop 0
	v_fma_f32 v64, -v62, v63, 1.0
	v_fmac_f32_e32 v63, v64, v63
	v_div_scale_f32 v64, vcc, s45, v72, s45
	v_mul_f32_e32 v65, v64, v63
	v_fma_f32 v96, -v62, v65, v64
	v_fmac_f32_e32 v65, v96, v63
	v_fma_f32 v62, -v62, v65, v64
	v_div_fmas_f32 v96, v62, v63, v65
	v_mul_f32_e32 v62, 0xbfb8aa3b, v73
	v_exp_f32_e32 v62, v62
	s_nop 0
	v_add_f32_e32 v73, 1.0, v62
	v_div_scale_f32 v62, s[10:11], v73, v73, s45
	v_rcp_f32_e32 v63, v62
	s_nop 0
	v_fma_f32 v64, -v62, v63, 1.0
	v_fmac_f32_e32 v63, v64, v63
	v_div_scale_f32 v64, vcc, s45, v73, s45
	v_mul_f32_e32 v65, v64, v63
	v_fma_f32 v97, -v62, v65, v64
	v_fmac_f32_e32 v65, v97, v63
	v_fma_f32 v62, -v62, v65, v64
	v_div_fmas_f32 v97, v62, v63, v65
	v_div_scale_f32 v62, s[10:11], v61, v61, 1.0
	v_rcp_f32_e32 v63, v62
	s_nop 0
	v_fma_f32 v64, -v62, v63, 1.0
	v_fmac_f32_e32 v63, v64, v63
	v_div_scale_f32 v64, vcc, 1.0, v61, 1.0
	v_mul_f32_e32 v65, v64, v63
	v_fma_f32 v200, -v62, v65, v64
	v_fmac_f32_e32 v65, v200, v63
	v_fma_f32 v62, -v62, v65, v64
	v_div_fmas_f32 v62, v62, v63, v65
	v_div_scale_f32 v63, s[10:11], v60, v60, 1.0
	v_rcp_f32_e32 v64, v63
	v_div_fixup_f32 v61, v62, v61, 1.0
	v_fma_f32 v65, -v63, v64, 1.0
	v_fmac_f32_e32 v64, v65, v64
	v_div_scale_f32 v65, vcc, 1.0, v60, 1.0
	v_mul_f32_e32 v200, v65, v64
	v_fma_f32 v201, -v63, v200, v65
	v_fmac_f32_e32 v200, v201, v64
	v_fma_f32 v63, -v63, v200, v65
	v_div_fmas_f32 v63, v63, v64, v200
	v_div_fixup_f32 v60, v63, v60, 1.0
	v_pk_add_f32 v[62:63], v[58:59], -1.0 op_sel_hi:[1,0]
	v_pk_add_f32 v[64:65], v[60:61], -1.0 op_sel_hi:[1,0]
	v_pk_fma_f32 v[62:63], v[78:79], v[62:63], 1.0 op_sel_hi:[1,1,0]
	v_pk_fma_f32 v[64:65], v[80:81], v[64:65], 1.0 op_sel_hi:[1,1,0]
	v_pk_mul_f32 v[54:55], v[54:55], v[62:63]
	v_pk_mul_f32 v[56:57], v[56:57], v[64:65]
	v_div_fixup_f32 v62, v92, v70, s45
	v_div_fixup_f32 v63, v93, v71, s45
	v_div_fixup_f32 v64, v96, v72, s45
	v_div_fixup_f32 v65, v97, v73, s45
	v_mul_f32_e32 v62, 0x3fb8aa3b, v62
	v_mul_f32_e32 v63, 0x3fb8aa3b, v63
	v_mul_f32_e32 v64, 0x3fb8aa3b, v64
	v_mul_f32_e32 v65, 0x3fb8aa3b, v65
	v_exp_f32_e32 v62, v62
	v_exp_f32_e32 v63, v63
	v_exp_f32_e32 v64, v64
	v_exp_f32_e32 v65, v65
	v_xor_b32_e32 v59, 0x80000000, v59
	v_xor_b32_e32 v58, 0x80000000, v58
	v_xor_b32_e32 v61, 0x80000000, v61
	v_xor_b32_e32 v60, 0x80000000, v60
	v_pk_mul_f32 v[58:59], v[74:75], v[58:59]
	v_pk_mul_f32 v[60:61], v[76:77], v[60:61]
	global_store_dwordx4 v[82:83], v[62:65], off offset:64
	global_store_dwordx4 v[82:83], v[58:61], off offset:320
	global_store_dwordx4 v[82:83], v[54:57], off offset:576
	s_nop 0
	v_lshl_add_u64 v[58:59], v[170:171], 2, v[190:191]
	global_load_dwordx4 v[70:73], v[58:59], off
	s_nop 0
	global_load_dwordx4 v[58:61], v[188:189], off offset:2176
	flat_load_dwordx4 v[74:77], v[174:175] offset:128
	flat_load_dwordx4 v[62:65], v[176:177] offset:128
	s_waitcnt vmcnt(0)
	global_store_dwordx4 v[186:187], v[70:73], off offset:640
	s_nop 1
	v_pk_mul_f32 v[72:73], v[196:197], v[130:131] op_sel_hi:[1,0]
	v_pk_mul_f32 v[70:71], v[198:199], v[130:131] op_sel_hi:[1,0]
	global_store_dwordx4 v[186:187], v[58:61], off offset:128
	global_store_dwordx4 v[186:187], v[70:73], off offset:384
	ds_read_b128 v[78:81], v255 offset:32
	s_waitcnt lgkmcnt(0)
	v_add_f32_e32 v78, v42, v78
	v_add_f32_e32 v79, v43, v79
	v_add_f32_e32 v80, v44, v80
	v_add_f32_e32 v81, v45, v81
	ds_read_b128 v[42:45], v255 offset:160
	s_waitcnt lgkmcnt(0)
	v_add_f32_e32 v44, v40, v44
	v_mul_f32_e32 v40, 0xbfb8aa3b, v78
	v_exp_f32_e32 v40, v40
	v_add_f32_e32 v45, v41, v45
	v_add_f32_e32 v38, v38, v42
	v_add_f32_e32 v39, v39, v43
	v_add_f32_e32 v40, 1.0, v40
	v_div_scale_f32 v41, s[10:11], v40, v40, s45
	v_rcp_f32_e32 v42, v41
	v_mul_f32_e32 v38, 0xbfb8aa3b, v38
	v_mul_f32_e32 v39, 0xbfb8aa3b, v39
	v_exp_f32_e32 v38, v38
	v_fma_f32 v43, -v41, v42, 1.0
	v_fmac_f32_e32 v42, v43, v42
	v_div_scale_f32 v43, vcc, s45, v40, s45
	v_mul_f32_e32 v78, v43, v42
	v_fma_f32 v92, -v41, v78, v43
	v_fmac_f32_e32 v78, v92, v42
	v_fma_f32 v41, -v41, v78, v43
	v_div_fmas_f32 v41, v41, v42, v78
	v_mul_f32_e32 v42, 0xbfb8aa3b, v79
	v_exp_f32_e32 v42, v42
	v_exp_f32_e32 v39, v39
	v_add_f32_e32 v78, 1.0, v42
	v_div_scale_f32 v42, s[10:11], v78, v78, s45
	v_rcp_f32_e32 v43, v42
	s_nop 0
	v_fma_f32 v79, -v42, v43, 1.0
	v_fmac_f32_e32 v43, v79, v43
	v_div_scale_f32 v79, vcc, s45, v78, s45
	v_mul_f32_e32 v92, v79, v43
	v_fma_f32 v93, -v42, v92, v79
	v_fmac_f32_e32 v92, v93, v43
	v_fma_f32 v42, -v42, v92, v79
	v_div_fmas_f32 v79, v42, v43, v92
	v_pk_add_f32 v[42:43], v[38:39], 1.0 op_sel_hi:[1,0]
	s_nop 0
	v_div_scale_f32 v38, s[10:11], v43, v43, 1.0
	v_rcp_f32_e32 v39, v38
	s_nop 0
	v_fma_f32 v92, -v38, v39, 1.0
	v_fmac_f32_e32 v39, v92, v39
	v_div_scale_f32 v92, vcc, 1.0, v43, 1.0
	v_mul_f32_e32 v93, v92, v39
	v_fma_f32 v96, -v38, v93, v92
	v_fmac_f32_e32 v93, v96, v39
	v_fma_f32 v38, -v38, v93, v92
	v_div_fmas_f32 v92, v38, v39, v93
	v_div_scale_f32 v38, s[10:11], v42, v42, 1.0
	v_rcp_f32_e32 v39, v38
	v_div_fixup_f32 v43, v92, v43, 1.0
	v_fma_f32 v93, -v38, v39, 1.0
	v_fmac_f32_e32 v39, v93, v39
	v_div_scale_f32 v93, vcc, 1.0, v42, 1.0
	v_mul_f32_e32 v96, v93, v39
	v_fma_f32 v97, -v38, v96, v93
	v_fmac_f32_e32 v96, v97, v39
	v_fma_f32 v38, -v38, v96, v93
	v_div_fmas_f32 v93, v38, v39, v96
	v_mul_f32_e32 v38, 0xbfb8aa3b, v80
	v_exp_f32_e32 v38, v38
	v_div_fixup_f32 v42, v93, v42, 1.0
	v_add_f32_e32 v80, 1.0, v38
	v_div_scale_f32 v38, s[10:11], v80, v80, s45
	v_rcp_f32_e32 v39, v38
	s_nop 0
	v_fma_f32 v96, -v38, v39, 1.0
	v_fmac_f32_e32 v39, v96, v39
	v_div_scale_f32 v96, vcc, s45, v80, s45
	v_mul_f32_e32 v97, v96, v39
	v_fma_f32 v196, -v38, v97, v96
	v_fmac_f32_e32 v97, v196, v39
	v_fma_f32 v38, -v38, v97, v96
	v_div_fmas_f32 v96, v38, v39, v97
	v_mul_f32_e32 v38, 0xbfb8aa3b, v81
	v_exp_f32_e32 v38, v38
	s_nop 0
	v_add_f32_e32 v81, 1.0, v38
	v_div_scale_f32 v38, s[10:11], v81, v81, s45
	v_rcp_f32_e32 v39, v38
	s_nop 0
	v_fma_f32 v97, -v38, v39, 1.0
	v_fmac_f32_e32 v39, v97, v39
	v_div_scale_f32 v97, vcc, s45, v81, s45
	v_mul_f32_e32 v196, v97, v39
	v_fma_f32 v197, -v38, v196, v97
	v_fmac_f32_e32 v196, v197, v39
	v_fma_f32 v38, -v38, v196, v97
	v_div_fmas_f32 v97, v38, v39, v196
	v_div_fixup_f32 v38, v41, v40, s45
	v_div_fixup_f32 v39, v79, v78, s45
	v_div_fixup_f32 v40, v96, v80, s45
	v_div_fixup_f32 v41, v97, v81, s45
	v_mul_f32_e32 v38, 0x3fb8aa3b, v38
	v_mul_f32_e32 v39, 0x3fb8aa3b, v39
	v_mul_f32_e32 v40, 0x3fb8aa3b, v40
	v_mul_f32_e32 v41, 0x3fb8aa3b, v41
	v_exp_f32_e32 v38, v38
	v_exp_f32_e32 v39, v39
	v_exp_f32_e32 v40, v40
	v_exp_f32_e32 v41, v41
	global_store_dwordx4 v[94:95], v[38:41], off offset:128
	s_nop 1
	v_mul_f32_e32 v38, 0xbfb8aa3b, v44
	v_mul_f32_e32 v39, 0xbfb8aa3b, v45
	v_exp_f32_e32 v38, v38
	v_exp_f32_e32 v39, v39
	s_nop 0
	v_pk_add_f32 v[38:39], v[38:39], 1.0 op_sel_hi:[1,0]
	s_nop 0
	v_div_scale_f32 v40, s[10:11], v39, v39, 1.0
	v_rcp_f32_e32 v41, v40
	s_nop 0
	v_fma_f32 v44, -v40, v41, 1.0
	v_fmac_f32_e32 v41, v44, v41
	v_div_scale_f32 v44, vcc, 1.0, v39, 1.0
	v_mul_f32_e32 v45, v44, v41
	v_fma_f32 v78, -v40, v45, v44
	v_fmac_f32_e32 v45, v78, v41
	v_fma_f32 v40, -v40, v45, v44
	v_div_fmas_f32 v40, v40, v41, v45
	v_div_scale_f32 v41, s[10:11], v38, v38, 1.0
	v_rcp_f32_e32 v44, v41
	s_nop 0
	v_fma_f32 v45, -v41, v44, 1.0
	v_fmac_f32_e32 v44, v45, v44
	v_div_scale_f32 v45, vcc, 1.0, v38, 1.0
	v_mul_f32_e32 v78, v45, v44
	v_fma_f32 v79, -v41, v78, v45
	v_fmac_f32_e32 v78, v79, v44
	v_fma_f32 v41, -v41, v78, v45
	v_div_fmas_f32 v41, v41, v44, v78
	v_div_fixup_f32 v45, v40, v39, 1.0
	v_div_fixup_f32 v44, v41, v38, 1.0
	v_xor_b32_e32 v39, 0x80000000, v43
	v_xor_b32_e32 v38, 0x80000000, v42
	v_xor_b32_e32 v41, 0x80000000, v45
	v_xor_b32_e32 v40, 0x80000000, v44
	v_pk_mul_f32 v[40:41], v[72:73], v[40:41]
	v_pk_mul_f32 v[38:39], v[70:71], v[38:39]
	global_store_dwordx4 v[94:95], v[38:41], off offset:384
	s_nop 1
	v_pk_add_f32 v[38:39], v[42:43], -1.0 op_sel_hi:[1,0]
	v_pk_add_f32 v[40:41], v[44:45], -1.0 op_sel_hi:[1,0]
	v_pk_fma_f32 v[38:39], v[74:75], v[38:39], 1.0 op_sel_hi:[1,1,0]
	v_pk_fma_f32 v[40:41], v[76:77], v[40:41], 1.0 op_sel_hi:[1,1,0]
	v_pk_mul_f32 v[38:39], v[26:27], v[38:39]
	v_pk_mul_f32 v[40:41], v[28:29], v[40:41]
	global_store_dwordx4 v[94:95], v[38:41], off offset:640
	ds_read_b128 v[42:45], v255 offset:96
	s_waitcnt lgkmcnt(0)
	v_add_f32_e32 v42, v34, v42
	v_add_f32_e32 v43, v35, v43
	v_add_f32_e32 v44, v36, v44
	v_add_f32_e32 v45, v37, v45
	ds_read_b128 v[34:37], v255 offset:224
	s_waitcnt lgkmcnt(0)
	v_add_f32_e32 v30, v30, v34
	v_mul_f32_e32 v34, 0xbfb8aa3b, v42
	v_exp_f32_e32 v34, v34
	v_add_f32_e32 v31, v31, v35
	v_add_f32_e32 v32, v32, v36
	v_add_f32_e32 v33, v33, v37
	v_add_f32_e32 v42, 1.0, v34
	v_div_scale_f32 v34, s[10:11], v42, v42, s45
	v_rcp_f32_e32 v35, v34
	v_mul_f32_e32 v30, 0xbfb8aa3b, v30
	v_mul_f32_e32 v31, 0xbfb8aa3b, v31
	v_exp_f32_e32 v30, v30
	v_fma_f32 v36, -v34, v35, 1.0
	v_fmac_f32_e32 v35, v36, v35
	v_div_scale_f32 v36, vcc, s45, v42, s45
	v_mul_f32_e32 v37, v36, v35
	v_fma_f32 v78, -v34, v37, v36
	v_fmac_f32_e32 v37, v78, v35
	v_fma_f32 v34, -v34, v37, v36
	v_div_fmas_f32 v78, v34, v35, v37
	v_mul_f32_e32 v34, 0xbfb8aa3b, v43
	v_exp_f32_e32 v34, v34
	v_exp_f32_e32 v31, v31
	v_mul_f32_e32 v32, 0xbfb8aa3b, v32
	v_mul_f32_e32 v33, 0xbfb8aa3b, v33
	v_add_f32_e32 v43, 1.0, v34
	v_div_scale_f32 v34, s[10:11], v43, v43, s45
	v_rcp_f32_e32 v35, v34
	v_pk_add_f32 v[30:31], v[30:31], 1.0 op_sel_hi:[1,0]
	v_exp_f32_e32 v32, v32
	v_exp_f32_e32 v33, v33
	v_fma_f32 v36, -v34, v35, 1.0
	v_fmac_f32_e32 v35, v36, v35
	v_div_scale_f32 v36, vcc, s45, v43, s45
	v_mul_f32_e32 v37, v36, v35
	v_fma_f32 v79, -v34, v37, v36
	v_fmac_f32_e32 v37, v79, v35
	v_fma_f32 v34, -v34, v37, v36
	v_div_fmas_f32 v79, v34, v35, v37
	v_div_scale_f32 v34, s[10:11], v31, v31, 1.0
	v_rcp_f32_e32 v35, v34
	v_pk_add_f32 v[32:33], v[32:33], 1.0 op_sel_hi:[1,0]
	v_fma_f32 v36, -v34, v35, 1.0
	v_fmac_f32_e32 v35, v36, v35
	v_div_scale_f32 v36, vcc, 1.0, v31, 1.0
	v_mul_f32_e32 v37, v36, v35
	v_fma_f32 v80, -v34, v37, v36
	v_fmac_f32_e32 v37, v80, v35
	v_fma_f32 v34, -v34, v37, v36
	v_div_fmas_f32 v34, v34, v35, v37
	v_div_scale_f32 v35, s[10:11], v30, v30, 1.0
	v_rcp_f32_e32 v36, v35
	v_div_fixup_f32 v31, v34, v31, 1.0
	v_mul_f32_e32 v34, 0xbfb8aa3b, v44
	v_exp_f32_e32 v34, v34
	v_fma_f32 v37, -v35, v36, 1.0
	v_fmac_f32_e32 v36, v37, v36
	v_div_scale_f32 v37, vcc, 1.0, v30, 1.0
	v_mul_f32_e32 v80, v37, v36
	v_fma_f32 v81, -v35, v80, v37
	v_fmac_f32_e32 v80, v81, v36
	v_fma_f32 v35, -v35, v80, v37
	v_add_f32_e32 v44, 1.0, v34
	v_div_fmas_f32 v35, v35, v36, v80
	v_div_scale_f32 v34, s[10:11], v44, v44, s45
	v_div_fixup_f32 v30, v35, v30, 1.0
	v_rcp_f32_e32 v35, v34
	s_nop 0
	v_fma_f32 v36, -v34, v35, 1.0
	v_fmac_f32_e32 v35, v36, v35
	v_div_scale_f32 v36, vcc, s45, v44, s45
	v_mul_f32_e32 v37, v36, v35
	v_fma_f32 v80, -v34, v37, v36
	v_fmac_f32_e32 v37, v80, v35
	v_fma_f32 v34, -v34, v37, v36
	v_div_fmas_f32 v80, v34, v35, v37
	v_mul_f32_e32 v34, 0xbfb8aa3b, v45
	v_exp_f32_e32 v34, v34
	s_nop 0
	v_add_f32_e32 v45, 1.0, v34
	v_div_scale_f32 v34, s[10:11], v45, v45, s45
	v_rcp_f32_e32 v35, v34
	s_nop 0
	v_fma_f32 v36, -v34, v35, 1.0
	v_fmac_f32_e32 v35, v36, v35
	v_div_scale_f32 v36, vcc, s45, v45, s45
	v_mul_f32_e32 v37, v36, v35
	v_fma_f32 v81, -v34, v37, v36
	v_fmac_f32_e32 v37, v81, v35
	v_fma_f32 v34, -v34, v37, v36
	v_div_fmas_f32 v81, v34, v35, v37
	v_div_scale_f32 v34, s[10:11], v33, v33, 1.0
	v_rcp_f32_e32 v35, v34
	s_nop 0
	v_fma_f32 v36, -v34, v35, 1.0
	v_fmac_f32_e32 v35, v36, v35
	v_div_scale_f32 v36, vcc, 1.0, v33, 1.0
	v_mul_f32_e32 v37, v36, v35
	v_fma_f32 v92, -v34, v37, v36
	v_fmac_f32_e32 v37, v92, v35
	v_fma_f32 v34, -v34, v37, v36
	v_div_fmas_f32 v34, v34, v35, v37
	v_div_scale_f32 v35, s[10:11], v32, v32, 1.0
	v_rcp_f32_e32 v36, v35
	v_div_fixup_f32 v33, v34, v33, 1.0
	v_fma_f32 v37, -v35, v36, 1.0
	v_fmac_f32_e32 v36, v37, v36
	v_div_scale_f32 v37, vcc, 1.0, v32, 1.0
	v_mul_f32_e32 v92, v37, v36
	v_fma_f32 v93, -v35, v92, v37
	v_fmac_f32_e32 v92, v93, v36
	v_fma_f32 v35, -v35, v92, v37
	v_div_fmas_f32 v35, v35, v36, v92
	v_div_fixup_f32 v32, v35, v32, 1.0
	v_pk_add_f32 v[34:35], v[30:31], -1.0 op_sel_hi:[1,0]
	v_pk_add_f32 v[36:37], v[32:33], -1.0 op_sel_hi:[1,0]
	v_pk_fma_f32 v[34:35], v[74:75], v[34:35], 1.0 op_sel_hi:[1,1,0]
	v_pk_fma_f32 v[36:37], v[76:77], v[36:37], 1.0 op_sel_hi:[1,1,0]
	v_pk_mul_f32 v[74:75], v[26:27], v[34:35]
	v_pk_mul_f32 v[76:77], v[28:29], v[36:37]
	v_xor_b32_e32 v27, 0x80000000, v31
	v_xor_b32_e32 v26, 0x80000000, v30
	v_xor_b32_e32 v29, 0x80000000, v33
	v_xor_b32_e32 v28, 0x80000000, v32
	v_div_fixup_f32 v30, v78, v42, s45
	v_div_fixup_f32 v31, v79, v43, s45
	v_div_fixup_f32 v32, v80, v44, s45
	v_div_fixup_f32 v33, v81, v45, s45
	v_mul_f32_e32 v30, 0x3fb8aa3b, v30
	v_mul_f32_e32 v31, 0x3fb8aa3b, v31
	v_mul_f32_e32 v32, 0x3fb8aa3b, v32
	v_mul_f32_e32 v33, 0x3fb8aa3b, v33
	v_exp_f32_e32 v30, v30
	v_exp_f32_e32 v31, v31
	v_exp_f32_e32 v32, v32
	v_exp_f32_e32 v33, v33
	v_pk_mul_f32 v[28:29], v[72:73], v[28:29]
	v_pk_mul_f32 v[26:27], v[70:71], v[26:27]
	global_store_dwordx4 v[82:83], v[30:33], off offset:128
	global_store_dwordx4 v[82:83], v[26:29], off offset:384
	global_store_dwordx4 v[82:83], v[74:77], off offset:640
	v_lshl_add_u64 v[30:31], v[172:173], 2, v[190:191]
	global_load_dwordx4 v[70:73], v[30:31], off
	s_nop 0
	global_load_dwordx4 v[30:33], v[188:189], off offset:2240
	flat_load_dwordx4 v[42:45], v[174:175] offset:192
	flat_load_dwordx4 v[34:37], v[176:177] offset:192
	v_pk_mul_f32 v[28:29], v[192:193], v[130:131] op_sel_hi:[1,0]
	v_pk_mul_f32 v[26:27], v[194:195], v[130:131] op_sel_hi:[1,0]
	s_waitcnt vmcnt(0)
	global_store_dwordx4 v[186:187], v[70:73], off offset:704
	global_store_dwordx4 v[186:187], v[30:33], off offset:192
	global_store_dwordx4 v[186:187], v[26:29], off offset:448
	ds_read_b128 v[70:73], v255 offset:48
	s_waitcnt lgkmcnt(0)
	v_add_f32_e32 v70, v18, v70
	v_add_f32_e32 v71, v19, v71
	v_add_f32_e32 v72, v20, v72
	v_add_f32_e32 v73, v21, v73
	ds_read_b128 v[18:21], v255 offset:176
	s_waitcnt lgkmcnt(0)
	v_add_f32_e32 v15, v15, v19
	v_add_f32_e32 v19, v16, v20
	v_mul_f32_e32 v16, 0xbfb8aa3b, v70
	v_exp_f32_e32 v16, v16
	v_add_f32_e32 v78, v17, v21
	v_add_f32_e32 v14, v14, v18
	v_fma_f32 v18, v22, v84, 0
	v_add_f32_e32 v16, 1.0, v16
	v_div_scale_f32 v17, s[10:11], v16, v16, s45
	v_rcp_f32_e32 v20, v17
	v_fmac_f32_e32 v18, v23, v85
	v_fmac_f32_e32 v18, v24, v86
	v_fmac_f32_e32 v18, v25, v87
	v_fma_f32 v21, -v17, v20, 1.0
	v_fmac_f32_e32 v20, v21, v20
	v_div_scale_f32 v21, vcc, s45, v16, s45
	v_fmac_f32_e32 v18, v22, v88
	v_mul_f32_e32 v22, v21, v20
	v_fmac_f32_e32 v18, v23, v89
	v_fma_f32 v23, -v17, v22, v21
	v_fmac_f32_e32 v22, v23, v20
	v_fma_f32 v17, -v17, v22, v21
	v_div_fmas_f32 v17, v17, v20, v22
	v_mul_f32_e32 v20, 0xbfb8aa3b, v71
	v_exp_f32_e32 v20, v20
	v_mul_f32_e32 v14, 0xbfb8aa3b, v14
	v_mul_f32_e32 v15, 0xbfb8aa3b, v15
	v_fmac_f32_e32 v18, v24, v90
	v_add_f32_e32 v22, 1.0, v20
	v_div_scale_f32 v20, s[10:11], v22, v22, s45
	v_rcp_f32_e32 v21, v20
	v_exp_f32_e32 v14, v14
	v_exp_f32_e32 v15, v15
	v_fmac_f32_e32 v18, v25, v91
	v_fma_f32 v23, -v20, v21, 1.0
	v_fmac_f32_e32 v21, v23, v21
	v_div_scale_f32 v23, vcc, s45, v22, s45
	v_mul_f32_e32 v24, v23, v21
	v_fma_f32 v25, -v20, v24, v23
	v_fmac_f32_e32 v24, v25, v21
	v_fma_f32 v20, -v20, v24, v23
	v_div_fmas_f32 v23, v20, v21, v24
	v_pk_add_f32 v[20:21], v[14:15], 1.0 op_sel_hi:[1,0]
	s_nop 0
	v_div_scale_f32 v14, s[10:11], v21, v21, 1.0
	v_rcp_f32_e32 v15, v14
	s_nop 0
	v_fma_f32 v24, -v14, v15, 1.0
	v_fmac_f32_e32 v15, v24, v15
	v_div_scale_f32 v24, vcc, 1.0, v21, 1.0
	v_mul_f32_e32 v25, v24, v15
	v_fma_f32 v70, -v14, v25, v24
	v_fmac_f32_e32 v25, v70, v15
	v_fma_f32 v14, -v14, v25, v24
	v_div_fmas_f32 v24, v14, v15, v25
	v_div_scale_f32 v14, s[10:11], v20, v20, 1.0
	v_rcp_f32_e32 v15, v14
	v_div_fixup_f32 v21, v24, v21, 1.0
	v_fma_f32 v25, -v14, v15, 1.0
	v_fmac_f32_e32 v15, v25, v15
	v_div_scale_f32 v25, vcc, 1.0, v20, 1.0
	v_mul_f32_e32 v70, v25, v15
	v_fma_f32 v71, -v14, v70, v25
	v_fmac_f32_e32 v70, v71, v15
	v_fma_f32 v14, -v14, v70, v25
	v_div_fmas_f32 v25, v14, v15, v70
	v_mul_f32_e32 v14, 0xbfb8aa3b, v72
	v_exp_f32_e32 v14, v14
	v_div_fixup_f32 v20, v25, v20, 1.0
	v_add_f32_e32 v70, 1.0, v14
	v_div_scale_f32 v14, s[10:11], v70, v70, s45
	v_rcp_f32_e32 v15, v14
	s_nop 0
	v_fma_f32 v71, -v14, v15, 1.0
	v_fmac_f32_e32 v15, v71, v15
	v_div_scale_f32 v71, vcc, s45, v70, s45
	v_mul_f32_e32 v72, v71, v15
	v_fma_f32 v79, -v14, v72, v71
	v_fmac_f32_e32 v72, v79, v15
	v_fma_f32 v14, -v14, v72, v71
	v_div_fmas_f32 v71, v14, v15, v72
	v_mul_f32_e32 v14, 0xbfb8aa3b, v73
	v_exp_f32_e32 v14, v14
	s_nop 0
	v_add_f32_e32 v72, 1.0, v14
	v_div_scale_f32 v14, s[10:11], v72, v72, s45
	v_rcp_f32_e32 v15, v14
	s_nop 0
	v_fma_f32 v73, -v14, v15, 1.0
	v_fmac_f32_e32 v15, v73, v15
	v_div_scale_f32 v73, vcc, s45, v72, s45
	v_mul_f32_e32 v79, v73, v15
	v_fma_f32 v80, -v14, v79, v73
	v_fmac_f32_e32 v79, v80, v15
	v_fma_f32 v14, -v14, v79, v73
	v_div_fmas_f32 v73, v14, v15, v79
	v_div_fixup_f32 v14, v17, v16, s45
	v_div_fixup_f32 v15, v23, v22, s45
	v_div_fixup_f32 v16, v71, v70, s45
	v_div_fixup_f32 v17, v73, v72, s45
	v_mul_f32_e32 v14, 0x3fb8aa3b, v14
	v_mul_f32_e32 v15, 0x3fb8aa3b, v15
	v_mul_f32_e32 v16, 0x3fb8aa3b, v16
	v_mul_f32_e32 v17, 0x3fb8aa3b, v17
	v_exp_f32_e32 v14, v14
	v_exp_f32_e32 v15, v15
	v_exp_f32_e32 v16, v16
	v_exp_f32_e32 v17, v17
	global_store_dwordx4 v[94:95], v[14:17], off offset:192
	s_nop 1
	v_mul_f32_e32 v14, 0xbfb8aa3b, v19
	v_mul_f32_e32 v15, 0xbfb8aa3b, v78
	v_exp_f32_e32 v14, v14
	v_exp_f32_e32 v15, v15
	s_nop 0
	v_pk_add_f32 v[14:15], v[14:15], 1.0 op_sel_hi:[1,0]
	s_nop 0
	v_div_scale_f32 v16, s[10:11], v15, v15, 1.0
	v_rcp_f32_e32 v17, v16
	s_nop 0
	v_fma_f32 v19, -v16, v17, 1.0
	v_fmac_f32_e32 v17, v19, v17
	v_div_scale_f32 v19, vcc, 1.0, v15, 1.0
	v_mul_f32_e32 v22, v19, v17
	v_fma_f32 v23, -v16, v22, v19
	v_fmac_f32_e32 v22, v23, v17
	v_fma_f32 v16, -v16, v22, v19
	v_div_fmas_f32 v16, v16, v17, v22
	v_div_scale_f32 v17, s[10:11], v14, v14, 1.0
	v_rcp_f32_e32 v19, v17
	s_nop 0
	v_fma_f32 v22, -v17, v19, 1.0
	v_fmac_f32_e32 v19, v22, v19
	v_div_scale_f32 v22, vcc, 1.0, v14, 1.0
	v_mul_f32_e32 v23, v22, v19
	v_fma_f32 v24, -v17, v23, v22
	v_fmac_f32_e32 v23, v24, v19
	v_fma_f32 v17, -v17, v23, v22
	v_div_fmas_f32 v17, v17, v19, v23
	v_div_fixup_f32 v23, v16, v15, 1.0
	v_div_fixup_f32 v22, v17, v14, 1.0
	v_xor_b32_e32 v15, 0x80000000, v21
	v_xor_b32_e32 v14, 0x80000000, v20
	v_xor_b32_e32 v17, 0x80000000, v23
	v_xor_b32_e32 v16, 0x80000000, v22
	v_pk_mul_f32 v[16:17], v[28:29], v[16:17]
	v_pk_mul_f32 v[14:15], v[26:27], v[14:15]
	global_store_dwordx4 v[94:95], v[14:17], off offset:448
	v_mul_f32_e32 v19, v46, v66
	v_fmac_f32_e32 v18, v50, v19
	v_pk_add_f32 v[14:15], v[20:21], -1.0 op_sel_hi:[1,0]
	v_mul_f32_e32 v19, v47, v67
	v_pk_fma_f32 v[14:15], v[42:43], v[14:15], 1.0 op_sel_hi:[1,1,0]
	v_fmac_f32_e32 v18, v51, v19
	v_pk_mul_f32 v[20:21], v[10:11], v[14:15]
	v_pk_add_f32 v[14:15], v[22:23], -1.0 op_sel_hi:[1,0]
	v_mul_f32_e32 v19, v48, v68
	v_pk_fma_f32 v[14:15], v[44:45], v[14:15], 1.0 op_sel_hi:[1,1,0]
	v_fmac_f32_e32 v18, v52, v19
	v_pk_mul_f32 v[22:23], v[12:13], v[14:15]
	global_store_dwordx4 v[94:95], v[20:23], off offset:704
	ds_read_b128 v[14:17], v255 offset:112
	v_mul_f32_e32 v19, v49, v69
	ds_read_b128 v[66:69], v255 offset:240
	v_fmac_f32_e32 v18, v53, v19
	v_mul_f32_e32 v19, v46, v54
	v_fmac_f32_e32 v18, v50, v19
	v_mul_f32_e32 v19, v47, v55
	v_fmac_f32_e32 v18, v51, v19
	v_mul_f32_e32 v19, v48, v56
	v_fmac_f32_e32 v18, v52, v19
	v_mul_f32_e32 v19, v49, v57
	v_fmac_f32_e32 v18, v53, v19
	v_mul_f32_e32 v19, v58, v38
	v_fmac_f32_e32 v18, v62, v19
	v_mul_f32_e32 v19, v59, v39
	v_fmac_f32_e32 v18, v63, v19
	v_mul_f32_e32 v19, v60, v40
	v_fmac_f32_e32 v18, v64, v19
	v_mul_f32_e32 v19, v61, v41
	v_fmac_f32_e32 v18, v65, v19
	v_mul_f32_e32 v19, v58, v74
	v_fmac_f32_e32 v18, v62, v19
	v_mul_f32_e32 v19, v59, v75
	v_fmac_f32_e32 v18, v63, v19
	v_mul_f32_e32 v19, v60, v76
	v_fmac_f32_e32 v18, v64, v19
	v_mul_f32_e32 v19, v61, v77
	v_fmac_f32_e32 v18, v65, v19
	v_mul_f32_e32 v19, v30, v20
	v_fmac_f32_e32 v18, v34, v19
	s_waitcnt lgkmcnt(0)
	v_add_f32_e32 v2, v2, v14
	v_mul_f32_e32 v2, 0xbfb8aa3b, v2
	v_exp_f32_e32 v2, v2
	v_mul_f32_e32 v14, v31, v21
	v_fmac_f32_e32 v18, v35, v14
	v_mul_f32_e32 v14, v32, v22
	v_add_f32_e32 v2, 1.0, v2
	v_div_scale_f32 v19, s[10:11], v2, v2, s45
	v_rcp_f32_e32 v20, v19
	v_add_f32_e32 v3, v3, v15
	v_fmac_f32_e32 v18, v36, v14
	v_mul_f32_e32 v14, v33, v23
	v_mul_f32_e32 v3, 0xbfb8aa3b, v3
	v_fmac_f32_e32 v18, v37, v14
	v_fma_f32 v14, -v19, v20, 1.0
	v_exp_f32_e32 v3, v3
	v_fmac_f32_e32 v20, v14, v20
	v_div_scale_f32 v14, vcc, s45, v2, s45
	v_mul_f32_e32 v21, v14, v20
	v_fma_f32 v22, -v19, v21, v14
	v_fmac_f32_e32 v21, v22, v20
	v_add_f32_e32 v15, 1.0, v3
	v_fma_f32 v14, -v19, v21, v14
	v_div_scale_f32 v19, s[10:11], v15, v15, s45
	v_div_fmas_f32 v14, v14, v20, v21
	v_rcp_f32_e32 v20, v19
	v_div_fixup_f32 v2, v14, v2, s45
	v_mul_f32_e32 v2, 0x3fb8aa3b, v2
	v_exp_f32_e32 v14, v2
	v_fma_f32 v3, -v19, v20, 1.0
	v_add_f32_e32 v2, v6, v66
	v_fmac_f32_e32 v20, v3, v20
	v_div_scale_f32 v6, vcc, s45, v15, s45
	v_mul_f32_e32 v21, v6, v20
	v_fma_f32 v3, -v19, v21, v6
	v_fmac_f32_e32 v21, v3, v20
	v_add_f32_e32 v3, v7, v67
	v_mul_f32_e32 v2, 0xbfb8aa3b, v2
	v_mul_f32_e32 v3, 0xbfb8aa3b, v3
	v_exp_f32_e32 v2, v2
	v_exp_f32_e32 v3, v3
	v_fma_f32 v6, -v19, v21, v6
	v_div_fmas_f32 v6, v6, v20, v21
	v_div_fixup_f32 v6, v6, v15, s45
	v_pk_add_f32 v[2:3], v[2:3], 1.0 op_sel_hi:[1,0]
	v_mul_f32_e32 v6, 0x3fb8aa3b, v6
	v_div_scale_f32 v7, s[10:11], v3, v3, 1.0
	v_rcp_f32_e32 v19, v7
	v_exp_f32_e32 v15, v6
	v_add_f32_e32 v4, v4, v16
	v_mul_f32_e32 v4, 0xbfb8aa3b, v4
	v_fma_f32 v6, -v7, v19, 1.0
	v_fmac_f32_e32 v19, v6, v19
	v_div_scale_f32 v6, vcc, 1.0, v3, 1.0
	v_mul_f32_e32 v20, v6, v19
	v_fma_f32 v21, -v7, v20, v6
	v_fmac_f32_e32 v20, v21, v19
	v_fma_f32 v6, -v7, v20, v6
	v_div_scale_f32 v7, s[10:11], v2, v2, 1.0
	v_rcp_f32_e32 v21, v7
	v_div_fmas_f32 v6, v6, v19, v20
	v_div_fixup_f32 v3, v6, v3, 1.0
	v_exp_f32_e32 v4, v4
	v_fma_f32 v6, -v7, v21, 1.0
	v_fmac_f32_e32 v21, v6, v21
	v_div_scale_f32 v6, vcc, 1.0, v2, 1.0
	v_mul_f32_e32 v19, v6, v21
	v_fma_f32 v20, -v7, v19, v6
	v_fmac_f32_e32 v19, v20, v21
	v_fma_f32 v6, -v7, v19, v6
	v_div_fmas_f32 v6, v6, v21, v19
	v_div_fixup_f32 v2, v6, v2, 1.0
	v_pk_add_f32 v[6:7], v[2:3], -1.0 op_sel_hi:[1,0]
	v_add_f32_e32 v4, 1.0, v4
	v_pk_fma_f32 v[6:7], v[42:43], v[6:7], 1.0 op_sel_hi:[1,1,0]
	v_add_f32_e32 v5, v5, v17
	v_pk_mul_f32 v[6:7], v[10:11], v[6:7]
	v_div_scale_f32 v11, s[10:11], v4, v4, s45
	v_rcp_f32_e32 v16, v11
	v_mul_f32_e32 v10, v30, v6
	v_fmac_f32_e32 v18, v34, v10
	v_mul_f32_e32 v10, v31, v7
	v_fmac_f32_e32 v18, v35, v10
	v_fma_f32 v10, -v11, v16, 1.0
	v_fmac_f32_e32 v16, v10, v16
	v_div_scale_f32 v10, vcc, s45, v4, s45
	v_mul_f32_e32 v19, v10, v16
	v_mul_f32_e32 v5, 0xbfb8aa3b, v5
	v_fma_f32 v20, -v11, v19, v10
	v_exp_f32_e32 v5, v5
	v_fmac_f32_e32 v19, v20, v16
	v_fma_f32 v10, -v11, v19, v10
	v_div_fmas_f32 v10, v10, v16, v19
	v_div_fixup_f32 v4, v10, v4, s45
	v_add_f32_e32 v10, 1.0, v5
	v_div_scale_f32 v11, s[10:11], v10, v10, s45
	v_rcp_f32_e32 v17, v11
	v_mul_f32_e32 v4, 0x3fb8aa3b, v4
	v_exp_f32_e32 v16, v4
	v_add_f32_e32 v4, v8, v68
	v_fma_f32 v5, -v11, v17, 1.0
	v_fmac_f32_e32 v17, v5, v17
	v_div_scale_f32 v8, vcc, s45, v10, s45
	v_mul_f32_e32 v19, v8, v17
	v_fma_f32 v5, -v11, v19, v8
	v_fmac_f32_e32 v19, v5, v17
	v_add_f32_e32 v5, v9, v69
	v_mul_f32_e32 v4, 0xbfb8aa3b, v4
	v_mul_f32_e32 v5, 0xbfb8aa3b, v5
	v_exp_f32_e32 v4, v4
	v_exp_f32_e32 v5, v5
	v_fma_f32 v8, -v11, v19, v8
	v_div_fmas_f32 v8, v8, v17, v19
	v_div_fixup_f32 v8, v8, v10, s45
	v_pk_add_f32 v[4:5], v[4:5], 1.0 op_sel_hi:[1,0]
	v_mul_f32_e32 v8, 0x3fb8aa3b, v8
	v_div_scale_f32 v9, s[10:11], v5, v5, 1.0
	v_rcp_f32_e32 v11, v9
	v_exp_f32_e32 v17, v8
	v_fma_f32 v8, -v9, v11, 1.0
	v_fmac_f32_e32 v11, v8, v11
	v_div_scale_f32 v8, vcc, 1.0, v5, 1.0
	v_mul_f32_e32 v10, v8, v11
	v_fma_f32 v19, -v9, v10, v8
	v_fmac_f32_e32 v10, v19, v11
	v_fma_f32 v8, -v9, v10, v8
	v_div_scale_f32 v9, s[10:11], v4, v4, 1.0
	v_rcp_f32_e32 v19, v9
	v_div_fmas_f32 v8, v8, v11, v10
	v_div_fixup_f32 v5, v8, v5, 1.0
	v_fma_f32 v8, -v9, v19, 1.0
	v_fmac_f32_e32 v19, v8, v19
	v_div_scale_f32 v8, vcc, 1.0, v4, 1.0
	v_mul_f32_e32 v10, v8, v19
	v_fma_f32 v11, -v9, v10, v8
	v_fmac_f32_e32 v10, v11, v19
	v_fma_f32 v8, -v9, v10, v8
	v_div_fmas_f32 v8, v8, v19, v10
	v_div_fixup_f32 v4, v8, v4, 1.0
	v_pk_add_f32 v[8:9], v[4:5], -1.0 op_sel_hi:[1,0]
	v_xor_b32_e32 v11, 0x80000000, v3
	v_pk_fma_f32 v[8:9], v[44:45], v[8:9], 1.0 op_sel_hi:[1,1,0]
	s_nop 0
	v_pk_mul_f32 v[8:9], v[12:13], v[8:9]
	s_nop 0
	v_mul_f32_e32 v10, v32, v8
	v_fmac_f32_e32 v18, v36, v10
	v_mul_f32_e32 v3, v33, v9
	v_fmac_f32_e32 v18, v37, v3
	ds_bpermute_b32 v19, v244, v18
	v_xor_b32_e32 v10, 0x80000000, v2
	v_xor_b32_e32 v3, 0x80000000, v5
	v_xor_b32_e32 v2, 0x80000000, v4
	v_pk_mul_f32 v[12:13], v[28:29], v[2:3]
	s_waitcnt lgkmcnt(0)
	v_add_f32_e32 v2, v18, v19
	ds_bpermute_b32 v3, v245, v2
	v_pk_mul_f32 v[10:11], v[26:27], v[10:11]
	global_store_dwordx4 v[82:83], v[14:17], off offset:192
	global_store_dwordx4 v[82:83], v[10:13], off offset:448
	global_store_dwordx4 v[82:83], v[6:9], off offset:704
	s_and_saveexec_b64 s[10:11], s[6:7]
	s_cbranch_execz .LBB0_473
	s_waitcnt lgkmcnt(0)
	v_add_f32_e32 v4, v2, v3
	v_lshl_add_u32 v2, v243, 2, v98
	v_ashrrev_i32_e32 v3, 31, v2
	v_lshl_add_u64 v[2:3], v[2:3], 2, s[52:53]
	global_store_dword v[2:3], v4, off
	s_branch .LBB0_473
